# gla_prep: per-column gate dot products and the softplus tail for a token pair use packed f32 (v_pk_fma/add/mul), pair-interleaved LDS layout
# speedup vs baseline: 1.0049x; 1.0007x over previous
.LBB0_219:
	s_cmp_lt_i32 s24, 3
	s_cselect_b64 s[4:5], -1, 0
	s_cmp_gt_i32 s25, 2
	s_cselect_b64 s[6:7], -1, 0
	s_and_b64 s[4:5], s[4:5], s[6:7]
	s_andn2_b64 vcc, exec, s[4:5]
	s_cbranch_vccnz .LBB0_279
	s_cmpk_gt_i32 s2, 0xff
	s_cbranch_scc1 .LBB0_225
	s_mov_b64 exec, -1
	s_load_dwordx16 s[4:19], s[0:1], 0x40
	s_load_dword s3, s[0:1], 0x148
	v_lshlrev_b32_e32 v0, 2, v129
	v_lshlrev_b32_e32 v1, 1, v129
	v_lshlrev_b32_e32 v2, 7, v129
	v_mov_b32_e32 v3, 0
	v_lshrrev_b32_e32 v4, 4, v129
	v_and_b32_e32 v5, 15, v129
	v_mul_u32_u24_e32 v4, 0x1a00, v4
	v_lshl_add_u32 v4, v5, 1, v4
	v_lshrrev_b32_e32 v130, 5, v129
	v_lshlrev_b32_e32 v130, 7, v130
	v_lshl_add_u32 v130, v5, 3, v130
	v_bfe_u32 v131, v129, 4, 1
	v_lshl_add_u32 v130, v131, 2, v130
	s_mov_b32 s82, s2
	s_waitcnt lgkmcnt(0)
	s_mov_b32 s7, 0xbfb8aa3b
	s_mov_b32 s9, 0x3f317217
	s_mov_b32 s87, 0x3377d1cf
	s_mov_b64 s[84:85], s[12:13]
	s_mov_b64 s[80:81], s[14:15]
.Lprep_item:
	s_barrier
	s_lshr_b32 s4, s82, 5
	s_lshl_b32 s4, s4, 11
	s_and_b32 s5, s82, 31
	s_lshl_b32 s5, s5, 6
	s_add_u32 s4, s4, s5
	s_mul_i32 s5, s4, 0x1a00
	s_mul_hi_u32 s6, s4, 0x1a00
	s_add_u32 s20, s46, s5
	s_addc_u32 s21, s47, s6
	s_mov_b64 s[22:23], s[20:21]
	s_add_u32 s30, s20, 0x1800
	s_addc_u32 s31, s21, 0
	s_add_u32 s16, s30, 0x34000
	s_addc_u32 s17, s31, 0
	s_lshl_b32 s5, s82, 16
	s_lshr_b32 s6, s82, 16
	s_add_u32 s26, s46, 0x6b40000
	s_addc_u32 s27, s47, 0
	s_add_u32 s26, s26, s5
	s_addc_u32 s27, s27, s6
	s_mul_i32 s5, s82, 0x1800
	s_add_u32 s28, s46, 0x7b40000
	s_addc_u32 s29, s47, 0
	s_add_u32 s28, s28, s5
	s_addc_u32 s29, s29, 0
	s_mov_b64 s[34:35], s[84:85]
	global_load_ushort v6, v4, s[30:31]
	global_load_ushort v7, v4, s[16:17]
	global_load_dword v16, v0, s[34:35]
	global_load_dword v17, v0, s[34:35] offset:2048
	s_add_u32 s34, s34, 0x1000
	s_addc_u32 s35, s35, 0
	global_load_dword v18, v0, s[34:35]
	global_load_dword v19, v0, s[34:35] offset:2048
	s_add_u32 s34, s34, 0x1000
	s_addc_u32 s35, s35, 0
	global_load_dword v20, v0, s[34:35]
	global_load_dword v21, v0, s[34:35] offset:2048
	s_add_u32 s34, s34, 0x1000
	s_addc_u32 s35, s35, 0
	global_load_dword v22, v0, s[34:35]
	global_load_dword v23, v0, s[34:35] offset:2048
	s_add_u32 s34, s34, 0x1000
	s_addc_u32 s35, s35, 0
	global_load_dword v24, v0, s[34:35]
	global_load_dword v25, v0, s[34:35] offset:2048
	s_add_u32 s34, s34, 0x1000
	s_addc_u32 s35, s35, 0
	global_load_dword v26, v0, s[34:35]
	global_load_dword v27, v0, s[34:35] offset:2048
	s_add_u32 s34, s34, 0x1000
	s_addc_u32 s35, s35, 0
	global_load_dword v28, v0, s[34:35]
	global_load_dword v29, v0, s[34:35] offset:2048
	s_add_u32 s34, s34, 0x1000
	s_addc_u32 s35, s35, 0
	global_load_dword v30, v0, s[34:35]
	global_load_dword v31, v0, s[34:35] offset:2048
	global_load_dword v32, v0, s[80:81]
	s_waitcnt vmcnt(17)
	v_lshlrev_b32_e32 v6, 16, v6
	v_lshlrev_b32_e32 v7, 16, v7
	ds_write_b32 v130, v6
	ds_write_b32 v130, v7 offset:2048
	s_waitcnt lgkmcnt(0)
	s_barrier
	ds_read_b128 v[34:37], v3 offset:0
	ds_read_b128 v[38:41], v3 offset:16
	ds_read_b128 v[42:45], v3 offset:32
	ds_read_b128 v[46:49], v3 offset:48
	ds_read_b128 v[200:203], v3 offset:64
	ds_read_b128 v[204:207], v3 offset:80
	ds_read_b128 v[208:211], v3 offset:96
	ds_read_b128 v[212:215], v3 offset:112
	s_waitcnt vmcnt(0)
	s_waitcnt lgkmcnt(0)
	ds_read_b128 v[216:219], v3 offset:128
	ds_read_b128 v[220:223], v3 offset:144
	ds_read_b128 v[224:227], v3 offset:160
	ds_read_b128 v[232:235], v3 offset:176
	ds_read_b128 v[236:239], v3 offset:192
	ds_read_b128 v[240:243], v3 offset:208
	ds_read_b128 v[244:247], v3 offset:224
	ds_read_b128 v[248:251], v3 offset:240
	global_load_ushort v136, v1, s[20:21]
	global_load_ushort v137, v1, s[20:21] offset:1024
	s_add_u32 s20, s20, 0x1a00
	s_addc_u32 s21, s21, 0
	global_load_ushort v138, v1, s[20:21]
	global_load_ushort v139, v1, s[20:21] offset:1024
	s_add_u32 s20, s20, 0x1a00
	s_addc_u32 s21, s21, 0
	v_pk_fma_f32 v[50:51], v[16:17], v[34:35], v[32:33] op_sel_hi:[0,1,0]
	v_pk_fma_f32 v[50:51], v[16:17], v[36:37], v[50:51] op_sel:[1,0,0] op_sel_hi:[1,1,1]
	v_pk_fma_f32 v[50:51], v[18:19], v[38:39], v[50:51] op_sel_hi:[0,1,1]
	v_pk_fma_f32 v[50:51], v[18:19], v[40:41], v[50:51] op_sel:[1,0,0] op_sel_hi:[1,1,1]
	v_pk_fma_f32 v[50:51], v[20:21], v[42:43], v[50:51] op_sel_hi:[0,1,1]
	v_pk_fma_f32 v[50:51], v[20:21], v[44:45], v[50:51] op_sel:[1,0,0] op_sel_hi:[1,1,1]
	v_pk_fma_f32 v[50:51], v[22:23], v[46:47], v[50:51] op_sel_hi:[0,1,1]
	v_pk_fma_f32 v[50:51], v[22:23], v[48:49], v[50:51] op_sel:[1,0,0] op_sel_hi:[1,1,1]
	v_pk_fma_f32 v[50:51], v[24:25], v[200:201], v[50:51] op_sel_hi:[0,1,1]
	v_pk_fma_f32 v[50:51], v[24:25], v[202:203], v[50:51] op_sel:[1,0,0] op_sel_hi:[1,1,1]
	v_pk_fma_f32 v[50:51], v[26:27], v[204:205], v[50:51] op_sel_hi:[0,1,1]
	v_pk_fma_f32 v[50:51], v[26:27], v[206:207], v[50:51] op_sel:[1,0,0] op_sel_hi:[1,1,1]
	v_pk_fma_f32 v[50:51], v[28:29], v[208:209], v[50:51] op_sel_hi:[0,1,1]
	v_pk_fma_f32 v[50:51], v[28:29], v[210:211], v[50:51] op_sel:[1,0,0] op_sel_hi:[1,1,1]
	v_pk_fma_f32 v[50:51], v[30:31], v[212:213], v[50:51] op_sel_hi:[0,1,1]
	v_pk_fma_f32 v[50:51], v[30:31], v[214:215], v[50:51] op_sel:[1,0,0] op_sel_hi:[1,1,1]
	v_mul_f32_e64 v52, |v50|, s7
	v_mul_f32_e64 v53, |v51|, s7
	v_exp_f32_e32 v52, v52
	v_exp_f32_e32 v53, v53
	v_min_f32_e32 v50, 0, v50
	v_min_f32_e32 v51, 0, v51
	v_pk_add_f32 v[52:53], v[52:53], 1.0 op_sel_hi:[1,0]
	v_log_f32_e32 v52, v52
	v_log_f32_e32 v53, v53
	s_nop 0
	v_pk_mul_f32 v[54:55], v[52:53], s[8:9] op_sel:[0,1] op_sel_hi:[1,1]
	v_pk_fma_f32 v[56:57], v[52:53], s[8:9], v[54:55] op_sel:[0,1,0] op_sel_hi:[1,1,1] neg_lo:[0,0,1] neg_hi:[0,0,1]
	v_pk_fma_f32 v[56:57], v[52:53], s[86:87], v[56:57] op_sel:[0,1,0] op_sel_hi:[1,1,1]
	v_pk_add_f32 v[54:55], v[54:55], v[56:57]
	v_pk_add_f32 v[50:51], v[50:51], v[54:55] neg_lo:[0,1] neg_hi:[0,1]
	v_mul_f32_e32 v64, 0x3d800000, v50
	v_fmamk_f32 v65, v51, 0x3d800000, v64
	s_waitcnt lgkmcnt(0)
	ds_read_b128 v[34:37], v3 offset:256
	ds_read_b128 v[38:41], v3 offset:272
	ds_read_b128 v[42:45], v3 offset:288
	ds_read_b128 v[46:49], v3 offset:304
	ds_read_b128 v[200:203], v3 offset:320
	ds_read_b128 v[204:207], v3 offset:336
	ds_read_b128 v[208:211], v3 offset:352
	ds_read_b128 v[212:215], v3 offset:368
	global_load_ushort v140, v1, s[20:21]
	global_load_ushort v141, v1, s[20:21] offset:1024
	s_add_u32 s20, s20, 0x1a00
	s_addc_u32 s21, s21, 0
	global_load_ushort v142, v1, s[20:21]
	global_load_ushort v143, v1, s[20:21] offset:1024
	s_add_u32 s20, s20, 0x1a00
	s_addc_u32 s21, s21, 0
	v_pk_fma_f32 v[50:51], v[16:17], v[216:217], v[32:33] op_sel_hi:[0,1,0]
	v_pk_fma_f32 v[50:51], v[16:17], v[218:219], v[50:51] op_sel:[1,0,0] op_sel_hi:[1,1,1]
	v_pk_fma_f32 v[50:51], v[18:19], v[220:221], v[50:51] op_sel_hi:[0,1,1]
	v_pk_fma_f32 v[50:51], v[18:19], v[222:223], v[50:51] op_sel:[1,0,0] op_sel_hi:[1,1,1]
	v_pk_fma_f32 v[50:51], v[20:21], v[224:225], v[50:51] op_sel_hi:[0,1,1]
	v_pk_fma_f32 v[50:51], v[20:21], v[226:227], v[50:51] op_sel:[1,0,0] op_sel_hi:[1,1,1]
	v_pk_fma_f32 v[50:51], v[22:23], v[232:233], v[50:51] op_sel_hi:[0,1,1]
	v_pk_fma_f32 v[50:51], v[22:23], v[234:235], v[50:51] op_sel:[1,0,0] op_sel_hi:[1,1,1]
	v_pk_fma_f32 v[50:51], v[24:25], v[236:237], v[50:51] op_sel_hi:[0,1,1]
	v_pk_fma_f32 v[50:51], v[24:25], v[238:239], v[50:51] op_sel:[1,0,0] op_sel_hi:[1,1,1]
	v_pk_fma_f32 v[50:51], v[26:27], v[240:241], v[50:51] op_sel_hi:[0,1,1]
	v_pk_fma_f32 v[50:51], v[26:27], v[242:243], v[50:51] op_sel:[1,0,0] op_sel_hi:[1,1,1]
	v_pk_fma_f32 v[50:51], v[28:29], v[244:245], v[50:51] op_sel_hi:[0,1,1]
	v_pk_fma_f32 v[50:51], v[28:29], v[246:247], v[50:51] op_sel:[1,0,0] op_sel_hi:[1,1,1]
	v_pk_fma_f32 v[50:51], v[30:31], v[248:249], v[50:51] op_sel_hi:[0,1,1]
	v_pk_fma_f32 v[50:51], v[30:31], v[250:251], v[50:51] op_sel:[1,0,0] op_sel_hi:[1,1,1]
	v_mul_f32_e64 v52, |v50|, s7
	v_mul_f32_e64 v53, |v51|, s7
	v_exp_f32_e32 v52, v52
	v_exp_f32_e32 v53, v53
	v_min_f32_e32 v50, 0, v50
	v_min_f32_e32 v51, 0, v51
	v_pk_add_f32 v[52:53], v[52:53], 1.0 op_sel_hi:[1,0]
	v_log_f32_e32 v52, v52
	v_log_f32_e32 v53, v53
	s_nop 0
	v_pk_mul_f32 v[54:55], v[52:53], s[8:9] op_sel:[0,1] op_sel_hi:[1,1]
	v_pk_fma_f32 v[56:57], v[52:53], s[8:9], v[54:55] op_sel:[0,1,0] op_sel_hi:[1,1,1] neg_lo:[0,0,1] neg_hi:[0,0,1]
	v_pk_fma_f32 v[56:57], v[52:53], s[86:87], v[56:57] op_sel:[0,1,0] op_sel_hi:[1,1,1]
	v_pk_add_f32 v[54:55], v[54:55], v[56:57]
	v_pk_add_f32 v[50:51], v[50:51], v[54:55] neg_lo:[0,1] neg_hi:[0,1]
	v_fmamk_f32 v66, v50, 0x3d800000, v65
	v_fmamk_f32 v67, v51, 0x3d800000, v66
	s_waitcnt lgkmcnt(0)
	ds_read_b128 v[216:219], v3 offset:384
	ds_read_b128 v[220:223], v3 offset:400
	ds_read_b128 v[224:227], v3 offset:416
	ds_read_b128 v[232:235], v3 offset:432
	ds_read_b128 v[236:239], v3 offset:448
	ds_read_b128 v[240:243], v3 offset:464
	ds_read_b128 v[244:247], v3 offset:480
	ds_read_b128 v[248:251], v3 offset:496
	global_load_ushort v144, v1, s[20:21]
	global_load_ushort v145, v1, s[20:21] offset:1024
	s_add_u32 s20, s20, 0x1a00
	s_addc_u32 s21, s21, 0
	global_load_ushort v146, v1, s[20:21]
	global_load_ushort v147, v1, s[20:21] offset:1024
	s_add_u32 s20, s20, 0x1a00
	s_addc_u32 s21, s21, 0
	v_pk_fma_f32 v[50:51], v[16:17], v[34:35], v[32:33] op_sel_hi:[0,1,0]
	v_pk_fma_f32 v[50:51], v[16:17], v[36:37], v[50:51] op_sel:[1,0,0] op_sel_hi:[1,1,1]
	v_pk_fma_f32 v[50:51], v[18:19], v[38:39], v[50:51] op_sel_hi:[0,1,1]
	v_pk_fma_f32 v[50:51], v[18:19], v[40:41], v[50:51] op_sel:[1,0,0] op_sel_hi:[1,1,1]
	v_pk_fma_f32 v[50:51], v[20:21], v[42:43], v[50:51] op_sel_hi:[0,1,1]
	v_pk_fma_f32 v[50:51], v[20:21], v[44:45], v[50:51] op_sel:[1,0,0] op_sel_hi:[1,1,1]
	v_pk_fma_f32 v[50:51], v[22:23], v[46:47], v[50:51] op_sel_hi:[0,1,1]
	v_pk_fma_f32 v[50:51], v[22:23], v[48:49], v[50:51] op_sel:[1,0,0] op_sel_hi:[1,1,1]
	v_pk_fma_f32 v[50:51], v[24:25], v[200:201], v[50:51] op_sel_hi:[0,1,1]
	v_pk_fma_f32 v[50:51], v[24:25], v[202:203], v[50:51] op_sel:[1,0,0] op_sel_hi:[1,1,1]
	v_pk_fma_f32 v[50:51], v[26:27], v[204:205], v[50:51] op_sel_hi:[0,1,1]
	v_pk_fma_f32 v[50:51], v[26:27], v[206:207], v[50:51] op_sel:[1,0,0] op_sel_hi:[1,1,1]
	v_pk_fma_f32 v[50:51], v[28:29], v[208:209], v[50:51] op_sel_hi:[0,1,1]
	v_pk_fma_f32 v[50:51], v[28:29], v[210:211], v[50:51] op_sel:[1,0,0] op_sel_hi:[1,1,1]
	v_pk_fma_f32 v[50:51], v[30:31], v[212:213], v[50:51] op_sel_hi:[0,1,1]
	v_pk_fma_f32 v[50:51], v[30:31], v[214:215], v[50:51] op_sel:[1,0,0] op_sel_hi:[1,1,1]
	v_mul_f32_e64 v52, |v50|, s7
	v_mul_f32_e64 v53, |v51|, s7
	v_exp_f32_e32 v52, v52
	v_exp_f32_e32 v53, v53
	v_min_f32_e32 v50, 0, v50
	v_min_f32_e32 v51, 0, v51
	v_pk_add_f32 v[52:53], v[52:53], 1.0 op_sel_hi:[1,0]
	v_log_f32_e32 v52, v52
	v_log_f32_e32 v53, v53
	s_nop 0
	v_pk_mul_f32 v[54:55], v[52:53], s[8:9] op_sel:[0,1] op_sel_hi:[1,1]
	v_pk_fma_f32 v[56:57], v[52:53], s[8:9], v[54:55] op_sel:[0,1,0] op_sel_hi:[1,1,1] neg_lo:[0,0,1] neg_hi:[0,0,1]
	v_pk_fma_f32 v[56:57], v[52:53], s[86:87], v[56:57] op_sel:[0,1,0] op_sel_hi:[1,1,1]
	v_pk_add_f32 v[54:55], v[54:55], v[56:57]
	v_pk_add_f32 v[50:51], v[50:51], v[54:55] neg_lo:[0,1] neg_hi:[0,1]
	v_fmamk_f32 v68, v50, 0x3d800000, v67
	v_fmamk_f32 v69, v51, 0x3d800000, v68
	s_waitcnt lgkmcnt(0)
	ds_read_b128 v[34:37], v3 offset:512
	ds_read_b128 v[38:41], v3 offset:528
	ds_read_b128 v[42:45], v3 offset:544
	ds_read_b128 v[46:49], v3 offset:560
	ds_read_b128 v[200:203], v3 offset:576
	ds_read_b128 v[204:207], v3 offset:592
	ds_read_b128 v[208:211], v3 offset:608
	ds_read_b128 v[212:215], v3 offset:624
	global_load_ushort v148, v1, s[20:21]
	global_load_ushort v149, v1, s[20:21] offset:1024
	s_add_u32 s20, s20, 0x1a00
	s_addc_u32 s21, s21, 0
	global_load_ushort v150, v1, s[20:21]
	global_load_ushort v151, v1, s[20:21] offset:1024
	s_add_u32 s20, s20, 0x1a00
	s_addc_u32 s21, s21, 0
	v_pk_fma_f32 v[50:51], v[16:17], v[216:217], v[32:33] op_sel_hi:[0,1,0]
	v_pk_fma_f32 v[50:51], v[16:17], v[218:219], v[50:51] op_sel:[1,0,0] op_sel_hi:[1,1,1]
	v_pk_fma_f32 v[50:51], v[18:19], v[220:221], v[50:51] op_sel_hi:[0,1,1]
	v_pk_fma_f32 v[50:51], v[18:19], v[222:223], v[50:51] op_sel:[1,0,0] op_sel_hi:[1,1,1]
	v_pk_fma_f32 v[50:51], v[20:21], v[224:225], v[50:51] op_sel_hi:[0,1,1]
	v_pk_fma_f32 v[50:51], v[20:21], v[226:227], v[50:51] op_sel:[1,0,0] op_sel_hi:[1,1,1]
	v_pk_fma_f32 v[50:51], v[22:23], v[232:233], v[50:51] op_sel_hi:[0,1,1]
	v_pk_fma_f32 v[50:51], v[22:23], v[234:235], v[50:51] op_sel:[1,0,0] op_sel_hi:[1,1,1]
	v_pk_fma_f32 v[50:51], v[24:25], v[236:237], v[50:51] op_sel_hi:[0,1,1]
	v_pk_fma_f32 v[50:51], v[24:25], v[238:239], v[50:51] op_sel:[1,0,0] op_sel_hi:[1,1,1]
	v_pk_fma_f32 v[50:51], v[26:27], v[240:241], v[50:51] op_sel_hi:[0,1,1]
	v_pk_fma_f32 v[50:51], v[26:27], v[242:243], v[50:51] op_sel:[1,0,0] op_sel_hi:[1,1,1]
	v_pk_fma_f32 v[50:51], v[28:29], v[244:245], v[50:51] op_sel_hi:[0,1,1]
	v_pk_fma_f32 v[50:51], v[28:29], v[246:247], v[50:51] op_sel:[1,0,0] op_sel_hi:[1,1,1]
	v_pk_fma_f32 v[50:51], v[30:31], v[248:249], v[50:51] op_sel_hi:[0,1,1]
	v_pk_fma_f32 v[50:51], v[30:31], v[250:251], v[50:51] op_sel:[1,0,0] op_sel_hi:[1,1,1]
	v_mul_f32_e64 v52, |v50|, s7
	v_mul_f32_e64 v53, |v51|, s7
	v_exp_f32_e32 v52, v52
	v_exp_f32_e32 v53, v53
	v_min_f32_e32 v50, 0, v50
	v_min_f32_e32 v51, 0, v51
	v_pk_add_f32 v[52:53], v[52:53], 1.0 op_sel_hi:[1,0]
	v_log_f32_e32 v52, v52
	v_log_f32_e32 v53, v53
	s_nop 0
	v_pk_mul_f32 v[54:55], v[52:53], s[8:9] op_sel:[0,1] op_sel_hi:[1,1]
	v_pk_fma_f32 v[56:57], v[52:53], s[8:9], v[54:55] op_sel:[0,1,0] op_sel_hi:[1,1,1] neg_lo:[0,0,1] neg_hi:[0,0,1]
	v_pk_fma_f32 v[56:57], v[52:53], s[86:87], v[56:57] op_sel:[0,1,0] op_sel_hi:[1,1,1]
	v_pk_add_f32 v[54:55], v[54:55], v[56:57]
	v_pk_add_f32 v[50:51], v[50:51], v[54:55] neg_lo:[0,1] neg_hi:[0,1]
	v_fmamk_f32 v70, v50, 0x3d800000, v69
	v_fmamk_f32 v71, v51, 0x3d800000, v70
	s_waitcnt lgkmcnt(0)
	ds_read_b128 v[216:219], v3 offset:640
	ds_read_b128 v[220:223], v3 offset:656
	ds_read_b128 v[224:227], v3 offset:672
	ds_read_b128 v[232:235], v3 offset:688
	ds_read_b128 v[236:239], v3 offset:704
	ds_read_b128 v[240:243], v3 offset:720
	ds_read_b128 v[244:247], v3 offset:736
	ds_read_b128 v[248:251], v3 offset:752
	global_load_ushort v152, v1, s[20:21]
	global_load_ushort v153, v1, s[20:21] offset:1024
	s_add_u32 s20, s20, 0x1a00
	s_addc_u32 s21, s21, 0
	global_load_ushort v154, v1, s[20:21]
	global_load_ushort v155, v1, s[20:21] offset:1024
	s_add_u32 s20, s20, 0x1a00
	s_addc_u32 s21, s21, 0
	v_pk_fma_f32 v[50:51], v[16:17], v[34:35], v[32:33] op_sel_hi:[0,1,0]
	v_pk_fma_f32 v[50:51], v[16:17], v[36:37], v[50:51] op_sel:[1,0,0] op_sel_hi:[1,1,1]
	v_pk_fma_f32 v[50:51], v[18:19], v[38:39], v[50:51] op_sel_hi:[0,1,1]
	v_pk_fma_f32 v[50:51], v[18:19], v[40:41], v[50:51] op_sel:[1,0,0] op_sel_hi:[1,1,1]
	v_pk_fma_f32 v[50:51], v[20:21], v[42:43], v[50:51] op_sel_hi:[0,1,1]
	v_pk_fma_f32 v[50:51], v[20:21], v[44:45], v[50:51] op_sel:[1,0,0] op_sel_hi:[1,1,1]
	v_pk_fma_f32 v[50:51], v[22:23], v[46:47], v[50:51] op_sel_hi:[0,1,1]
	v_pk_fma_f32 v[50:51], v[22:23], v[48:49], v[50:51] op_sel:[1,0,0] op_sel_hi:[1,1,1]
	v_pk_fma_f32 v[50:51], v[24:25], v[200:201], v[50:51] op_sel_hi:[0,1,1]
	v_pk_fma_f32 v[50:51], v[24:25], v[202:203], v[50:51] op_sel:[1,0,0] op_sel_hi:[1,1,1]
	v_pk_fma_f32 v[50:51], v[26:27], v[204:205], v[50:51] op_sel_hi:[0,1,1]
	v_pk_fma_f32 v[50:51], v[26:27], v[206:207], v[50:51] op_sel:[1,0,0] op_sel_hi:[1,1,1]
	v_pk_fma_f32 v[50:51], v[28:29], v[208:209], v[50:51] op_sel_hi:[0,1,1]
	v_pk_fma_f32 v[50:51], v[28:29], v[210:211], v[50:51] op_sel:[1,0,0] op_sel_hi:[1,1,1]
	v_pk_fma_f32 v[50:51], v[30:31], v[212:213], v[50:51] op_sel_hi:[0,1,1]
	v_pk_fma_f32 v[50:51], v[30:31], v[214:215], v[50:51] op_sel:[1,0,0] op_sel_hi:[1,1,1]
	v_mul_f32_e64 v52, |v50|, s7
	v_mul_f32_e64 v53, |v51|, s7
	v_exp_f32_e32 v52, v52
	v_exp_f32_e32 v53, v53
	v_min_f32_e32 v50, 0, v50
	v_min_f32_e32 v51, 0, v51
	v_pk_add_f32 v[52:53], v[52:53], 1.0 op_sel_hi:[1,0]
	v_log_f32_e32 v52, v52
	v_log_f32_e32 v53, v53
	s_nop 0
	v_pk_mul_f32 v[54:55], v[52:53], s[8:9] op_sel:[0,1] op_sel_hi:[1,1]
	v_pk_fma_f32 v[56:57], v[52:53], s[8:9], v[54:55] op_sel:[0,1,0] op_sel_hi:[1,1,1] neg_lo:[0,0,1] neg_hi:[0,0,1]
	v_pk_fma_f32 v[56:57], v[52:53], s[86:87], v[56:57] op_sel:[0,1,0] op_sel_hi:[1,1,1]
	v_pk_add_f32 v[54:55], v[54:55], v[56:57]
	v_pk_add_f32 v[50:51], v[50:51], v[54:55] neg_lo:[0,1] neg_hi:[0,1]
	v_fmamk_f32 v72, v50, 0x3d800000, v71
	v_fmamk_f32 v73, v51, 0x3d800000, v72
	s_waitcnt lgkmcnt(0)
	ds_read_b128 v[34:37], v3 offset:768
	ds_read_b128 v[38:41], v3 offset:784
	ds_read_b128 v[42:45], v3 offset:800
	ds_read_b128 v[46:49], v3 offset:816
	ds_read_b128 v[200:203], v3 offset:832
	ds_read_b128 v[204:207], v3 offset:848
	ds_read_b128 v[208:211], v3 offset:864
	ds_read_b128 v[212:215], v3 offset:880
	global_load_ushort v156, v1, s[20:21]
	global_load_ushort v157, v1, s[20:21] offset:1024
	s_add_u32 s20, s20, 0x1a00
	s_addc_u32 s21, s21, 0
	global_load_ushort v158, v1, s[20:21]
	global_load_ushort v159, v1, s[20:21] offset:1024
	s_add_u32 s20, s20, 0x1a00
	s_addc_u32 s21, s21, 0
	v_pk_fma_f32 v[50:51], v[16:17], v[216:217], v[32:33] op_sel_hi:[0,1,0]
	v_pk_fma_f32 v[50:51], v[16:17], v[218:219], v[50:51] op_sel:[1,0,0] op_sel_hi:[1,1,1]
	v_pk_fma_f32 v[50:51], v[18:19], v[220:221], v[50:51] op_sel_hi:[0,1,1]
	v_pk_fma_f32 v[50:51], v[18:19], v[222:223], v[50:51] op_sel:[1,0,0] op_sel_hi:[1,1,1]
	v_pk_fma_f32 v[50:51], v[20:21], v[224:225], v[50:51] op_sel_hi:[0,1,1]
	v_pk_fma_f32 v[50:51], v[20:21], v[226:227], v[50:51] op_sel:[1,0,0] op_sel_hi:[1,1,1]
	v_pk_fma_f32 v[50:51], v[22:23], v[232:233], v[50:51] op_sel_hi:[0,1,1]
	v_pk_fma_f32 v[50:51], v[22:23], v[234:235], v[50:51] op_sel:[1,0,0] op_sel_hi:[1,1,1]
	v_pk_fma_f32 v[50:51], v[24:25], v[236:237], v[50:51] op_sel_hi:[0,1,1]
	v_pk_fma_f32 v[50:51], v[24:25], v[238:239], v[50:51] op_sel:[1,0,0] op_sel_hi:[1,1,1]
	v_pk_fma_f32 v[50:51], v[26:27], v[240:241], v[50:51] op_sel_hi:[0,1,1]
	v_pk_fma_f32 v[50:51], v[26:27], v[242:243], v[50:51] op_sel:[1,0,0] op_sel_hi:[1,1,1]
	v_pk_fma_f32 v[50:51], v[28:29], v[244:245], v[50:51] op_sel_hi:[0,1,1]
	v_pk_fma_f32 v[50:51], v[28:29], v[246:247], v[50:51] op_sel:[1,0,0] op_sel_hi:[1,1,1]
	v_pk_fma_f32 v[50:51], v[30:31], v[248:249], v[50:51] op_sel_hi:[0,1,1]
	v_pk_fma_f32 v[50:51], v[30:31], v[250:251], v[50:51] op_sel:[1,0,0] op_sel_hi:[1,1,1]
	v_mul_f32_e64 v52, |v50|, s7
	v_mul_f32_e64 v53, |v51|, s7
	v_exp_f32_e32 v52, v52
	v_exp_f32_e32 v53, v53
	v_min_f32_e32 v50, 0, v50
	v_min_f32_e32 v51, 0, v51
	v_pk_add_f32 v[52:53], v[52:53], 1.0 op_sel_hi:[1,0]
	v_log_f32_e32 v52, v52
	v_log_f32_e32 v53, v53
	s_nop 0
	v_pk_mul_f32 v[54:55], v[52:53], s[8:9] op_sel:[0,1] op_sel_hi:[1,1]
	v_pk_fma_f32 v[56:57], v[52:53], s[8:9], v[54:55] op_sel:[0,1,0] op_sel_hi:[1,1,1] neg_lo:[0,0,1] neg_hi:[0,0,1]
	v_pk_fma_f32 v[56:57], v[52:53], s[86:87], v[56:57] op_sel:[0,1,0] op_sel_hi:[1,1,1]
	v_pk_add_f32 v[54:55], v[54:55], v[56:57]
	v_pk_add_f32 v[50:51], v[50:51], v[54:55] neg_lo:[0,1] neg_hi:[0,1]
	v_fmamk_f32 v74, v50, 0x3d800000, v73
	v_fmamk_f32 v75, v51, 0x3d800000, v74
	s_waitcnt lgkmcnt(0)
	ds_read_b128 v[216:219], v3 offset:896
	ds_read_b128 v[220:223], v3 offset:912
	ds_read_b128 v[224:227], v3 offset:928
	ds_read_b128 v[232:235], v3 offset:944
	ds_read_b128 v[236:239], v3 offset:960
	ds_read_b128 v[240:243], v3 offset:976
	ds_read_b128 v[244:247], v3 offset:992
	ds_read_b128 v[248:251], v3 offset:1008
	global_load_ushort v160, v1, s[20:21]
	global_load_ushort v161, v1, s[20:21] offset:1024
	s_add_u32 s20, s20, 0x1a00
	s_addc_u32 s21, s21, 0
	global_load_ushort v162, v1, s[20:21]
	global_load_ushort v163, v1, s[20:21] offset:1024
	s_add_u32 s20, s20, 0x1a00
	s_addc_u32 s21, s21, 0
	v_pk_fma_f32 v[50:51], v[16:17], v[34:35], v[32:33] op_sel_hi:[0,1,0]
	v_pk_fma_f32 v[50:51], v[16:17], v[36:37], v[50:51] op_sel:[1,0,0] op_sel_hi:[1,1,1]
	v_pk_fma_f32 v[50:51], v[18:19], v[38:39], v[50:51] op_sel_hi:[0,1,1]
	v_pk_fma_f32 v[50:51], v[18:19], v[40:41], v[50:51] op_sel:[1,0,0] op_sel_hi:[1,1,1]
	v_pk_fma_f32 v[50:51], v[20:21], v[42:43], v[50:51] op_sel_hi:[0,1,1]
	v_pk_fma_f32 v[50:51], v[20:21], v[44:45], v[50:51] op_sel:[1,0,0] op_sel_hi:[1,1,1]
	v_pk_fma_f32 v[50:51], v[22:23], v[46:47], v[50:51] op_sel_hi:[0,1,1]
	v_pk_fma_f32 v[50:51], v[22:23], v[48:49], v[50:51] op_sel:[1,0,0] op_sel_hi:[1,1,1]
	v_pk_fma_f32 v[50:51], v[24:25], v[200:201], v[50:51] op_sel_hi:[0,1,1]
	v_pk_fma_f32 v[50:51], v[24:25], v[202:203], v[50:51] op_sel:[1,0,0] op_sel_hi:[1,1,1]
	v_pk_fma_f32 v[50:51], v[26:27], v[204:205], v[50:51] op_sel_hi:[0,1,1]
	v_pk_fma_f32 v[50:51], v[26:27], v[206:207], v[50:51] op_sel:[1,0,0] op_sel_hi:[1,1,1]
	v_pk_fma_f32 v[50:51], v[28:29], v[208:209], v[50:51] op_sel_hi:[0,1,1]
	v_pk_fma_f32 v[50:51], v[28:29], v[210:211], v[50:51] op_sel:[1,0,0] op_sel_hi:[1,1,1]
	v_pk_fma_f32 v[50:51], v[30:31], v[212:213], v[50:51] op_sel_hi:[0,1,1]
	v_pk_fma_f32 v[50:51], v[30:31], v[214:215], v[50:51] op_sel:[1,0,0] op_sel_hi:[1,1,1]
	v_mul_f32_e64 v52, |v50|, s7
	v_mul_f32_e64 v53, |v51|, s7
	v_exp_f32_e32 v52, v52
	v_exp_f32_e32 v53, v53
	v_min_f32_e32 v50, 0, v50
	v_min_f32_e32 v51, 0, v51
	v_pk_add_f32 v[52:53], v[52:53], 1.0 op_sel_hi:[1,0]
	v_log_f32_e32 v52, v52
	v_log_f32_e32 v53, v53
	s_nop 0
	v_pk_mul_f32 v[54:55], v[52:53], s[8:9] op_sel:[0,1] op_sel_hi:[1,1]
	v_pk_fma_f32 v[56:57], v[52:53], s[8:9], v[54:55] op_sel:[0,1,0] op_sel_hi:[1,1,1] neg_lo:[0,0,1] neg_hi:[0,0,1]
	v_pk_fma_f32 v[56:57], v[52:53], s[86:87], v[56:57] op_sel:[0,1,0] op_sel_hi:[1,1,1]
	v_pk_add_f32 v[54:55], v[54:55], v[56:57]
	v_pk_add_f32 v[50:51], v[50:51], v[54:55] neg_lo:[0,1] neg_hi:[0,1]
	v_fmamk_f32 v76, v50, 0x3d800000, v75
	v_fmamk_f32 v77, v51, 0x3d800000, v76
	s_waitcnt lgkmcnt(0)
	ds_read_b128 v[34:37], v3 offset:1024
	ds_read_b128 v[38:41], v3 offset:1040
	ds_read_b128 v[42:45], v3 offset:1056
	ds_read_b128 v[46:49], v3 offset:1072
	ds_read_b128 v[200:203], v3 offset:1088
	ds_read_b128 v[204:207], v3 offset:1104
	ds_read_b128 v[208:211], v3 offset:1120
	ds_read_b128 v[212:215], v3 offset:1136
	global_load_ushort v164, v1, s[20:21]
	global_load_ushort v165, v1, s[20:21] offset:1024
	s_add_u32 s20, s20, 0x1a00
	s_addc_u32 s21, s21, 0
	global_load_ushort v166, v1, s[20:21]
	global_load_ushort v167, v1, s[20:21] offset:1024
	s_add_u32 s20, s20, 0x1a00
	s_addc_u32 s21, s21, 0
	v_pk_fma_f32 v[50:51], v[16:17], v[216:217], v[32:33] op_sel_hi:[0,1,0]
	v_pk_fma_f32 v[50:51], v[16:17], v[218:219], v[50:51] op_sel:[1,0,0] op_sel_hi:[1,1,1]
	v_pk_fma_f32 v[50:51], v[18:19], v[220:221], v[50:51] op_sel_hi:[0,1,1]
	v_pk_fma_f32 v[50:51], v[18:19], v[222:223], v[50:51] op_sel:[1,0,0] op_sel_hi:[1,1,1]
	v_pk_fma_f32 v[50:51], v[20:21], v[224:225], v[50:51] op_sel_hi:[0,1,1]
	v_pk_fma_f32 v[50:51], v[20:21], v[226:227], v[50:51] op_sel:[1,0,0] op_sel_hi:[1,1,1]
	v_pk_fma_f32 v[50:51], v[22:23], v[232:233], v[50:51] op_sel_hi:[0,1,1]
	v_pk_fma_f32 v[50:51], v[22:23], v[234:235], v[50:51] op_sel:[1,0,0] op_sel_hi:[1,1,1]
	v_pk_fma_f32 v[50:51], v[24:25], v[236:237], v[50:51] op_sel_hi:[0,1,1]
	v_pk_fma_f32 v[50:51], v[24:25], v[238:239], v[50:51] op_sel:[1,0,0] op_sel_hi:[1,1,1]
	v_pk_fma_f32 v[50:51], v[26:27], v[240:241], v[50:51] op_sel_hi:[0,1,1]
	v_pk_fma_f32 v[50:51], v[26:27], v[242:243], v[50:51] op_sel:[1,0,0] op_sel_hi:[1,1,1]
	v_pk_fma_f32 v[50:51], v[28:29], v[244:245], v[50:51] op_sel_hi:[0,1,1]
	v_pk_fma_f32 v[50:51], v[28:29], v[246:247], v[50:51] op_sel:[1,0,0] op_sel_hi:[1,1,1]
	v_pk_fma_f32 v[50:51], v[30:31], v[248:249], v[50:51] op_sel_hi:[0,1,1]
	v_pk_fma_f32 v[50:51], v[30:31], v[250:251], v[50:51] op_sel:[1,0,0] op_sel_hi:[1,1,1]
	v_mul_f32_e64 v52, |v50|, s7
	v_mul_f32_e64 v53, |v51|, s7
	v_exp_f32_e32 v52, v52
	v_exp_f32_e32 v53, v53
	v_min_f32_e32 v50, 0, v50
	v_min_f32_e32 v51, 0, v51
	v_pk_add_f32 v[52:53], v[52:53], 1.0 op_sel_hi:[1,0]
	v_log_f32_e32 v52, v52
	v_log_f32_e32 v53, v53
	s_nop 0
	v_pk_mul_f32 v[54:55], v[52:53], s[8:9] op_sel:[0,1] op_sel_hi:[1,1]
	v_pk_fma_f32 v[56:57], v[52:53], s[8:9], v[54:55] op_sel:[0,1,0] op_sel_hi:[1,1,1] neg_lo:[0,0,1] neg_hi:[0,0,1]
	v_pk_fma_f32 v[56:57], v[52:53], s[86:87], v[56:57] op_sel:[0,1,0] op_sel_hi:[1,1,1]
	v_pk_add_f32 v[54:55], v[54:55], v[56:57]
	v_pk_add_f32 v[50:51], v[50:51], v[54:55] neg_lo:[0,1] neg_hi:[0,1]
	v_fmamk_f32 v78, v50, 0x3d800000, v77
	v_fmamk_f32 v79, v51, 0x3d800000, v78
	s_waitcnt lgkmcnt(0)
	ds_read_b128 v[216:219], v3 offset:1152
	ds_read_b128 v[220:223], v3 offset:1168
	ds_read_b128 v[224:227], v3 offset:1184
	ds_read_b128 v[232:235], v3 offset:1200
	ds_read_b128 v[236:239], v3 offset:1216
	ds_read_b128 v[240:243], v3 offset:1232
	ds_read_b128 v[244:247], v3 offset:1248
	ds_read_b128 v[248:251], v3 offset:1264
	global_load_ushort v168, v1, s[20:21]
	global_load_ushort v169, v1, s[20:21] offset:1024
	s_add_u32 s20, s20, 0x1a00
	s_addc_u32 s21, s21, 0
	global_load_ushort v170, v1, s[20:21]
	global_load_ushort v171, v1, s[20:21] offset:1024
	s_add_u32 s20, s20, 0x1a00
	s_addc_u32 s21, s21, 0
	v_pk_fma_f32 v[50:51], v[16:17], v[34:35], v[32:33] op_sel_hi:[0,1,0]
	v_pk_fma_f32 v[50:51], v[16:17], v[36:37], v[50:51] op_sel:[1,0,0] op_sel_hi:[1,1,1]
	v_pk_fma_f32 v[50:51], v[18:19], v[38:39], v[50:51] op_sel_hi:[0,1,1]
	v_pk_fma_f32 v[50:51], v[18:19], v[40:41], v[50:51] op_sel:[1,0,0] op_sel_hi:[1,1,1]
	v_pk_fma_f32 v[50:51], v[20:21], v[42:43], v[50:51] op_sel_hi:[0,1,1]
	v_pk_fma_f32 v[50:51], v[20:21], v[44:45], v[50:51] op_sel:[1,0,0] op_sel_hi:[1,1,1]
	v_pk_fma_f32 v[50:51], v[22:23], v[46:47], v[50:51] op_sel_hi:[0,1,1]
	v_pk_fma_f32 v[50:51], v[22:23], v[48:49], v[50:51] op_sel:[1,0,0] op_sel_hi:[1,1,1]
	v_pk_fma_f32 v[50:51], v[24:25], v[200:201], v[50:51] op_sel_hi:[0,1,1]
	v_pk_fma_f32 v[50:51], v[24:25], v[202:203], v[50:51] op_sel:[1,0,0] op_sel_hi:[1,1,1]
	v_pk_fma_f32 v[50:51], v[26:27], v[204:205], v[50:51] op_sel_hi:[0,1,1]
	v_pk_fma_f32 v[50:51], v[26:27], v[206:207], v[50:51] op_sel:[1,0,0] op_sel_hi:[1,1,1]
	v_pk_fma_f32 v[50:51], v[28:29], v[208:209], v[50:51] op_sel_hi:[0,1,1]
	v_pk_fma_f32 v[50:51], v[28:29], v[210:211], v[50:51] op_sel:[1,0,0] op_sel_hi:[1,1,1]
	v_pk_fma_f32 v[50:51], v[30:31], v[212:213], v[50:51] op_sel_hi:[0,1,1]
	v_pk_fma_f32 v[50:51], v[30:31], v[214:215], v[50:51] op_sel:[1,0,0] op_sel_hi:[1,1,1]
	v_mul_f32_e64 v52, |v50|, s7
	v_mul_f32_e64 v53, |v51|, s7
	v_exp_f32_e32 v52, v52
	v_exp_f32_e32 v53, v53
	v_min_f32_e32 v50, 0, v50
	v_min_f32_e32 v51, 0, v51
	v_pk_add_f32 v[52:53], v[52:53], 1.0 op_sel_hi:[1,0]
	v_log_f32_e32 v52, v52
	v_log_f32_e32 v53, v53
	s_nop 0
	v_pk_mul_f32 v[54:55], v[52:53], s[8:9] op_sel:[0,1] op_sel_hi:[1,1]
	v_pk_fma_f32 v[56:57], v[52:53], s[8:9], v[54:55] op_sel:[0,1,0] op_sel_hi:[1,1,1] neg_lo:[0,0,1] neg_hi:[0,0,1]
	v_pk_fma_f32 v[56:57], v[52:53], s[86:87], v[56:57] op_sel:[0,1,0] op_sel_hi:[1,1,1]
	v_pk_add_f32 v[54:55], v[54:55], v[56:57]
	v_pk_add_f32 v[50:51], v[50:51], v[54:55] neg_lo:[0,1] neg_hi:[0,1]
	v_fmamk_f32 v80, v50, 0x3d800000, v79
	v_fmamk_f32 v81, v51, 0x3d800000, v80
	s_waitcnt lgkmcnt(0)
	ds_read_b128 v[34:37], v3 offset:1280
	ds_read_b128 v[38:41], v3 offset:1296
	ds_read_b128 v[42:45], v3 offset:1312
	ds_read_b128 v[46:49], v3 offset:1328
	ds_read_b128 v[200:203], v3 offset:1344
	ds_read_b128 v[204:207], v3 offset:1360
	ds_read_b128 v[208:211], v3 offset:1376
	ds_read_b128 v[212:215], v3 offset:1392
	global_load_ushort v172, v1, s[20:21]
	global_load_ushort v173, v1, s[20:21] offset:1024
	s_add_u32 s20, s20, 0x1a00
	s_addc_u32 s21, s21, 0
	global_load_ushort v174, v1, s[20:21]
	global_load_ushort v175, v1, s[20:21] offset:1024
	s_add_u32 s20, s20, 0x1a00
	s_addc_u32 s21, s21, 0
	v_pk_fma_f32 v[50:51], v[16:17], v[216:217], v[32:33] op_sel_hi:[0,1,0]
	v_pk_fma_f32 v[50:51], v[16:17], v[218:219], v[50:51] op_sel:[1,0,0] op_sel_hi:[1,1,1]
	v_pk_fma_f32 v[50:51], v[18:19], v[220:221], v[50:51] op_sel_hi:[0,1,1]
	v_pk_fma_f32 v[50:51], v[18:19], v[222:223], v[50:51] op_sel:[1,0,0] op_sel_hi:[1,1,1]
	v_pk_fma_f32 v[50:51], v[20:21], v[224:225], v[50:51] op_sel_hi:[0,1,1]
	v_pk_fma_f32 v[50:51], v[20:21], v[226:227], v[50:51] op_sel:[1,0,0] op_sel_hi:[1,1,1]
	v_pk_fma_f32 v[50:51], v[22:23], v[232:233], v[50:51] op_sel_hi:[0,1,1]
	v_pk_fma_f32 v[50:51], v[22:23], v[234:235], v[50:51] op_sel:[1,0,0] op_sel_hi:[1,1,1]
	v_pk_fma_f32 v[50:51], v[24:25], v[236:237], v[50:51] op_sel_hi:[0,1,1]
	v_pk_fma_f32 v[50:51], v[24:25], v[238:239], v[50:51] op_sel:[1,0,0] op_sel_hi:[1,1,1]
	v_pk_fma_f32 v[50:51], v[26:27], v[240:241], v[50:51] op_sel_hi:[0,1,1]
	v_pk_fma_f32 v[50:51], v[26:27], v[242:243], v[50:51] op_sel:[1,0,0] op_sel_hi:[1,1,1]
	v_pk_fma_f32 v[50:51], v[28:29], v[244:245], v[50:51] op_sel_hi:[0,1,1]
	v_pk_fma_f32 v[50:51], v[28:29], v[246:247], v[50:51] op_sel:[1,0,0] op_sel_hi:[1,1,1]
	v_pk_fma_f32 v[50:51], v[30:31], v[248:249], v[50:51] op_sel_hi:[0,1,1]
	v_pk_fma_f32 v[50:51], v[30:31], v[250:251], v[50:51] op_sel:[1,0,0] op_sel_hi:[1,1,1]
	v_mul_f32_e64 v52, |v50|, s7
	v_mul_f32_e64 v53, |v51|, s7
	v_exp_f32_e32 v52, v52
	v_exp_f32_e32 v53, v53
	v_min_f32_e32 v50, 0, v50
	v_min_f32_e32 v51, 0, v51
	v_pk_add_f32 v[52:53], v[52:53], 1.0 op_sel_hi:[1,0]
	v_log_f32_e32 v52, v52
	v_log_f32_e32 v53, v53
	s_nop 0
	v_pk_mul_f32 v[54:55], v[52:53], s[8:9] op_sel:[0,1] op_sel_hi:[1,1]
	v_pk_fma_f32 v[56:57], v[52:53], s[8:9], v[54:55] op_sel:[0,1,0] op_sel_hi:[1,1,1] neg_lo:[0,0,1] neg_hi:[0,0,1]
	v_pk_fma_f32 v[56:57], v[52:53], s[86:87], v[56:57] op_sel:[0,1,0] op_sel_hi:[1,1,1]
	v_pk_add_f32 v[54:55], v[54:55], v[56:57]
	v_pk_add_f32 v[50:51], v[50:51], v[54:55] neg_lo:[0,1] neg_hi:[0,1]
	v_fmamk_f32 v82, v50, 0x3d800000, v81
	v_fmamk_f32 v83, v51, 0x3d800000, v82
	s_waitcnt lgkmcnt(0)
	ds_read_b128 v[216:219], v3 offset:1408
	ds_read_b128 v[220:223], v3 offset:1424
	ds_read_b128 v[224:227], v3 offset:1440
	ds_read_b128 v[232:235], v3 offset:1456
	ds_read_b128 v[236:239], v3 offset:1472
	ds_read_b128 v[240:243], v3 offset:1488
	ds_read_b128 v[244:247], v3 offset:1504
	ds_read_b128 v[248:251], v3 offset:1520
	global_load_ushort v176, v1, s[20:21]
	global_load_ushort v177, v1, s[20:21] offset:1024
	s_add_u32 s20, s20, 0x1a00
	s_addc_u32 s21, s21, 0
	global_load_ushort v178, v1, s[20:21]
	global_load_ushort v179, v1, s[20:21] offset:1024
	s_add_u32 s20, s20, 0x1a00
	s_addc_u32 s21, s21, 0
	v_pk_fma_f32 v[50:51], v[16:17], v[34:35], v[32:33] op_sel_hi:[0,1,0]
	v_pk_fma_f32 v[50:51], v[16:17], v[36:37], v[50:51] op_sel:[1,0,0] op_sel_hi:[1,1,1]
	v_pk_fma_f32 v[50:51], v[18:19], v[38:39], v[50:51] op_sel_hi:[0,1,1]
	v_pk_fma_f32 v[50:51], v[18:19], v[40:41], v[50:51] op_sel:[1,0,0] op_sel_hi:[1,1,1]
	v_pk_fma_f32 v[50:51], v[20:21], v[42:43], v[50:51] op_sel_hi:[0,1,1]
	v_pk_fma_f32 v[50:51], v[20:21], v[44:45], v[50:51] op_sel:[1,0,0] op_sel_hi:[1,1,1]
	v_pk_fma_f32 v[50:51], v[22:23], v[46:47], v[50:51] op_sel_hi:[0,1,1]
	v_pk_fma_f32 v[50:51], v[22:23], v[48:49], v[50:51] op_sel:[1,0,0] op_sel_hi:[1,1,1]
	v_pk_fma_f32 v[50:51], v[24:25], v[200:201], v[50:51] op_sel_hi:[0,1,1]
	v_pk_fma_f32 v[50:51], v[24:25], v[202:203], v[50:51] op_sel:[1,0,0] op_sel_hi:[1,1,1]
	v_pk_fma_f32 v[50:51], v[26:27], v[204:205], v[50:51] op_sel_hi:[0,1,1]
	v_pk_fma_f32 v[50:51], v[26:27], v[206:207], v[50:51] op_sel:[1,0,0] op_sel_hi:[1,1,1]
	v_pk_fma_f32 v[50:51], v[28:29], v[208:209], v[50:51] op_sel_hi:[0,1,1]
	v_pk_fma_f32 v[50:51], v[28:29], v[210:211], v[50:51] op_sel:[1,0,0] op_sel_hi:[1,1,1]
	v_pk_fma_f32 v[50:51], v[30:31], v[212:213], v[50:51] op_sel_hi:[0,1,1]
	v_pk_fma_f32 v[50:51], v[30:31], v[214:215], v[50:51] op_sel:[1,0,0] op_sel_hi:[1,1,1]
	v_mul_f32_e64 v52, |v50|, s7
	v_mul_f32_e64 v53, |v51|, s7
	v_exp_f32_e32 v52, v52
	v_exp_f32_e32 v53, v53
	v_min_f32_e32 v50, 0, v50
	v_min_f32_e32 v51, 0, v51
	v_pk_add_f32 v[52:53], v[52:53], 1.0 op_sel_hi:[1,0]
	v_log_f32_e32 v52, v52
	v_log_f32_e32 v53, v53
	s_nop 0
	v_pk_mul_f32 v[54:55], v[52:53], s[8:9] op_sel:[0,1] op_sel_hi:[1,1]
	v_pk_fma_f32 v[56:57], v[52:53], s[8:9], v[54:55] op_sel:[0,1,0] op_sel_hi:[1,1,1] neg_lo:[0,0,1] neg_hi:[0,0,1]
	v_pk_fma_f32 v[56:57], v[52:53], s[86:87], v[56:57] op_sel:[0,1,0] op_sel_hi:[1,1,1]
	v_pk_add_f32 v[54:55], v[54:55], v[56:57]
	v_pk_add_f32 v[50:51], v[50:51], v[54:55] neg_lo:[0,1] neg_hi:[0,1]
	v_fmamk_f32 v84, v50, 0x3d800000, v83
	v_fmamk_f32 v85, v51, 0x3d800000, v84
	s_waitcnt lgkmcnt(0)
	ds_read_b128 v[34:37], v3 offset:1536
	ds_read_b128 v[38:41], v3 offset:1552
	ds_read_b128 v[42:45], v3 offset:1568
	ds_read_b128 v[46:49], v3 offset:1584
	ds_read_b128 v[200:203], v3 offset:1600
	ds_read_b128 v[204:207], v3 offset:1616
	ds_read_b128 v[208:211], v3 offset:1632
	ds_read_b128 v[212:215], v3 offset:1648
	global_load_ushort v180, v1, s[20:21]
	global_load_ushort v181, v1, s[20:21] offset:1024
	s_add_u32 s20, s20, 0x1a00
	s_addc_u32 s21, s21, 0
	global_load_ushort v182, v1, s[20:21]
	global_load_ushort v183, v1, s[20:21] offset:1024
	s_add_u32 s20, s20, 0x1a00
	s_addc_u32 s21, s21, 0
	v_pk_fma_f32 v[50:51], v[16:17], v[216:217], v[32:33] op_sel_hi:[0,1,0]
	v_pk_fma_f32 v[50:51], v[16:17], v[218:219], v[50:51] op_sel:[1,0,0] op_sel_hi:[1,1,1]
	v_pk_fma_f32 v[50:51], v[18:19], v[220:221], v[50:51] op_sel_hi:[0,1,1]
	v_pk_fma_f32 v[50:51], v[18:19], v[222:223], v[50:51] op_sel:[1,0,0] op_sel_hi:[1,1,1]
	v_pk_fma_f32 v[50:51], v[20:21], v[224:225], v[50:51] op_sel_hi:[0,1,1]
	v_pk_fma_f32 v[50:51], v[20:21], v[226:227], v[50:51] op_sel:[1,0,0] op_sel_hi:[1,1,1]
	v_pk_fma_f32 v[50:51], v[22:23], v[232:233], v[50:51] op_sel_hi:[0,1,1]
	v_pk_fma_f32 v[50:51], v[22:23], v[234:235], v[50:51] op_sel:[1,0,0] op_sel_hi:[1,1,1]
	v_pk_fma_f32 v[50:51], v[24:25], v[236:237], v[50:51] op_sel_hi:[0,1,1]
	v_pk_fma_f32 v[50:51], v[24:25], v[238:239], v[50:51] op_sel:[1,0,0] op_sel_hi:[1,1,1]
	v_pk_fma_f32 v[50:51], v[26:27], v[240:241], v[50:51] op_sel_hi:[0,1,1]
	v_pk_fma_f32 v[50:51], v[26:27], v[242:243], v[50:51] op_sel:[1,0,0] op_sel_hi:[1,1,1]
	v_pk_fma_f32 v[50:51], v[28:29], v[244:245], v[50:51] op_sel_hi:[0,1,1]
	v_pk_fma_f32 v[50:51], v[28:29], v[246:247], v[50:51] op_sel:[1,0,0] op_sel_hi:[1,1,1]
	v_pk_fma_f32 v[50:51], v[30:31], v[248:249], v[50:51] op_sel_hi:[0,1,1]
	v_pk_fma_f32 v[50:51], v[30:31], v[250:251], v[50:51] op_sel:[1,0,0] op_sel_hi:[1,1,1]
	v_mul_f32_e64 v52, |v50|, s7
	v_mul_f32_e64 v53, |v51|, s7
	v_exp_f32_e32 v52, v52
	v_exp_f32_e32 v53, v53
	v_min_f32_e32 v50, 0, v50
	v_min_f32_e32 v51, 0, v51
	v_pk_add_f32 v[52:53], v[52:53], 1.0 op_sel_hi:[1,0]
	v_log_f32_e32 v52, v52
	v_log_f32_e32 v53, v53
	s_nop 0
	v_pk_mul_f32 v[54:55], v[52:53], s[8:9] op_sel:[0,1] op_sel_hi:[1,1]
	v_pk_fma_f32 v[56:57], v[52:53], s[8:9], v[54:55] op_sel:[0,1,0] op_sel_hi:[1,1,1] neg_lo:[0,0,1] neg_hi:[0,0,1]
	v_pk_fma_f32 v[56:57], v[52:53], s[86:87], v[56:57] op_sel:[0,1,0] op_sel_hi:[1,1,1]
	v_pk_add_f32 v[54:55], v[54:55], v[56:57]
	v_pk_add_f32 v[50:51], v[50:51], v[54:55] neg_lo:[0,1] neg_hi:[0,1]
	v_fmamk_f32 v86, v50, 0x3d800000, v85
	v_fmamk_f32 v87, v51, 0x3d800000, v86
	s_waitcnt lgkmcnt(0)
	ds_read_b128 v[216:219], v3 offset:1664
	ds_read_b128 v[220:223], v3 offset:1680
	ds_read_b128 v[224:227], v3 offset:1696
	ds_read_b128 v[232:235], v3 offset:1712
	ds_read_b128 v[236:239], v3 offset:1728
	ds_read_b128 v[240:243], v3 offset:1744
	ds_read_b128 v[244:247], v3 offset:1760
	ds_read_b128 v[248:251], v3 offset:1776
	global_load_ushort v184, v1, s[20:21]
	global_load_ushort v185, v1, s[20:21] offset:1024
	s_add_u32 s20, s20, 0x1a00
	s_addc_u32 s21, s21, 0
	global_load_ushort v186, v1, s[20:21]
	global_load_ushort v187, v1, s[20:21] offset:1024
	s_add_u32 s20, s20, 0x1a00
	s_addc_u32 s21, s21, 0
	v_pk_fma_f32 v[50:51], v[16:17], v[34:35], v[32:33] op_sel_hi:[0,1,0]
	v_pk_fma_f32 v[50:51], v[16:17], v[36:37], v[50:51] op_sel:[1,0,0] op_sel_hi:[1,1,1]
	v_pk_fma_f32 v[50:51], v[18:19], v[38:39], v[50:51] op_sel_hi:[0,1,1]
	v_pk_fma_f32 v[50:51], v[18:19], v[40:41], v[50:51] op_sel:[1,0,0] op_sel_hi:[1,1,1]
	v_pk_fma_f32 v[50:51], v[20:21], v[42:43], v[50:51] op_sel_hi:[0,1,1]
	v_pk_fma_f32 v[50:51], v[20:21], v[44:45], v[50:51] op_sel:[1,0,0] op_sel_hi:[1,1,1]
	v_pk_fma_f32 v[50:51], v[22:23], v[46:47], v[50:51] op_sel_hi:[0,1,1]
	v_pk_fma_f32 v[50:51], v[22:23], v[48:49], v[50:51] op_sel:[1,0,0] op_sel_hi:[1,1,1]
	v_pk_fma_f32 v[50:51], v[24:25], v[200:201], v[50:51] op_sel_hi:[0,1,1]
	v_pk_fma_f32 v[50:51], v[24:25], v[202:203], v[50:51] op_sel:[1,0,0] op_sel_hi:[1,1,1]
	v_pk_fma_f32 v[50:51], v[26:27], v[204:205], v[50:51] op_sel_hi:[0,1,1]
	v_pk_fma_f32 v[50:51], v[26:27], v[206:207], v[50:51] op_sel:[1,0,0] op_sel_hi:[1,1,1]
	v_pk_fma_f32 v[50:51], v[28:29], v[208:209], v[50:51] op_sel_hi:[0,1,1]
	v_pk_fma_f32 v[50:51], v[28:29], v[210:211], v[50:51] op_sel:[1,0,0] op_sel_hi:[1,1,1]
	v_pk_fma_f32 v[50:51], v[30:31], v[212:213], v[50:51] op_sel_hi:[0,1,1]
	v_pk_fma_f32 v[50:51], v[30:31], v[214:215], v[50:51] op_sel:[1,0,0] op_sel_hi:[1,1,1]
	v_mul_f32_e64 v52, |v50|, s7
	v_mul_f32_e64 v53, |v51|, s7
	v_exp_f32_e32 v52, v52
	v_exp_f32_e32 v53, v53
	v_min_f32_e32 v50, 0, v50
	v_min_f32_e32 v51, 0, v51
	v_pk_add_f32 v[52:53], v[52:53], 1.0 op_sel_hi:[1,0]
	v_log_f32_e32 v52, v52
	v_log_f32_e32 v53, v53
	s_nop 0
	v_pk_mul_f32 v[54:55], v[52:53], s[8:9] op_sel:[0,1] op_sel_hi:[1,1]
	v_pk_fma_f32 v[56:57], v[52:53], s[8:9], v[54:55] op_sel:[0,1,0] op_sel_hi:[1,1,1] neg_lo:[0,0,1] neg_hi:[0,0,1]
	v_pk_fma_f32 v[56:57], v[52:53], s[86:87], v[56:57] op_sel:[0,1,0] op_sel_hi:[1,1,1]
	v_pk_add_f32 v[54:55], v[54:55], v[56:57]
	v_pk_add_f32 v[50:51], v[50:51], v[54:55] neg_lo:[0,1] neg_hi:[0,1]
	v_fmamk_f32 v88, v50, 0x3d800000, v87
	v_fmamk_f32 v89, v51, 0x3d800000, v88
	s_waitcnt lgkmcnt(0)
	ds_read_b128 v[34:37], v3 offset:1792
	ds_read_b128 v[38:41], v3 offset:1808
	ds_read_b128 v[42:45], v3 offset:1824
	ds_read_b128 v[46:49], v3 offset:1840
	ds_read_b128 v[200:203], v3 offset:1856
	ds_read_b128 v[204:207], v3 offset:1872
	ds_read_b128 v[208:211], v3 offset:1888
	ds_read_b128 v[212:215], v3 offset:1904
	global_load_ushort v188, v1, s[20:21]
	global_load_ushort v189, v1, s[20:21] offset:1024
	s_add_u32 s20, s20, 0x1a00
	s_addc_u32 s21, s21, 0
	global_load_ushort v190, v1, s[20:21]
	global_load_ushort v191, v1, s[20:21] offset:1024
	s_add_u32 s20, s20, 0x1a00
	s_addc_u32 s21, s21, 0
	v_pk_fma_f32 v[50:51], v[16:17], v[216:217], v[32:33] op_sel_hi:[0,1,0]
	v_pk_fma_f32 v[50:51], v[16:17], v[218:219], v[50:51] op_sel:[1,0,0] op_sel_hi:[1,1,1]
	v_pk_fma_f32 v[50:51], v[18:19], v[220:221], v[50:51] op_sel_hi:[0,1,1]
	v_pk_fma_f32 v[50:51], v[18:19], v[222:223], v[50:51] op_sel:[1,0,0] op_sel_hi:[1,1,1]
	v_pk_fma_f32 v[50:51], v[20:21], v[224:225], v[50:51] op_sel_hi:[0,1,1]
	v_pk_fma_f32 v[50:51], v[20:21], v[226:227], v[50:51] op_sel:[1,0,0] op_sel_hi:[1,1,1]
	v_pk_fma_f32 v[50:51], v[22:23], v[232:233], v[50:51] op_sel_hi:[0,1,1]
	v_pk_fma_f32 v[50:51], v[22:23], v[234:235], v[50:51] op_sel:[1,0,0] op_sel_hi:[1,1,1]
	v_pk_fma_f32 v[50:51], v[24:25], v[236:237], v[50:51] op_sel_hi:[0,1,1]
	v_pk_fma_f32 v[50:51], v[24:25], v[238:239], v[50:51] op_sel:[1,0,0] op_sel_hi:[1,1,1]
	v_pk_fma_f32 v[50:51], v[26:27], v[240:241], v[50:51] op_sel_hi:[0,1,1]
	v_pk_fma_f32 v[50:51], v[26:27], v[242:243], v[50:51] op_sel:[1,0,0] op_sel_hi:[1,1,1]
	v_pk_fma_f32 v[50:51], v[28:29], v[244:245], v[50:51] op_sel_hi:[0,1,1]
	v_pk_fma_f32 v[50:51], v[28:29], v[246:247], v[50:51] op_sel:[1,0,0] op_sel_hi:[1,1,1]
	v_pk_fma_f32 v[50:51], v[30:31], v[248:249], v[50:51] op_sel_hi:[0,1,1]
	v_pk_fma_f32 v[50:51], v[30:31], v[250:251], v[50:51] op_sel:[1,0,0] op_sel_hi:[1,1,1]
	v_mul_f32_e64 v52, |v50|, s7
	v_mul_f32_e64 v53, |v51|, s7
	v_exp_f32_e32 v52, v52
	v_exp_f32_e32 v53, v53
	v_min_f32_e32 v50, 0, v50
	v_min_f32_e32 v51, 0, v51
	v_pk_add_f32 v[52:53], v[52:53], 1.0 op_sel_hi:[1,0]
	v_log_f32_e32 v52, v52
	v_log_f32_e32 v53, v53
	s_nop 0
	v_pk_mul_f32 v[54:55], v[52:53], s[8:9] op_sel:[0,1] op_sel_hi:[1,1]
	v_pk_fma_f32 v[56:57], v[52:53], s[8:9], v[54:55] op_sel:[0,1,0] op_sel_hi:[1,1,1] neg_lo:[0,0,1] neg_hi:[0,0,1]
	v_pk_fma_f32 v[56:57], v[52:53], s[86:87], v[56:57] op_sel:[0,1,0] op_sel_hi:[1,1,1]
	v_pk_add_f32 v[54:55], v[54:55], v[56:57]
	v_pk_add_f32 v[50:51], v[50:51], v[54:55] neg_lo:[0,1] neg_hi:[0,1]
	v_fmamk_f32 v90, v50, 0x3d800000, v89
	v_fmamk_f32 v91, v51, 0x3d800000, v90
	s_waitcnt lgkmcnt(0)
	ds_read_b128 v[216:219], v3 offset:1920
	ds_read_b128 v[220:223], v3 offset:1936
	ds_read_b128 v[224:227], v3 offset:1952
	ds_read_b128 v[232:235], v3 offset:1968
	ds_read_b128 v[236:239], v3 offset:1984
	ds_read_b128 v[240:243], v3 offset:2000
	ds_read_b128 v[244:247], v3 offset:2016
	ds_read_b128 v[248:251], v3 offset:2032
	s_waitcnt vmcnt(56)
	global_load_ushort v192, v1, s[20:21]
	global_load_ushort v193, v1, s[20:21] offset:1024
	s_add_u32 s20, s20, 0x1a00
	s_addc_u32 s21, s21, 0
	global_load_ushort v194, v1, s[20:21]
	global_load_ushort v195, v1, s[20:21] offset:1024
	s_add_u32 s20, s20, 0x1a00
	s_addc_u32 s21, s21, 0
	v_pk_fma_f32 v[50:51], v[16:17], v[34:35], v[32:33] op_sel_hi:[0,1,0]
	v_pk_fma_f32 v[50:51], v[16:17], v[36:37], v[50:51] op_sel:[1,0,0] op_sel_hi:[1,1,1]
	v_pk_fma_f32 v[50:51], v[18:19], v[38:39], v[50:51] op_sel_hi:[0,1,1]
	v_pk_fma_f32 v[50:51], v[18:19], v[40:41], v[50:51] op_sel:[1,0,0] op_sel_hi:[1,1,1]
	v_pk_fma_f32 v[50:51], v[20:21], v[42:43], v[50:51] op_sel_hi:[0,1,1]
	v_pk_fma_f32 v[50:51], v[20:21], v[44:45], v[50:51] op_sel:[1,0,0] op_sel_hi:[1,1,1]
	v_pk_fma_f32 v[50:51], v[22:23], v[46:47], v[50:51] op_sel_hi:[0,1,1]
	v_pk_fma_f32 v[50:51], v[22:23], v[48:49], v[50:51] op_sel:[1,0,0] op_sel_hi:[1,1,1]
	v_pk_fma_f32 v[50:51], v[24:25], v[200:201], v[50:51] op_sel_hi:[0,1,1]
	v_pk_fma_f32 v[50:51], v[24:25], v[202:203], v[50:51] op_sel:[1,0,0] op_sel_hi:[1,1,1]
	v_pk_fma_f32 v[50:51], v[26:27], v[204:205], v[50:51] op_sel_hi:[0,1,1]
	v_pk_fma_f32 v[50:51], v[26:27], v[206:207], v[50:51] op_sel:[1,0,0] op_sel_hi:[1,1,1]
	v_pk_fma_f32 v[50:51], v[28:29], v[208:209], v[50:51] op_sel_hi:[0,1,1]
	v_pk_fma_f32 v[50:51], v[28:29], v[210:211], v[50:51] op_sel:[1,0,0] op_sel_hi:[1,1,1]
	v_pk_fma_f32 v[50:51], v[30:31], v[212:213], v[50:51] op_sel_hi:[0,1,1]
	v_pk_fma_f32 v[50:51], v[30:31], v[214:215], v[50:51] op_sel:[1,0,0] op_sel_hi:[1,1,1]
	v_mul_f32_e64 v52, |v50|, s7
	v_mul_f32_e64 v53, |v51|, s7
	v_exp_f32_e32 v52, v52
	v_exp_f32_e32 v53, v53
	v_min_f32_e32 v50, 0, v50
	v_min_f32_e32 v51, 0, v51
	v_pk_add_f32 v[52:53], v[52:53], 1.0 op_sel_hi:[1,0]
	v_log_f32_e32 v52, v52
	v_log_f32_e32 v53, v53
	s_nop 0
	v_pk_mul_f32 v[54:55], v[52:53], s[8:9] op_sel:[0,1] op_sel_hi:[1,1]
	v_pk_fma_f32 v[56:57], v[52:53], s[8:9], v[54:55] op_sel:[0,1,0] op_sel_hi:[1,1,1] neg_lo:[0,0,1] neg_hi:[0,0,1]
	v_pk_fma_f32 v[56:57], v[52:53], s[86:87], v[56:57] op_sel:[0,1,0] op_sel_hi:[1,1,1]
	v_pk_add_f32 v[54:55], v[54:55], v[56:57]
	v_pk_add_f32 v[50:51], v[50:51], v[54:55] neg_lo:[0,1] neg_hi:[0,1]
	v_fmamk_f32 v92, v50, 0x3d800000, v91
	v_fmamk_f32 v93, v51, 0x3d800000, v92
	s_waitcnt lgkmcnt(0)
	ds_read_b128 v[34:37], v3 offset:2048
	ds_read_b128 v[38:41], v3 offset:2064
	ds_read_b128 v[42:45], v3 offset:2080
	ds_read_b128 v[46:49], v3 offset:2096
	ds_read_b128 v[200:203], v3 offset:2112
	ds_read_b128 v[204:207], v3 offset:2128
	ds_read_b128 v[208:211], v3 offset:2144
	ds_read_b128 v[212:215], v3 offset:2160
	s_waitcnt vmcnt(56)
	global_load_ushort v196, v1, s[20:21]
	global_load_ushort v197, v1, s[20:21] offset:1024
	s_add_u32 s20, s20, 0x1a00
	s_addc_u32 s21, s21, 0
	global_load_ushort v198, v1, s[20:21]
	global_load_ushort v199, v1, s[20:21] offset:1024
	s_add_u32 s20, s20, 0x1a00
	s_addc_u32 s21, s21, 0
	v_pk_fma_f32 v[50:51], v[16:17], v[216:217], v[32:33] op_sel_hi:[0,1,0]
	v_pk_fma_f32 v[50:51], v[16:17], v[218:219], v[50:51] op_sel:[1,0,0] op_sel_hi:[1,1,1]
	v_pk_fma_f32 v[50:51], v[18:19], v[220:221], v[50:51] op_sel_hi:[0,1,1]
	v_pk_fma_f32 v[50:51], v[18:19], v[222:223], v[50:51] op_sel:[1,0,0] op_sel_hi:[1,1,1]
	v_pk_fma_f32 v[50:51], v[20:21], v[224:225], v[50:51] op_sel_hi:[0,1,1]
	v_pk_fma_f32 v[50:51], v[20:21], v[226:227], v[50:51] op_sel:[1,0,0] op_sel_hi:[1,1,1]
	v_pk_fma_f32 v[50:51], v[22:23], v[232:233], v[50:51] op_sel_hi:[0,1,1]
	v_pk_fma_f32 v[50:51], v[22:23], v[234:235], v[50:51] op_sel:[1,0,0] op_sel_hi:[1,1,1]
	v_pk_fma_f32 v[50:51], v[24:25], v[236:237], v[50:51] op_sel_hi:[0,1,1]
	v_pk_fma_f32 v[50:51], v[24:25], v[238:239], v[50:51] op_sel:[1,0,0] op_sel_hi:[1,1,1]
	v_pk_fma_f32 v[50:51], v[26:27], v[240:241], v[50:51] op_sel_hi:[0,1,1]
	v_pk_fma_f32 v[50:51], v[26:27], v[242:243], v[50:51] op_sel:[1,0,0] op_sel_hi:[1,1,1]
	v_pk_fma_f32 v[50:51], v[28:29], v[244:245], v[50:51] op_sel_hi:[0,1,1]
	v_pk_fma_f32 v[50:51], v[28:29], v[246:247], v[50:51] op_sel:[1,0,0] op_sel_hi:[1,1,1]
	v_pk_fma_f32 v[50:51], v[30:31], v[248:249], v[50:51] op_sel_hi:[0,1,1]
	v_pk_fma_f32 v[50:51], v[30:31], v[250:251], v[50:51] op_sel:[1,0,0] op_sel_hi:[1,1,1]
	v_mul_f32_e64 v52, |v50|, s7
	v_mul_f32_e64 v53, |v51|, s7
	v_exp_f32_e32 v52, v52
	v_exp_f32_e32 v53, v53
	v_min_f32_e32 v50, 0, v50
	v_min_f32_e32 v51, 0, v51
	v_pk_add_f32 v[52:53], v[52:53], 1.0 op_sel_hi:[1,0]
	v_log_f32_e32 v52, v52
	v_log_f32_e32 v53, v53
	s_nop 0
	v_pk_mul_f32 v[54:55], v[52:53], s[8:9] op_sel:[0,1] op_sel_hi:[1,1]
	v_pk_fma_f32 v[56:57], v[52:53], s[8:9], v[54:55] op_sel:[0,1,0] op_sel_hi:[1,1,1] neg_lo:[0,0,1] neg_hi:[0,0,1]
	v_pk_fma_f32 v[56:57], v[52:53], s[86:87], v[56:57] op_sel:[0,1,0] op_sel_hi:[1,1,1]
	v_pk_add_f32 v[54:55], v[54:55], v[56:57]
	v_pk_add_f32 v[50:51], v[50:51], v[54:55] neg_lo:[0,1] neg_hi:[0,1]
	v_fmamk_f32 v94, v50, 0x3d800000, v93
	v_fmamk_f32 v95, v51, 0x3d800000, v94
	s_waitcnt lgkmcnt(0)
	ds_read_b128 v[216:219], v3 offset:2176
	ds_read_b128 v[220:223], v3 offset:2192
	ds_read_b128 v[224:227], v3 offset:2208
	ds_read_b128 v[232:235], v3 offset:2224
	ds_read_b128 v[236:239], v3 offset:2240
	ds_read_b128 v[240:243], v3 offset:2256
	ds_read_b128 v[244:247], v3 offset:2272
	ds_read_b128 v[248:251], v3 offset:2288
	v_pk_fma_f32 v[50:51], v[16:17], v[34:35], v[32:33] op_sel_hi:[0,1,0]
	v_pk_fma_f32 v[50:51], v[16:17], v[36:37], v[50:51] op_sel:[1,0,0] op_sel_hi:[1,1,1]
	v_pk_fma_f32 v[50:51], v[18:19], v[38:39], v[50:51] op_sel_hi:[0,1,1]
	v_pk_fma_f32 v[50:51], v[18:19], v[40:41], v[50:51] op_sel:[1,0,0] op_sel_hi:[1,1,1]
	v_pk_fma_f32 v[50:51], v[20:21], v[42:43], v[50:51] op_sel_hi:[0,1,1]
	v_pk_fma_f32 v[50:51], v[20:21], v[44:45], v[50:51] op_sel:[1,0,0] op_sel_hi:[1,1,1]
	v_pk_fma_f32 v[50:51], v[22:23], v[46:47], v[50:51] op_sel_hi:[0,1,1]
	v_pk_fma_f32 v[50:51], v[22:23], v[48:49], v[50:51] op_sel:[1,0,0] op_sel_hi:[1,1,1]
	v_pk_fma_f32 v[50:51], v[24:25], v[200:201], v[50:51] op_sel_hi:[0,1,1]
	v_pk_fma_f32 v[50:51], v[24:25], v[202:203], v[50:51] op_sel:[1,0,0] op_sel_hi:[1,1,1]
	v_pk_fma_f32 v[50:51], v[26:27], v[204:205], v[50:51] op_sel_hi:[0,1,1]
	v_pk_fma_f32 v[50:51], v[26:27], v[206:207], v[50:51] op_sel:[1,0,0] op_sel_hi:[1,1,1]
	v_pk_fma_f32 v[50:51], v[28:29], v[208:209], v[50:51] op_sel_hi:[0,1,1]
	v_pk_fma_f32 v[50:51], v[28:29], v[210:211], v[50:51] op_sel:[1,0,0] op_sel_hi:[1,1,1]
	v_pk_fma_f32 v[50:51], v[30:31], v[212:213], v[50:51] op_sel_hi:[0,1,1]
	v_pk_fma_f32 v[50:51], v[30:31], v[214:215], v[50:51] op_sel:[1,0,0] op_sel_hi:[1,1,1]
	v_mul_f32_e64 v52, |v50|, s7
	v_mul_f32_e64 v53, |v51|, s7
	v_exp_f32_e32 v52, v52
	v_exp_f32_e32 v53, v53
	v_min_f32_e32 v50, 0, v50
	v_min_f32_e32 v51, 0, v51
	v_pk_add_f32 v[52:53], v[52:53], 1.0 op_sel_hi:[1,0]
	v_log_f32_e32 v52, v52
	v_log_f32_e32 v53, v53
	s_nop 0
	v_pk_mul_f32 v[54:55], v[52:53], s[8:9] op_sel:[0,1] op_sel_hi:[1,1]
	v_pk_fma_f32 v[56:57], v[52:53], s[8:9], v[54:55] op_sel:[0,1,0] op_sel_hi:[1,1,1] neg_lo:[0,0,1] neg_hi:[0,0,1]
	v_pk_fma_f32 v[56:57], v[52:53], s[86:87], v[56:57] op_sel:[0,1,0] op_sel_hi:[1,1,1]
	v_pk_add_f32 v[54:55], v[54:55], v[56:57]
	v_pk_add_f32 v[50:51], v[50:51], v[54:55] neg_lo:[0,1] neg_hi:[0,1]
	v_fmamk_f32 v96, v50, 0x3d800000, v95
	v_fmamk_f32 v97, v51, 0x3d800000, v96
	s_waitcnt vmcnt(0)
	v_sub_f32_e32 v52, v64, v96
	v_lshlrev_b32_e32 v50, 16, v136
	v_mul_f32_e32 v52, 0x3fb8aa3b, v52
	v_lshlrev_b32_e32 v51, 16, v137
	v_exp_f32_e32 v53, v52
	v_exp_f32_e64 v54, -v52
	v_mul_f32_e32 v50, 0x3db504f3, v50
	s_nop 0
	v_mul_f32_e32 v50, v53, v50
	v_mul_f32_e32 v8, v54, v51
	v_cvt_pk_bf16_f32 v50, v50, v8
	global_store_short v1, v50, s[22:23]
	global_store_short_d16_hi v1, v50, s[22:23] offset:1024
	s_add_u32 s22, s22, 0x1a00
	s_addc_u32 s23, s23, 0
	global_load_ushort v136, v1, s[20:21]
	global_load_ushort v137, v1, s[20:21] offset:1024
	s_add_u32 s20, s20, 0x1a00
	s_addc_u32 s21, s21, 0
	v_sub_f32_e32 v52, v65, v96
	v_lshlrev_b32_e32 v50, 16, v138
	v_mul_f32_e32 v52, 0x3fb8aa3b, v52
	v_lshlrev_b32_e32 v51, 16, v139
	v_exp_f32_e32 v53, v52
	v_exp_f32_e64 v54, -v52
	v_mul_f32_e32 v50, 0x3db504f3, v50
	s_nop 0
	v_mul_f32_e32 v50, v53, v50
	v_mul_f32_e32 v9, v54, v51
	v_cvt_pk_bf16_f32 v50, v50, v9
	global_store_short v1, v50, s[22:23]
	global_store_short_d16_hi v1, v50, s[22:23] offset:1024
	s_add_u32 s22, s22, 0x1a00
	s_addc_u32 s23, s23, 0
	global_load_ushort v138, v1, s[20:21]
	global_load_ushort v139, v1, s[20:21] offset:1024
	s_add_u32 s20, s20, 0x1a00
	s_addc_u32 s21, s21, 0
	v_sub_f32_e32 v52, v66, v96
	v_lshlrev_b32_e32 v50, 16, v140
	v_mul_f32_e32 v52, 0x3fb8aa3b, v52
	v_lshlrev_b32_e32 v51, 16, v141
	v_exp_f32_e32 v53, v52
	v_exp_f32_e64 v54, -v52
	v_mul_f32_e32 v50, 0x3db504f3, v50
	s_nop 0
	v_mul_f32_e32 v50, v53, v50
	v_mul_f32_e32 v10, v54, v51
	v_cvt_pk_bf16_f32 v50, v50, v10
	global_store_short v1, v50, s[22:23]
	global_store_short_d16_hi v1, v50, s[22:23] offset:1024
	s_add_u32 s22, s22, 0x1a00
	s_addc_u32 s23, s23, 0
	global_load_ushort v140, v1, s[20:21]
	global_load_ushort v141, v1, s[20:21] offset:1024
	s_add_u32 s20, s20, 0x1a00
	s_addc_u32 s21, s21, 0
	v_sub_f32_e32 v52, v67, v96
	v_lshlrev_b32_e32 v50, 16, v142
	v_mul_f32_e32 v52, 0x3fb8aa3b, v52
	v_lshlrev_b32_e32 v51, 16, v143
	v_exp_f32_e32 v53, v52
	v_exp_f32_e64 v54, -v52
	v_mul_f32_e32 v50, 0x3db504f3, v50
	s_nop 0
	v_mul_f32_e32 v50, v53, v50
	v_mul_f32_e32 v11, v54, v51
	v_cvt_pk_bf16_f32 v50, v50, v11
	global_store_short v1, v50, s[22:23]
	global_store_short_d16_hi v1, v50, s[22:23] offset:1024
	s_add_u32 s22, s22, 0x1a00
	s_addc_u32 s23, s23, 0
	global_load_ushort v142, v1, s[20:21]
	global_load_ushort v143, v1, s[20:21] offset:1024
	s_add_u32 s20, s20, 0x1a00
	s_addc_u32 s21, s21, 0
	v_sub_f32_e32 v52, v68, v96
	v_lshlrev_b32_e32 v50, 16, v144
	v_mul_f32_e32 v52, 0x3fb8aa3b, v52
	v_lshlrev_b32_e32 v51, 16, v145
	v_exp_f32_e32 v53, v52
	v_exp_f32_e64 v54, -v52
	v_mul_f32_e32 v50, 0x3db504f3, v50
	s_nop 0
	v_mul_f32_e32 v50, v53, v50
	v_mul_f32_e32 v12, v54, v51
	v_cvt_pk_bf16_f32 v50, v50, v12
	global_store_short v1, v50, s[22:23]
	global_store_short_d16_hi v1, v50, s[22:23] offset:1024
	s_add_u32 s22, s22, 0x1a00
	s_addc_u32 s23, s23, 0
	global_load_ushort v144, v1, s[20:21]
	global_load_ushort v145, v1, s[20:21] offset:1024
	s_add_u32 s20, s20, 0x1a00
	s_addc_u32 s21, s21, 0
	v_sub_f32_e32 v52, v69, v96
	v_lshlrev_b32_e32 v50, 16, v146
	v_mul_f32_e32 v52, 0x3fb8aa3b, v52
	v_lshlrev_b32_e32 v51, 16, v147
	v_exp_f32_e32 v53, v52
	v_exp_f32_e64 v54, -v52
	v_mul_f32_e32 v50, 0x3db504f3, v50
	s_nop 0
	v_mul_f32_e32 v50, v53, v50
	v_mul_f32_e32 v13, v54, v51
	v_cvt_pk_bf16_f32 v50, v50, v13
	global_store_short v1, v50, s[22:23]
	global_store_short_d16_hi v1, v50, s[22:23] offset:1024
	s_add_u32 s22, s22, 0x1a00
	s_addc_u32 s23, s23, 0
	global_load_ushort v146, v1, s[20:21]
	global_load_ushort v147, v1, s[20:21] offset:1024
	s_add_u32 s20, s20, 0x1a00
	s_addc_u32 s21, s21, 0
	v_sub_f32_e32 v52, v70, v96
	v_lshlrev_b32_e32 v50, 16, v148
	v_mul_f32_e32 v52, 0x3fb8aa3b, v52
	v_lshlrev_b32_e32 v51, 16, v149
	v_exp_f32_e32 v53, v52
	v_exp_f32_e64 v54, -v52
	v_mul_f32_e32 v50, 0x3db504f3, v50
	s_nop 0
	v_mul_f32_e32 v50, v53, v50
	v_mul_f32_e32 v14, v54, v51
	v_cvt_pk_bf16_f32 v50, v50, v14
	global_store_short v1, v50, s[22:23]
	global_store_short_d16_hi v1, v50, s[22:23] offset:1024
	s_add_u32 s22, s22, 0x1a00
	s_addc_u32 s23, s23, 0
	global_load_ushort v148, v1, s[20:21]
	global_load_ushort v149, v1, s[20:21] offset:1024
	s_add_u32 s20, s20, 0x1a00
	s_addc_u32 s21, s21, 0
	v_sub_f32_e32 v52, v71, v96
	v_lshlrev_b32_e32 v50, 16, v150
	v_mul_f32_e32 v52, 0x3fb8aa3b, v52
	v_lshlrev_b32_e32 v51, 16, v151
	v_exp_f32_e32 v53, v52
	v_exp_f32_e64 v54, -v52
	v_mul_f32_e32 v50, 0x3db504f3, v50
	s_nop 0
	v_mul_f32_e32 v50, v53, v50
	v_mul_f32_e32 v15, v54, v51
	v_cvt_pk_bf16_f32 v50, v50, v15
	global_store_short v1, v50, s[22:23]
	global_store_short_d16_hi v1, v50, s[22:23] offset:1024
	s_add_u32 s22, s22, 0x1a00
	s_addc_u32 s23, s23, 0
	v_cvt_pk_bf16_f32 v4, v8, v9
	v_cvt_pk_bf16_f32 v5, v10, v11
	v_cvt_pk_bf16_f32 v6, v12, v13
	v_cvt_pk_bf16_f32 v7, v14, v15
	global_store_dwordx4 v2, v[4:7], s[26:27] offset:0
	global_load_ushort v150, v1, s[20:21]
	global_load_ushort v151, v1, s[20:21] offset:1024
	s_add_u32 s20, s20, 0x1a00
	s_addc_u32 s21, s21, 0
	v_sub_f32_e32 v52, v72, v96
	v_lshlrev_b32_e32 v50, 16, v152
	v_mul_f32_e32 v52, 0x3fb8aa3b, v52
	v_lshlrev_b32_e32 v51, 16, v153
	v_exp_f32_e32 v53, v52
	v_exp_f32_e64 v54, -v52
	v_mul_f32_e32 v50, 0x3db504f3, v50
	s_nop 0
	v_mul_f32_e32 v50, v53, v50
	v_mul_f32_e32 v8, v54, v51
	v_cvt_pk_bf16_f32 v50, v50, v8
	global_store_short v1, v50, s[22:23]
	global_store_short_d16_hi v1, v50, s[22:23] offset:1024
	s_add_u32 s22, s22, 0x1a00
	s_addc_u32 s23, s23, 0
	global_load_ushort v152, v1, s[20:21]
	global_load_ushort v153, v1, s[20:21] offset:1024
	s_add_u32 s20, s20, 0x1a00
	s_addc_u32 s21, s21, 0
	v_sub_f32_e32 v52, v73, v96
	v_lshlrev_b32_e32 v50, 16, v154
	v_mul_f32_e32 v52, 0x3fb8aa3b, v52
	v_lshlrev_b32_e32 v51, 16, v155
	v_exp_f32_e32 v53, v52
	v_exp_f32_e64 v54, -v52
	v_mul_f32_e32 v50, 0x3db504f3, v50
	s_nop 0
	v_mul_f32_e32 v50, v53, v50
	v_mul_f32_e32 v9, v54, v51
	v_cvt_pk_bf16_f32 v50, v50, v9
	global_store_short v1, v50, s[22:23]
	global_store_short_d16_hi v1, v50, s[22:23] offset:1024
	s_add_u32 s22, s22, 0x1a00
	s_addc_u32 s23, s23, 0
	global_load_ushort v154, v1, s[20:21]
	global_load_ushort v155, v1, s[20:21] offset:1024
	s_add_u32 s20, s20, 0x1a00
	s_addc_u32 s21, s21, 0
	v_sub_f32_e32 v52, v74, v96
	v_lshlrev_b32_e32 v50, 16, v156
	v_mul_f32_e32 v52, 0x3fb8aa3b, v52
	v_lshlrev_b32_e32 v51, 16, v157
	v_exp_f32_e32 v53, v52
	v_exp_f32_e64 v54, -v52
	v_mul_f32_e32 v50, 0x3db504f3, v50
	s_nop 0
	v_mul_f32_e32 v50, v53, v50
	v_mul_f32_e32 v10, v54, v51
	v_cvt_pk_bf16_f32 v50, v50, v10
	global_store_short v1, v50, s[22:23]
	global_store_short_d16_hi v1, v50, s[22:23] offset:1024
	s_add_u32 s22, s22, 0x1a00
	s_addc_u32 s23, s23, 0
	global_load_ushort v156, v1, s[20:21]
	global_load_ushort v157, v1, s[20:21] offset:1024
	s_add_u32 s20, s20, 0x1a00
	s_addc_u32 s21, s21, 0
	v_sub_f32_e32 v52, v75, v96
	v_lshlrev_b32_e32 v50, 16, v158
	v_mul_f32_e32 v52, 0x3fb8aa3b, v52
	v_lshlrev_b32_e32 v51, 16, v159
	v_exp_f32_e32 v53, v52
	v_exp_f32_e64 v54, -v52
	v_mul_f32_e32 v50, 0x3db504f3, v50
	s_nop 0
	v_mul_f32_e32 v50, v53, v50
	v_mul_f32_e32 v11, v54, v51
	v_cvt_pk_bf16_f32 v50, v50, v11
	global_store_short v1, v50, s[22:23]
	global_store_short_d16_hi v1, v50, s[22:23] offset:1024
	s_add_u32 s22, s22, 0x1a00
	s_addc_u32 s23, s23, 0
	global_load_ushort v158, v1, s[20:21]
	global_load_ushort v159, v1, s[20:21] offset:1024
	s_add_u32 s20, s20, 0x1a00
	s_addc_u32 s21, s21, 0
	s_waitcnt vmcnt(52)
	v_sub_f32_e32 v52, v76, v96
	v_lshlrev_b32_e32 v50, 16, v160
	v_mul_f32_e32 v52, 0x3fb8aa3b, v52
	v_lshlrev_b32_e32 v51, 16, v161
	v_exp_f32_e32 v53, v52
	v_exp_f32_e64 v54, -v52
	v_mul_f32_e32 v50, 0x3db504f3, v50
	s_nop 0
	v_mul_f32_e32 v50, v53, v50
	v_mul_f32_e32 v12, v54, v51
	v_cvt_pk_bf16_f32 v50, v50, v12
	global_store_short v1, v50, s[22:23]
	global_store_short_d16_hi v1, v50, s[22:23] offset:1024
	s_add_u32 s22, s22, 0x1a00
	s_addc_u32 s23, s23, 0
	global_load_ushort v160, v1, s[20:21]
	global_load_ushort v161, v1, s[20:21] offset:1024
	s_add_u32 s20, s20, 0x1a00
	s_addc_u32 s21, s21, 0
	s_waitcnt vmcnt(52)
	v_sub_f32_e32 v52, v77, v96
	v_lshlrev_b32_e32 v50, 16, v162
	v_mul_f32_e32 v52, 0x3fb8aa3b, v52
	v_lshlrev_b32_e32 v51, 16, v163
	v_exp_f32_e32 v53, v52
	v_exp_f32_e64 v54, -v52
	v_mul_f32_e32 v50, 0x3db504f3, v50
	s_nop 0
	v_mul_f32_e32 v50, v53, v50
	v_mul_f32_e32 v13, v54, v51
	v_cvt_pk_bf16_f32 v50, v50, v13
	global_store_short v1, v50, s[22:23]
	global_store_short_d16_hi v1, v50, s[22:23] offset:1024
	s_add_u32 s22, s22, 0x1a00
	s_addc_u32 s23, s23, 0
	global_load_ushort v162, v1, s[20:21]
	global_load_ushort v163, v1, s[20:21] offset:1024
	s_add_u32 s20, s20, 0x1a00
	s_addc_u32 s21, s21, 0
	s_waitcnt vmcnt(52)
	v_sub_f32_e32 v52, v78, v96
	v_lshlrev_b32_e32 v50, 16, v164
	v_mul_f32_e32 v52, 0x3fb8aa3b, v52
	v_lshlrev_b32_e32 v51, 16, v165
	v_exp_f32_e32 v53, v52
	v_exp_f32_e64 v54, -v52
	v_mul_f32_e32 v50, 0x3db504f3, v50
	s_nop 0
	v_mul_f32_e32 v50, v53, v50
	v_mul_f32_e32 v14, v54, v51
	v_cvt_pk_bf16_f32 v50, v50, v14
	global_store_short v1, v50, s[22:23]
	global_store_short_d16_hi v1, v50, s[22:23] offset:1024
	s_add_u32 s22, s22, 0x1a00
	s_addc_u32 s23, s23, 0
	global_load_ushort v164, v1, s[20:21]
	global_load_ushort v165, v1, s[20:21] offset:1024
	s_add_u32 s20, s20, 0x1a00
	s_addc_u32 s21, s21, 0
	s_waitcnt vmcnt(52)
	v_sub_f32_e32 v52, v79, v96
	v_lshlrev_b32_e32 v50, 16, v166
	v_mul_f32_e32 v52, 0x3fb8aa3b, v52
	v_lshlrev_b32_e32 v51, 16, v167
	v_exp_f32_e32 v53, v52
	v_exp_f32_e64 v54, -v52
	v_mul_f32_e32 v50, 0x3db504f3, v50
	s_nop 0
	v_mul_f32_e32 v50, v53, v50
	v_mul_f32_e32 v15, v54, v51
	v_cvt_pk_bf16_f32 v50, v50, v15
	global_store_short v1, v50, s[22:23]
	global_store_short_d16_hi v1, v50, s[22:23] offset:1024
	s_add_u32 s22, s22, 0x1a00
	s_addc_u32 s23, s23, 0
	v_cvt_pk_bf16_f32 v4, v8, v9
	v_cvt_pk_bf16_f32 v5, v10, v11
	v_cvt_pk_bf16_f32 v6, v12, v13
	v_cvt_pk_bf16_f32 v7, v14, v15
	global_store_dwordx4 v2, v[4:7], s[26:27] offset:16
	global_load_ushort v166, v1, s[20:21]
	global_load_ushort v167, v1, s[20:21] offset:1024
	s_add_u32 s20, s20, 0x1a00
	s_addc_u32 s21, s21, 0
	s_waitcnt vmcnt(52)
	v_sub_f32_e32 v52, v80, v96
	v_lshlrev_b32_e32 v50, 16, v168
	v_mul_f32_e32 v52, 0x3fb8aa3b, v52
	v_lshlrev_b32_e32 v51, 16, v169
	v_exp_f32_e32 v53, v52
	v_exp_f32_e64 v54, -v52
	v_mul_f32_e32 v50, 0x3db504f3, v50
	s_nop 0
	v_mul_f32_e32 v50, v53, v50
	v_mul_f32_e32 v8, v54, v51
	v_cvt_pk_bf16_f32 v50, v50, v8
	global_store_short v1, v50, s[22:23]
	global_store_short_d16_hi v1, v50, s[22:23] offset:1024
	s_add_u32 s22, s22, 0x1a00
	s_addc_u32 s23, s23, 0
	global_load_ushort v168, v1, s[20:21]
	global_load_ushort v169, v1, s[20:21] offset:1024
	s_add_u32 s20, s20, 0x1a00
	s_addc_u32 s21, s21, 0
	s_waitcnt vmcnt(52)
	v_sub_f32_e32 v52, v81, v96
	v_lshlrev_b32_e32 v50, 16, v170
	v_mul_f32_e32 v52, 0x3fb8aa3b, v52
	v_lshlrev_b32_e32 v51, 16, v171
	v_exp_f32_e32 v53, v52
	v_exp_f32_e64 v54, -v52
	v_mul_f32_e32 v50, 0x3db504f3, v50
	s_nop 0
	v_mul_f32_e32 v50, v53, v50
	v_mul_f32_e32 v9, v54, v51
	v_cvt_pk_bf16_f32 v50, v50, v9
	global_store_short v1, v50, s[22:23]
	global_store_short_d16_hi v1, v50, s[22:23] offset:1024
	s_add_u32 s22, s22, 0x1a00
	s_addc_u32 s23, s23, 0
	global_load_ushort v170, v1, s[20:21]
	global_load_ushort v171, v1, s[20:21] offset:1024
	s_add_u32 s20, s20, 0x1a00
	s_addc_u32 s21, s21, 0
	s_waitcnt vmcnt(52)
	v_sub_f32_e32 v52, v82, v96
	v_lshlrev_b32_e32 v50, 16, v172
	v_mul_f32_e32 v52, 0x3fb8aa3b, v52
	v_lshlrev_b32_e32 v51, 16, v173
	v_exp_f32_e32 v53, v52
	v_exp_f32_e64 v54, -v52
	v_mul_f32_e32 v50, 0x3db504f3, v50
	s_nop 0
	v_mul_f32_e32 v50, v53, v50
	v_mul_f32_e32 v10, v54, v51
	v_cvt_pk_bf16_f32 v50, v50, v10
	global_store_short v1, v50, s[22:23]
	global_store_short_d16_hi v1, v50, s[22:23] offset:1024
	s_add_u32 s22, s22, 0x1a00
	s_addc_u32 s23, s23, 0
	global_load_ushort v172, v1, s[20:21]
	global_load_ushort v173, v1, s[20:21] offset:1024
	s_add_u32 s20, s20, 0x1a00
	s_addc_u32 s21, s21, 0
	s_waitcnt vmcnt(52)
	v_sub_f32_e32 v52, v83, v96
	v_lshlrev_b32_e32 v50, 16, v174
	v_mul_f32_e32 v52, 0x3fb8aa3b, v52
	v_lshlrev_b32_e32 v51, 16, v175
	v_exp_f32_e32 v53, v52
	v_exp_f32_e64 v54, -v52
	v_mul_f32_e32 v50, 0x3db504f3, v50
	s_nop 0
	v_mul_f32_e32 v50, v53, v50
	v_mul_f32_e32 v11, v54, v51
	v_cvt_pk_bf16_f32 v50, v50, v11
	global_store_short v1, v50, s[22:23]
	global_store_short_d16_hi v1, v50, s[22:23] offset:1024
	s_add_u32 s22, s22, 0x1a00
	s_addc_u32 s23, s23, 0
	global_load_ushort v174, v1, s[20:21]
	global_load_ushort v175, v1, s[20:21] offset:1024
	s_add_u32 s20, s20, 0x1a00
	s_addc_u32 s21, s21, 0
	s_waitcnt vmcnt(52)
	v_sub_f32_e32 v52, v84, v96
	v_lshlrev_b32_e32 v50, 16, v176
	v_mul_f32_e32 v52, 0x3fb8aa3b, v52
	v_lshlrev_b32_e32 v51, 16, v177
	v_exp_f32_e32 v53, v52
	v_exp_f32_e64 v54, -v52
	v_mul_f32_e32 v50, 0x3db504f3, v50
	s_nop 0
	v_mul_f32_e32 v50, v53, v50
	v_mul_f32_e32 v12, v54, v51
	v_cvt_pk_bf16_f32 v50, v50, v12
	global_store_short v1, v50, s[22:23]
	global_store_short_d16_hi v1, v50, s[22:23] offset:1024
	s_add_u32 s22, s22, 0x1a00
	s_addc_u32 s23, s23, 0
	global_load_ushort v176, v1, s[20:21]
	global_load_ushort v177, v1, s[20:21] offset:1024
	s_add_u32 s20, s20, 0x1a00
	s_addc_u32 s21, s21, 0
	s_waitcnt vmcnt(52)
	v_sub_f32_e32 v52, v85, v96
	v_lshlrev_b32_e32 v50, 16, v178
	v_mul_f32_e32 v52, 0x3fb8aa3b, v52
	v_lshlrev_b32_e32 v51, 16, v179
	v_exp_f32_e32 v53, v52
	v_exp_f32_e64 v54, -v52
	v_mul_f32_e32 v50, 0x3db504f3, v50
	s_nop 0
	v_mul_f32_e32 v50, v53, v50
	v_mul_f32_e32 v13, v54, v51
	v_cvt_pk_bf16_f32 v50, v50, v13
	global_store_short v1, v50, s[22:23]
	global_store_short_d16_hi v1, v50, s[22:23] offset:1024
	s_add_u32 s22, s22, 0x1a00
	s_addc_u32 s23, s23, 0
	global_load_ushort v178, v1, s[20:21]
	global_load_ushort v179, v1, s[20:21] offset:1024
	s_add_u32 s20, s20, 0x1a00
	s_addc_u32 s21, s21, 0
	s_waitcnt vmcnt(52)
	v_sub_f32_e32 v52, v86, v96
	v_lshlrev_b32_e32 v50, 16, v180
	v_mul_f32_e32 v52, 0x3fb8aa3b, v52
	v_lshlrev_b32_e32 v51, 16, v181
	v_exp_f32_e32 v53, v52
	v_exp_f32_e64 v54, -v52
	v_mul_f32_e32 v50, 0x3db504f3, v50
	s_nop 0
	v_mul_f32_e32 v50, v53, v50
	v_mul_f32_e32 v14, v54, v51
	v_cvt_pk_bf16_f32 v50, v50, v14
	global_store_short v1, v50, s[22:23]
	global_store_short_d16_hi v1, v50, s[22:23] offset:1024
	s_add_u32 s22, s22, 0x1a00
	s_addc_u32 s23, s23, 0
	global_load_ushort v180, v1, s[20:21]
	global_load_ushort v181, v1, s[20:21] offset:1024
	s_add_u32 s20, s20, 0x1a00
	s_addc_u32 s21, s21, 0
	s_waitcnt vmcnt(52)
	v_sub_f32_e32 v52, v87, v96
	v_lshlrev_b32_e32 v50, 16, v182
	v_mul_f32_e32 v52, 0x3fb8aa3b, v52
	v_lshlrev_b32_e32 v51, 16, v183
	v_exp_f32_e32 v53, v52
	v_exp_f32_e64 v54, -v52
	v_mul_f32_e32 v50, 0x3db504f3, v50
	s_nop 0
	v_mul_f32_e32 v50, v53, v50
	v_mul_f32_e32 v15, v54, v51
	v_cvt_pk_bf16_f32 v50, v50, v15
	global_store_short v1, v50, s[22:23]
	global_store_short_d16_hi v1, v50, s[22:23] offset:1024
	s_add_u32 s22, s22, 0x1a00
	s_addc_u32 s23, s23, 0
	v_cvt_pk_bf16_f32 v4, v8, v9
	v_cvt_pk_bf16_f32 v5, v10, v11
	v_cvt_pk_bf16_f32 v6, v12, v13
	v_cvt_pk_bf16_f32 v7, v14, v15
	global_store_dwordx4 v2, v[4:7], s[26:27] offset:32
	global_load_ushort v182, v1, s[20:21]
	global_load_ushort v183, v1, s[20:21] offset:1024
	s_add_u32 s20, s20, 0x1a00
	s_addc_u32 s21, s21, 0
	s_waitcnt vmcnt(52)
	v_sub_f32_e32 v52, v88, v96
	v_lshlrev_b32_e32 v50, 16, v184
	v_mul_f32_e32 v52, 0x3fb8aa3b, v52
	v_lshlrev_b32_e32 v51, 16, v185
	v_exp_f32_e32 v53, v52
	v_exp_f32_e64 v54, -v52
	v_mul_f32_e32 v50, 0x3db504f3, v50
	s_nop 0
	v_mul_f32_e32 v50, v53, v50
	v_mul_f32_e32 v8, v54, v51
	v_cvt_pk_bf16_f32 v50, v50, v8
	global_store_short v1, v50, s[22:23]
	global_store_short_d16_hi v1, v50, s[22:23] offset:1024
	s_add_u32 s22, s22, 0x1a00
	s_addc_u32 s23, s23, 0
	global_load_ushort v184, v1, s[20:21]
	global_load_ushort v185, v1, s[20:21] offset:1024
	s_add_u32 s20, s20, 0x1a00
	s_addc_u32 s21, s21, 0
	s_waitcnt vmcnt(52)
	v_sub_f32_e32 v52, v89, v96
	v_lshlrev_b32_e32 v50, 16, v186
	v_mul_f32_e32 v52, 0x3fb8aa3b, v52
	v_lshlrev_b32_e32 v51, 16, v187
	v_exp_f32_e32 v53, v52
	v_exp_f32_e64 v54, -v52
	v_mul_f32_e32 v50, 0x3db504f3, v50
	s_nop 0
	v_mul_f32_e32 v50, v53, v50
	v_mul_f32_e32 v9, v54, v51
	v_cvt_pk_bf16_f32 v50, v50, v9
	global_store_short v1, v50, s[22:23]
	global_store_short_d16_hi v1, v50, s[22:23] offset:1024
	s_add_u32 s22, s22, 0x1a00
	s_addc_u32 s23, s23, 0
	global_load_ushort v186, v1, s[20:21]
	global_load_ushort v187, v1, s[20:21] offset:1024
	s_add_u32 s20, s20, 0x1a00
	s_addc_u32 s21, s21, 0
	s_waitcnt vmcnt(52)
	v_sub_f32_e32 v52, v90, v96
	v_lshlrev_b32_e32 v50, 16, v188
	v_mul_f32_e32 v52, 0x3fb8aa3b, v52
	v_lshlrev_b32_e32 v51, 16, v189
	v_exp_f32_e32 v53, v52
	v_exp_f32_e64 v54, -v52
	v_mul_f32_e32 v50, 0x3db504f3, v50
	s_nop 0
	v_mul_f32_e32 v50, v53, v50
	v_mul_f32_e32 v10, v54, v51
	v_cvt_pk_bf16_f32 v50, v50, v10
	global_store_short v1, v50, s[22:23]
	global_store_short_d16_hi v1, v50, s[22:23] offset:1024
	s_add_u32 s22, s22, 0x1a00
	s_addc_u32 s23, s23, 0
	global_load_ushort v188, v1, s[20:21]
	global_load_ushort v189, v1, s[20:21] offset:1024
	s_add_u32 s20, s20, 0x1a00
	s_addc_u32 s21, s21, 0
	s_waitcnt vmcnt(52)
	v_sub_f32_e32 v52, v91, v96
	v_lshlrev_b32_e32 v50, 16, v190
	v_mul_f32_e32 v52, 0x3fb8aa3b, v52
	v_lshlrev_b32_e32 v51, 16, v191
	v_exp_f32_e32 v53, v52
	v_exp_f32_e64 v54, -v52
	v_mul_f32_e32 v50, 0x3db504f3, v50
	s_nop 0
	v_mul_f32_e32 v50, v53, v50
	v_mul_f32_e32 v11, v54, v51
	v_cvt_pk_bf16_f32 v50, v50, v11
	global_store_short v1, v50, s[22:23]
	global_store_short_d16_hi v1, v50, s[22:23] offset:1024
	s_add_u32 s22, s22, 0x1a00
	s_addc_u32 s23, s23, 0
	global_load_ushort v190, v1, s[20:21]
	global_load_ushort v191, v1, s[20:21] offset:1024
	s_add_u32 s20, s20, 0x1a00
	s_addc_u32 s21, s21, 0
	s_waitcnt vmcnt(52)
	v_sub_f32_e32 v52, v92, v96
	v_lshlrev_b32_e32 v50, 16, v192
	v_mul_f32_e32 v52, 0x3fb8aa3b, v52
	v_lshlrev_b32_e32 v51, 16, v193
	v_exp_f32_e32 v53, v52
	v_exp_f32_e64 v54, -v52
	v_mul_f32_e32 v50, 0x3db504f3, v50
	s_nop 0
	v_mul_f32_e32 v50, v53, v50
	v_mul_f32_e32 v12, v54, v51
	v_cvt_pk_bf16_f32 v50, v50, v12
	global_store_short v1, v50, s[22:23]
	global_store_short_d16_hi v1, v50, s[22:23] offset:1024
	s_add_u32 s22, s22, 0x1a00
	s_addc_u32 s23, s23, 0
	global_load_ushort v192, v1, s[20:21]
	global_load_ushort v193, v1, s[20:21] offset:1024
	s_add_u32 s20, s20, 0x1a00
	s_addc_u32 s21, s21, 0
	s_waitcnt vmcnt(52)
	v_sub_f32_e32 v52, v93, v96
	v_lshlrev_b32_e32 v50, 16, v194
	v_mul_f32_e32 v52, 0x3fb8aa3b, v52
	v_lshlrev_b32_e32 v51, 16, v195
	v_exp_f32_e32 v53, v52
	v_exp_f32_e64 v54, -v52
	v_mul_f32_e32 v50, 0x3db504f3, v50
	s_nop 0
	v_mul_f32_e32 v50, v53, v50
	v_mul_f32_e32 v13, v54, v51
	v_cvt_pk_bf16_f32 v50, v50, v13
	global_store_short v1, v50, s[22:23]
	global_store_short_d16_hi v1, v50, s[22:23] offset:1024
	s_add_u32 s22, s22, 0x1a00
	s_addc_u32 s23, s23, 0
	global_load_ushort v194, v1, s[20:21]
	global_load_ushort v195, v1, s[20:21] offset:1024
	s_add_u32 s20, s20, 0x1a00
	s_addc_u32 s21, s21, 0
	s_waitcnt vmcnt(52)
	v_sub_f32_e32 v52, v94, v96
	v_lshlrev_b32_e32 v50, 16, v196
	v_mul_f32_e32 v52, 0x3fb8aa3b, v52
	v_lshlrev_b32_e32 v51, 16, v197
	v_exp_f32_e32 v53, v52
	v_exp_f32_e64 v54, -v52
	v_mul_f32_e32 v50, 0x3db504f3, v50
	s_nop 0
	v_mul_f32_e32 v50, v53, v50
	v_mul_f32_e32 v14, v54, v51
	v_cvt_pk_bf16_f32 v50, v50, v14
	global_store_short v1, v50, s[22:23]
	global_store_short_d16_hi v1, v50, s[22:23] offset:1024
	s_add_u32 s22, s22, 0x1a00
	s_addc_u32 s23, s23, 0
	global_load_ushort v196, v1, s[20:21]
	global_load_ushort v197, v1, s[20:21] offset:1024
	s_add_u32 s20, s20, 0x1a00
	s_addc_u32 s21, s21, 0
	s_waitcnt vmcnt(52)
	v_sub_f32_e32 v52, v95, v96
	v_lshlrev_b32_e32 v50, 16, v198
	v_mul_f32_e32 v52, 0x3fb8aa3b, v52
	v_lshlrev_b32_e32 v51, 16, v199
	v_exp_f32_e32 v53, v52
	v_exp_f32_e64 v54, -v52
	v_mul_f32_e32 v50, 0x3db504f3, v50
	s_nop 0
	v_mul_f32_e32 v50, v53, v50
	v_mul_f32_e32 v15, v54, v51
	v_cvt_pk_bf16_f32 v50, v50, v15
	global_store_short v1, v50, s[22:23]
	global_store_short_d16_hi v1, v50, s[22:23] offset:1024
	s_add_u32 s22, s22, 0x1a00
	s_addc_u32 s23, s23, 0
	v_cvt_pk_bf16_f32 v4, v8, v9
	v_cvt_pk_bf16_f32 v5, v10, v11
	v_cvt_pk_bf16_f32 v6, v12, v13
	v_cvt_pk_bf16_f32 v7, v14, v15
	global_store_dwordx4 v2, v[4:7], s[26:27] offset:48
	global_load_ushort v198, v1, s[20:21]
	global_load_ushort v199, v1, s[20:21] offset:1024
	s_add_u32 s20, s20, 0x1a00
	s_addc_u32 s21, s21, 0
	s_waitcnt lgkmcnt(0)
	ds_read_b128 v[34:37], v3 offset:2304
	ds_read_b128 v[38:41], v3 offset:2320
	ds_read_b128 v[42:45], v3 offset:2336
	ds_read_b128 v[46:49], v3 offset:2352
	ds_read_b128 v[200:203], v3 offset:2368
	ds_read_b128 v[204:207], v3 offset:2384
	ds_read_b128 v[208:211], v3 offset:2400
	ds_read_b128 v[212:215], v3 offset:2416
	v_pk_fma_f32 v[50:51], v[16:17], v[216:217], v[32:33] op_sel_hi:[0,1,0]
	v_pk_fma_f32 v[50:51], v[16:17], v[218:219], v[50:51] op_sel:[1,0,0] op_sel_hi:[1,1,1]
	v_pk_fma_f32 v[50:51], v[18:19], v[220:221], v[50:51] op_sel_hi:[0,1,1]
	v_pk_fma_f32 v[50:51], v[18:19], v[222:223], v[50:51] op_sel:[1,0,0] op_sel_hi:[1,1,1]
	v_pk_fma_f32 v[50:51], v[20:21], v[224:225], v[50:51] op_sel_hi:[0,1,1]
	v_pk_fma_f32 v[50:51], v[20:21], v[226:227], v[50:51] op_sel:[1,0,0] op_sel_hi:[1,1,1]
	v_pk_fma_f32 v[50:51], v[22:23], v[232:233], v[50:51] op_sel_hi:[0,1,1]
	v_pk_fma_f32 v[50:51], v[22:23], v[234:235], v[50:51] op_sel:[1,0,0] op_sel_hi:[1,1,1]
	v_pk_fma_f32 v[50:51], v[24:25], v[236:237], v[50:51] op_sel_hi:[0,1,1]
	v_pk_fma_f32 v[50:51], v[24:25], v[238:239], v[50:51] op_sel:[1,0,0] op_sel_hi:[1,1,1]
	v_pk_fma_f32 v[50:51], v[26:27], v[240:241], v[50:51] op_sel_hi:[0,1,1]
	v_pk_fma_f32 v[50:51], v[26:27], v[242:243], v[50:51] op_sel:[1,0,0] op_sel_hi:[1,1,1]
	v_pk_fma_f32 v[50:51], v[28:29], v[244:245], v[50:51] op_sel_hi:[0,1,1]
	v_pk_fma_f32 v[50:51], v[28:29], v[246:247], v[50:51] op_sel:[1,0,0] op_sel_hi:[1,1,1]
	v_pk_fma_f32 v[50:51], v[30:31], v[248:249], v[50:51] op_sel_hi:[0,1,1]
	v_pk_fma_f32 v[50:51], v[30:31], v[250:251], v[50:51] op_sel:[1,0,0] op_sel_hi:[1,1,1]
	v_mul_f32_e64 v52, |v50|, s7
	v_mul_f32_e64 v53, |v51|, s7
	v_exp_f32_e32 v52, v52
	v_exp_f32_e32 v53, v53
	v_min_f32_e32 v50, 0, v50
	v_min_f32_e32 v51, 0, v51
	v_pk_add_f32 v[52:53], v[52:53], 1.0 op_sel_hi:[1,0]
	v_log_f32_e32 v52, v52
	v_log_f32_e32 v53, v53
	s_nop 0
	v_pk_mul_f32 v[54:55], v[52:53], s[8:9] op_sel:[0,1] op_sel_hi:[1,1]
	v_pk_fma_f32 v[56:57], v[52:53], s[8:9], v[54:55] op_sel:[0,1,0] op_sel_hi:[1,1,1] neg_lo:[0,0,1] neg_hi:[0,0,1]
	v_pk_fma_f32 v[56:57], v[52:53], s[86:87], v[56:57] op_sel:[0,1,0] op_sel_hi:[1,1,1]
	v_pk_add_f32 v[54:55], v[54:55], v[56:57]
	v_pk_add_f32 v[50:51], v[50:51], v[54:55] neg_lo:[0,1] neg_hi:[0,1]
	v_fmamk_f32 v98, v50, 0x3d800000, v97
	v_fmamk_f32 v99, v51, 0x3d800000, v98
	s_waitcnt lgkmcnt(0)
	ds_read_b128 v[216:219], v3 offset:2432
	ds_read_b128 v[220:223], v3 offset:2448
	ds_read_b128 v[224:227], v3 offset:2464
	ds_read_b128 v[232:235], v3 offset:2480
	ds_read_b128 v[236:239], v3 offset:2496
	ds_read_b128 v[240:243], v3 offset:2512
	ds_read_b128 v[244:247], v3 offset:2528
	ds_read_b128 v[248:251], v3 offset:2544
	v_pk_fma_f32 v[50:51], v[16:17], v[34:35], v[32:33] op_sel_hi:[0,1,0]
	v_pk_fma_f32 v[50:51], v[16:17], v[36:37], v[50:51] op_sel:[1,0,0] op_sel_hi:[1,1,1]
	v_pk_fma_f32 v[50:51], v[18:19], v[38:39], v[50:51] op_sel_hi:[0,1,1]
	v_pk_fma_f32 v[50:51], v[18:19], v[40:41], v[50:51] op_sel:[1,0,0] op_sel_hi:[1,1,1]
	v_pk_fma_f32 v[50:51], v[20:21], v[42:43], v[50:51] op_sel_hi:[0,1,1]
	v_pk_fma_f32 v[50:51], v[20:21], v[44:45], v[50:51] op_sel:[1,0,0] op_sel_hi:[1,1,1]
	v_pk_fma_f32 v[50:51], v[22:23], v[46:47], v[50:51] op_sel_hi:[0,1,1]
	v_pk_fma_f32 v[50:51], v[22:23], v[48:49], v[50:51] op_sel:[1,0,0] op_sel_hi:[1,1,1]
	v_pk_fma_f32 v[50:51], v[24:25], v[200:201], v[50:51] op_sel_hi:[0,1,1]
	v_pk_fma_f32 v[50:51], v[24:25], v[202:203], v[50:51] op_sel:[1,0,0] op_sel_hi:[1,1,1]
	v_pk_fma_f32 v[50:51], v[26:27], v[204:205], v[50:51] op_sel_hi:[0,1,1]
	v_pk_fma_f32 v[50:51], v[26:27], v[206:207], v[50:51] op_sel:[1,0,0] op_sel_hi:[1,1,1]
	v_pk_fma_f32 v[50:51], v[28:29], v[208:209], v[50:51] op_sel_hi:[0,1,1]
	v_pk_fma_f32 v[50:51], v[28:29], v[210:211], v[50:51] op_sel:[1,0,0] op_sel_hi:[1,1,1]
	v_pk_fma_f32 v[50:51], v[30:31], v[212:213], v[50:51] op_sel_hi:[0,1,1]
	v_pk_fma_f32 v[50:51], v[30:31], v[214:215], v[50:51] op_sel:[1,0,0] op_sel_hi:[1,1,1]
	v_mul_f32_e64 v52, |v50|, s7
	v_mul_f32_e64 v53, |v51|, s7
	v_exp_f32_e32 v52, v52
	v_exp_f32_e32 v53, v53
	v_min_f32_e32 v50, 0, v50
	v_min_f32_e32 v51, 0, v51
	v_pk_add_f32 v[52:53], v[52:53], 1.0 op_sel_hi:[1,0]
	v_log_f32_e32 v52, v52
	v_log_f32_e32 v53, v53
	s_nop 0
	v_pk_mul_f32 v[54:55], v[52:53], s[8:9] op_sel:[0,1] op_sel_hi:[1,1]
	v_pk_fma_f32 v[56:57], v[52:53], s[8:9], v[54:55] op_sel:[0,1,0] op_sel_hi:[1,1,1] neg_lo:[0,0,1] neg_hi:[0,0,1]
	v_pk_fma_f32 v[56:57], v[52:53], s[86:87], v[56:57] op_sel:[0,1,0] op_sel_hi:[1,1,1]
	v_pk_add_f32 v[54:55], v[54:55], v[56:57]
	v_pk_add_f32 v[50:51], v[50:51], v[54:55] neg_lo:[0,1] neg_hi:[0,1]
	v_fmamk_f32 v100, v50, 0x3d800000, v99
	v_fmamk_f32 v101, v51, 0x3d800000, v100
	s_waitcnt lgkmcnt(0)
	ds_read_b128 v[34:37], v3 offset:2560
	ds_read_b128 v[38:41], v3 offset:2576
	ds_read_b128 v[42:45], v3 offset:2592
	ds_read_b128 v[46:49], v3 offset:2608
	ds_read_b128 v[200:203], v3 offset:2624
	ds_read_b128 v[204:207], v3 offset:2640
	ds_read_b128 v[208:211], v3 offset:2656
	ds_read_b128 v[212:215], v3 offset:2672
	v_pk_fma_f32 v[50:51], v[16:17], v[216:217], v[32:33] op_sel_hi:[0,1,0]
	v_pk_fma_f32 v[50:51], v[16:17], v[218:219], v[50:51] op_sel:[1,0,0] op_sel_hi:[1,1,1]
	v_pk_fma_f32 v[50:51], v[18:19], v[220:221], v[50:51] op_sel_hi:[0,1,1]
	v_pk_fma_f32 v[50:51], v[18:19], v[222:223], v[50:51] op_sel:[1,0,0] op_sel_hi:[1,1,1]
	v_pk_fma_f32 v[50:51], v[20:21], v[224:225], v[50:51] op_sel_hi:[0,1,1]
	v_pk_fma_f32 v[50:51], v[20:21], v[226:227], v[50:51] op_sel:[1,0,0] op_sel_hi:[1,1,1]
	v_pk_fma_f32 v[50:51], v[22:23], v[232:233], v[50:51] op_sel_hi:[0,1,1]
	v_pk_fma_f32 v[50:51], v[22:23], v[234:235], v[50:51] op_sel:[1,0,0] op_sel_hi:[1,1,1]
	v_pk_fma_f32 v[50:51], v[24:25], v[236:237], v[50:51] op_sel_hi:[0,1,1]
	v_pk_fma_f32 v[50:51], v[24:25], v[238:239], v[50:51] op_sel:[1,0,0] op_sel_hi:[1,1,1]
	v_pk_fma_f32 v[50:51], v[26:27], v[240:241], v[50:51] op_sel_hi:[0,1,1]
	v_pk_fma_f32 v[50:51], v[26:27], v[242:243], v[50:51] op_sel:[1,0,0] op_sel_hi:[1,1,1]
	v_pk_fma_f32 v[50:51], v[28:29], v[244:245], v[50:51] op_sel_hi:[0,1,1]
	v_pk_fma_f32 v[50:51], v[28:29], v[246:247], v[50:51] op_sel:[1,0,0] op_sel_hi:[1,1,1]
	v_pk_fma_f32 v[50:51], v[30:31], v[248:249], v[50:51] op_sel_hi:[0,1,1]
	v_pk_fma_f32 v[50:51], v[30:31], v[250:251], v[50:51] op_sel:[1,0,0] op_sel_hi:[1,1,1]
	v_mul_f32_e64 v52, |v50|, s7
	v_mul_f32_e64 v53, |v51|, s7
	v_exp_f32_e32 v52, v52
	v_exp_f32_e32 v53, v53
	v_min_f32_e32 v50, 0, v50
	v_min_f32_e32 v51, 0, v51
	v_pk_add_f32 v[52:53], v[52:53], 1.0 op_sel_hi:[1,0]
	v_log_f32_e32 v52, v52
	v_log_f32_e32 v53, v53
	s_nop 0
	v_pk_mul_f32 v[54:55], v[52:53], s[8:9] op_sel:[0,1] op_sel_hi:[1,1]
	v_pk_fma_f32 v[56:57], v[52:53], s[8:9], v[54:55] op_sel:[0,1,0] op_sel_hi:[1,1,1] neg_lo:[0,0,1] neg_hi:[0,0,1]
	v_pk_fma_f32 v[56:57], v[52:53], s[86:87], v[56:57] op_sel:[0,1,0] op_sel_hi:[1,1,1]
	v_pk_add_f32 v[54:55], v[54:55], v[56:57]
	v_pk_add_f32 v[50:51], v[50:51], v[54:55] neg_lo:[0,1] neg_hi:[0,1]
	v_fmamk_f32 v102, v50, 0x3d800000, v101
	v_fmamk_f32 v103, v51, 0x3d800000, v102
	s_waitcnt lgkmcnt(0)
	ds_read_b128 v[216:219], v3 offset:2688
	ds_read_b128 v[220:223], v3 offset:2704
	ds_read_b128 v[224:227], v3 offset:2720
	ds_read_b128 v[232:235], v3 offset:2736
	ds_read_b128 v[236:239], v3 offset:2752
	ds_read_b128 v[240:243], v3 offset:2768
	ds_read_b128 v[244:247], v3 offset:2784
	ds_read_b128 v[248:251], v3 offset:2800
	v_pk_fma_f32 v[50:51], v[16:17], v[34:35], v[32:33] op_sel_hi:[0,1,0]
	v_pk_fma_f32 v[50:51], v[16:17], v[36:37], v[50:51] op_sel:[1,0,0] op_sel_hi:[1,1,1]
	v_pk_fma_f32 v[50:51], v[18:19], v[38:39], v[50:51] op_sel_hi:[0,1,1]
	v_pk_fma_f32 v[50:51], v[18:19], v[40:41], v[50:51] op_sel:[1,0,0] op_sel_hi:[1,1,1]
	v_pk_fma_f32 v[50:51], v[20:21], v[42:43], v[50:51] op_sel_hi:[0,1,1]
	v_pk_fma_f32 v[50:51], v[20:21], v[44:45], v[50:51] op_sel:[1,0,0] op_sel_hi:[1,1,1]
	v_pk_fma_f32 v[50:51], v[22:23], v[46:47], v[50:51] op_sel_hi:[0,1,1]
	v_pk_fma_f32 v[50:51], v[22:23], v[48:49], v[50:51] op_sel:[1,0,0] op_sel_hi:[1,1,1]
	v_pk_fma_f32 v[50:51], v[24:25], v[200:201], v[50:51] op_sel_hi:[0,1,1]
	v_pk_fma_f32 v[50:51], v[24:25], v[202:203], v[50:51] op_sel:[1,0,0] op_sel_hi:[1,1,1]
	v_pk_fma_f32 v[50:51], v[26:27], v[204:205], v[50:51] op_sel_hi:[0,1,1]
	v_pk_fma_f32 v[50:51], v[26:27], v[206:207], v[50:51] op_sel:[1,0,0] op_sel_hi:[1,1,1]
	v_pk_fma_f32 v[50:51], v[28:29], v[208:209], v[50:51] op_sel_hi:[0,1,1]
	v_pk_fma_f32 v[50:51], v[28:29], v[210:211], v[50:51] op_sel:[1,0,0] op_sel_hi:[1,1,1]
	v_pk_fma_f32 v[50:51], v[30:31], v[212:213], v[50:51] op_sel_hi:[0,1,1]
	v_pk_fma_f32 v[50:51], v[30:31], v[214:215], v[50:51] op_sel:[1,0,0] op_sel_hi:[1,1,1]
	v_mul_f32_e64 v52, |v50|, s7
	v_mul_f32_e64 v53, |v51|, s7
	v_exp_f32_e32 v52, v52
	v_exp_f32_e32 v53, v53
	v_min_f32_e32 v50, 0, v50
	v_min_f32_e32 v51, 0, v51
	v_pk_add_f32 v[52:53], v[52:53], 1.0 op_sel_hi:[1,0]
	v_log_f32_e32 v52, v52
	v_log_f32_e32 v53, v53
	s_nop 0
	v_pk_mul_f32 v[54:55], v[52:53], s[8:9] op_sel:[0,1] op_sel_hi:[1,1]
	v_pk_fma_f32 v[56:57], v[52:53], s[8:9], v[54:55] op_sel:[0,1,0] op_sel_hi:[1,1,1] neg_lo:[0,0,1] neg_hi:[0,0,1]
	v_pk_fma_f32 v[56:57], v[52:53], s[86:87], v[56:57] op_sel:[0,1,0] op_sel_hi:[1,1,1]
	v_pk_add_f32 v[54:55], v[54:55], v[56:57]
	v_pk_add_f32 v[50:51], v[50:51], v[54:55] neg_lo:[0,1] neg_hi:[0,1]
	v_fmamk_f32 v104, v50, 0x3d800000, v103
	v_fmamk_f32 v105, v51, 0x3d800000, v104
	s_waitcnt lgkmcnt(0)
	ds_read_b128 v[34:37], v3 offset:2816
	ds_read_b128 v[38:41], v3 offset:2832
	ds_read_b128 v[42:45], v3 offset:2848
	ds_read_b128 v[46:49], v3 offset:2864
	ds_read_b128 v[200:203], v3 offset:2880
	ds_read_b128 v[204:207], v3 offset:2896
	ds_read_b128 v[208:211], v3 offset:2912
	ds_read_b128 v[212:215], v3 offset:2928
	v_pk_fma_f32 v[50:51], v[16:17], v[216:217], v[32:33] op_sel_hi:[0,1,0]
	v_pk_fma_f32 v[50:51], v[16:17], v[218:219], v[50:51] op_sel:[1,0,0] op_sel_hi:[1,1,1]
	v_pk_fma_f32 v[50:51], v[18:19], v[220:221], v[50:51] op_sel_hi:[0,1,1]
	v_pk_fma_f32 v[50:51], v[18:19], v[222:223], v[50:51] op_sel:[1,0,0] op_sel_hi:[1,1,1]
	v_pk_fma_f32 v[50:51], v[20:21], v[224:225], v[50:51] op_sel_hi:[0,1,1]
	v_pk_fma_f32 v[50:51], v[20:21], v[226:227], v[50:51] op_sel:[1,0,0] op_sel_hi:[1,1,1]
	v_pk_fma_f32 v[50:51], v[22:23], v[232:233], v[50:51] op_sel_hi:[0,1,1]
	v_pk_fma_f32 v[50:51], v[22:23], v[234:235], v[50:51] op_sel:[1,0,0] op_sel_hi:[1,1,1]
	v_pk_fma_f32 v[50:51], v[24:25], v[236:237], v[50:51] op_sel_hi:[0,1,1]
	v_pk_fma_f32 v[50:51], v[24:25], v[238:239], v[50:51] op_sel:[1,0,0] op_sel_hi:[1,1,1]
	v_pk_fma_f32 v[50:51], v[26:27], v[240:241], v[50:51] op_sel_hi:[0,1,1]
	v_pk_fma_f32 v[50:51], v[26:27], v[242:243], v[50:51] op_sel:[1,0,0] op_sel_hi:[1,1,1]
	v_pk_fma_f32 v[50:51], v[28:29], v[244:245], v[50:51] op_sel_hi:[0,1,1]
	v_pk_fma_f32 v[50:51], v[28:29], v[246:247], v[50:51] op_sel:[1,0,0] op_sel_hi:[1,1,1]
	v_pk_fma_f32 v[50:51], v[30:31], v[248:249], v[50:51] op_sel_hi:[0,1,1]
	v_pk_fma_f32 v[50:51], v[30:31], v[250:251], v[50:51] op_sel:[1,0,0] op_sel_hi:[1,1,1]
	v_mul_f32_e64 v52, |v50|, s7
	v_mul_f32_e64 v53, |v51|, s7
	v_exp_f32_e32 v52, v52
	v_exp_f32_e32 v53, v53
	v_min_f32_e32 v50, 0, v50
	v_min_f32_e32 v51, 0, v51
	v_pk_add_f32 v[52:53], v[52:53], 1.0 op_sel_hi:[1,0]
	v_log_f32_e32 v52, v52
	v_log_f32_e32 v53, v53
	s_nop 0
	v_pk_mul_f32 v[54:55], v[52:53], s[8:9] op_sel:[0,1] op_sel_hi:[1,1]
	v_pk_fma_f32 v[56:57], v[52:53], s[8:9], v[54:55] op_sel:[0,1,0] op_sel_hi:[1,1,1] neg_lo:[0,0,1] neg_hi:[0,0,1]
	v_pk_fma_f32 v[56:57], v[52:53], s[86:87], v[56:57] op_sel:[0,1,0] op_sel_hi:[1,1,1]
	v_pk_add_f32 v[54:55], v[54:55], v[56:57]
	v_pk_add_f32 v[50:51], v[50:51], v[54:55] neg_lo:[0,1] neg_hi:[0,1]
	v_fmamk_f32 v106, v50, 0x3d800000, v105
	v_fmamk_f32 v107, v51, 0x3d800000, v106
	s_waitcnt lgkmcnt(0)
	ds_read_b128 v[216:219], v3 offset:2944
	ds_read_b128 v[220:223], v3 offset:2960
	ds_read_b128 v[224:227], v3 offset:2976
	ds_read_b128 v[232:235], v3 offset:2992
	ds_read_b128 v[236:239], v3 offset:3008
	ds_read_b128 v[240:243], v3 offset:3024
	ds_read_b128 v[244:247], v3 offset:3040
	ds_read_b128 v[248:251], v3 offset:3056
	v_pk_fma_f32 v[50:51], v[16:17], v[34:35], v[32:33] op_sel_hi:[0,1,0]
	v_pk_fma_f32 v[50:51], v[16:17], v[36:37], v[50:51] op_sel:[1,0,0] op_sel_hi:[1,1,1]
	v_pk_fma_f32 v[50:51], v[18:19], v[38:39], v[50:51] op_sel_hi:[0,1,1]
	v_pk_fma_f32 v[50:51], v[18:19], v[40:41], v[50:51] op_sel:[1,0,0] op_sel_hi:[1,1,1]
	v_pk_fma_f32 v[50:51], v[20:21], v[42:43], v[50:51] op_sel_hi:[0,1,1]
	v_pk_fma_f32 v[50:51], v[20:21], v[44:45], v[50:51] op_sel:[1,0,0] op_sel_hi:[1,1,1]
	v_pk_fma_f32 v[50:51], v[22:23], v[46:47], v[50:51] op_sel_hi:[0,1,1]
	v_pk_fma_f32 v[50:51], v[22:23], v[48:49], v[50:51] op_sel:[1,0,0] op_sel_hi:[1,1,1]
	v_pk_fma_f32 v[50:51], v[24:25], v[200:201], v[50:51] op_sel_hi:[0,1,1]
	v_pk_fma_f32 v[50:51], v[24:25], v[202:203], v[50:51] op_sel:[1,0,0] op_sel_hi:[1,1,1]
	v_pk_fma_f32 v[50:51], v[26:27], v[204:205], v[50:51] op_sel_hi:[0,1,1]
	v_pk_fma_f32 v[50:51], v[26:27], v[206:207], v[50:51] op_sel:[1,0,0] op_sel_hi:[1,1,1]
	v_pk_fma_f32 v[50:51], v[28:29], v[208:209], v[50:51] op_sel_hi:[0,1,1]
	v_pk_fma_f32 v[50:51], v[28:29], v[210:211], v[50:51] op_sel:[1,0,0] op_sel_hi:[1,1,1]
	v_pk_fma_f32 v[50:51], v[30:31], v[212:213], v[50:51] op_sel_hi:[0,1,1]
	v_pk_fma_f32 v[50:51], v[30:31], v[214:215], v[50:51] op_sel:[1,0,0] op_sel_hi:[1,1,1]
	v_mul_f32_e64 v52, |v50|, s7
	v_mul_f32_e64 v53, |v51|, s7
	v_exp_f32_e32 v52, v52
	v_exp_f32_e32 v53, v53
	v_min_f32_e32 v50, 0, v50
	v_min_f32_e32 v51, 0, v51
	v_pk_add_f32 v[52:53], v[52:53], 1.0 op_sel_hi:[1,0]
	v_log_f32_e32 v52, v52
	v_log_f32_e32 v53, v53
	s_nop 0
	v_pk_mul_f32 v[54:55], v[52:53], s[8:9] op_sel:[0,1] op_sel_hi:[1,1]
	v_pk_fma_f32 v[56:57], v[52:53], s[8:9], v[54:55] op_sel:[0,1,0] op_sel_hi:[1,1,1] neg_lo:[0,0,1] neg_hi:[0,0,1]
	v_pk_fma_f32 v[56:57], v[52:53], s[86:87], v[56:57] op_sel:[0,1,0] op_sel_hi:[1,1,1]
	v_pk_add_f32 v[54:55], v[54:55], v[56:57]
	v_pk_add_f32 v[50:51], v[50:51], v[54:55] neg_lo:[0,1] neg_hi:[0,1]
	v_fmamk_f32 v108, v50, 0x3d800000, v107
	v_fmamk_f32 v109, v51, 0x3d800000, v108
	s_waitcnt lgkmcnt(0)
	ds_read_b128 v[34:37], v3 offset:3072
	ds_read_b128 v[38:41], v3 offset:3088
	ds_read_b128 v[42:45], v3 offset:3104
	ds_read_b128 v[46:49], v3 offset:3120
	ds_read_b128 v[200:203], v3 offset:3136
	ds_read_b128 v[204:207], v3 offset:3152
	ds_read_b128 v[208:211], v3 offset:3168
	ds_read_b128 v[212:215], v3 offset:3184
	v_pk_fma_f32 v[50:51], v[16:17], v[216:217], v[32:33] op_sel_hi:[0,1,0]
	v_pk_fma_f32 v[50:51], v[16:17], v[218:219], v[50:51] op_sel:[1,0,0] op_sel_hi:[1,1,1]
	v_pk_fma_f32 v[50:51], v[18:19], v[220:221], v[50:51] op_sel_hi:[0,1,1]
	v_pk_fma_f32 v[50:51], v[18:19], v[222:223], v[50:51] op_sel:[1,0,0] op_sel_hi:[1,1,1]
	v_pk_fma_f32 v[50:51], v[20:21], v[224:225], v[50:51] op_sel_hi:[0,1,1]
	v_pk_fma_f32 v[50:51], v[20:21], v[226:227], v[50:51] op_sel:[1,0,0] op_sel_hi:[1,1,1]
	v_pk_fma_f32 v[50:51], v[22:23], v[232:233], v[50:51] op_sel_hi:[0,1,1]
	v_pk_fma_f32 v[50:51], v[22:23], v[234:235], v[50:51] op_sel:[1,0,0] op_sel_hi:[1,1,1]
	v_pk_fma_f32 v[50:51], v[24:25], v[236:237], v[50:51] op_sel_hi:[0,1,1]
	v_pk_fma_f32 v[50:51], v[24:25], v[238:239], v[50:51] op_sel:[1,0,0] op_sel_hi:[1,1,1]
	v_pk_fma_f32 v[50:51], v[26:27], v[240:241], v[50:51] op_sel_hi:[0,1,1]
	v_pk_fma_f32 v[50:51], v[26:27], v[242:243], v[50:51] op_sel:[1,0,0] op_sel_hi:[1,1,1]
	v_pk_fma_f32 v[50:51], v[28:29], v[244:245], v[50:51] op_sel_hi:[0,1,1]
	v_pk_fma_f32 v[50:51], v[28:29], v[246:247], v[50:51] op_sel:[1,0,0] op_sel_hi:[1,1,1]
	v_pk_fma_f32 v[50:51], v[30:31], v[248:249], v[50:51] op_sel_hi:[0,1,1]
	v_pk_fma_f32 v[50:51], v[30:31], v[250:251], v[50:51] op_sel:[1,0,0] op_sel_hi:[1,1,1]
	v_mul_f32_e64 v52, |v50|, s7
	v_mul_f32_e64 v53, |v51|, s7
	v_exp_f32_e32 v52, v52
	v_exp_f32_e32 v53, v53
	v_min_f32_e32 v50, 0, v50
	v_min_f32_e32 v51, 0, v51
	v_pk_add_f32 v[52:53], v[52:53], 1.0 op_sel_hi:[1,0]
	v_log_f32_e32 v52, v52
	v_log_f32_e32 v53, v53
	s_nop 0
	v_pk_mul_f32 v[54:55], v[52:53], s[8:9] op_sel:[0,1] op_sel_hi:[1,1]
	v_pk_fma_f32 v[56:57], v[52:53], s[8:9], v[54:55] op_sel:[0,1,0] op_sel_hi:[1,1,1] neg_lo:[0,0,1] neg_hi:[0,0,1]
	v_pk_fma_f32 v[56:57], v[52:53], s[86:87], v[56:57] op_sel:[0,1,0] op_sel_hi:[1,1,1]
	v_pk_add_f32 v[54:55], v[54:55], v[56:57]
	v_pk_add_f32 v[50:51], v[50:51], v[54:55] neg_lo:[0,1] neg_hi:[0,1]
	v_fmamk_f32 v110, v50, 0x3d800000, v109
	v_fmamk_f32 v111, v51, 0x3d800000, v110
	s_waitcnt lgkmcnt(0)
	ds_read_b128 v[216:219], v3 offset:3200
	ds_read_b128 v[220:223], v3 offset:3216
	ds_read_b128 v[224:227], v3 offset:3232
	ds_read_b128 v[232:235], v3 offset:3248
	ds_read_b128 v[236:239], v3 offset:3264
	ds_read_b128 v[240:243], v3 offset:3280
	ds_read_b128 v[244:247], v3 offset:3296
	ds_read_b128 v[248:251], v3 offset:3312
	v_pk_fma_f32 v[50:51], v[16:17], v[34:35], v[32:33] op_sel_hi:[0,1,0]
	v_pk_fma_f32 v[50:51], v[16:17], v[36:37], v[50:51] op_sel:[1,0,0] op_sel_hi:[1,1,1]
	v_pk_fma_f32 v[50:51], v[18:19], v[38:39], v[50:51] op_sel_hi:[0,1,1]
	v_pk_fma_f32 v[50:51], v[18:19], v[40:41], v[50:51] op_sel:[1,0,0] op_sel_hi:[1,1,1]
	v_pk_fma_f32 v[50:51], v[20:21], v[42:43], v[50:51] op_sel_hi:[0,1,1]
	v_pk_fma_f32 v[50:51], v[20:21], v[44:45], v[50:51] op_sel:[1,0,0] op_sel_hi:[1,1,1]
	v_pk_fma_f32 v[50:51], v[22:23], v[46:47], v[50:51] op_sel_hi:[0,1,1]
	v_pk_fma_f32 v[50:51], v[22:23], v[48:49], v[50:51] op_sel:[1,0,0] op_sel_hi:[1,1,1]
	v_pk_fma_f32 v[50:51], v[24:25], v[200:201], v[50:51] op_sel_hi:[0,1,1]
	v_pk_fma_f32 v[50:51], v[24:25], v[202:203], v[50:51] op_sel:[1,0,0] op_sel_hi:[1,1,1]
	v_pk_fma_f32 v[50:51], v[26:27], v[204:205], v[50:51] op_sel_hi:[0,1,1]
	v_pk_fma_f32 v[50:51], v[26:27], v[206:207], v[50:51] op_sel:[1,0,0] op_sel_hi:[1,1,1]
	v_pk_fma_f32 v[50:51], v[28:29], v[208:209], v[50:51] op_sel_hi:[0,1,1]
	v_pk_fma_f32 v[50:51], v[28:29], v[210:211], v[50:51] op_sel:[1,0,0] op_sel_hi:[1,1,1]
	v_pk_fma_f32 v[50:51], v[30:31], v[212:213], v[50:51] op_sel_hi:[0,1,1]
	v_pk_fma_f32 v[50:51], v[30:31], v[214:215], v[50:51] op_sel:[1,0,0] op_sel_hi:[1,1,1]
	v_mul_f32_e64 v52, |v50|, s7
	v_mul_f32_e64 v53, |v51|, s7
	v_exp_f32_e32 v52, v52
	v_exp_f32_e32 v53, v53
	v_min_f32_e32 v50, 0, v50
	v_min_f32_e32 v51, 0, v51
	v_pk_add_f32 v[52:53], v[52:53], 1.0 op_sel_hi:[1,0]
	v_log_f32_e32 v52, v52
	v_log_f32_e32 v53, v53
	s_nop 0
	v_pk_mul_f32 v[54:55], v[52:53], s[8:9] op_sel:[0,1] op_sel_hi:[1,1]
	v_pk_fma_f32 v[56:57], v[52:53], s[8:9], v[54:55] op_sel:[0,1,0] op_sel_hi:[1,1,1] neg_lo:[0,0,1] neg_hi:[0,0,1]
	v_pk_fma_f32 v[56:57], v[52:53], s[86:87], v[56:57] op_sel:[0,1,0] op_sel_hi:[1,1,1]
	v_pk_add_f32 v[54:55], v[54:55], v[56:57]
	v_pk_add_f32 v[50:51], v[50:51], v[54:55] neg_lo:[0,1] neg_hi:[0,1]
	v_fmamk_f32 v112, v50, 0x3d800000, v111
	v_fmamk_f32 v113, v51, 0x3d800000, v112
	s_waitcnt lgkmcnt(0)
	ds_read_b128 v[34:37], v3 offset:3328
	ds_read_b128 v[38:41], v3 offset:3344
	ds_read_b128 v[42:45], v3 offset:3360
	ds_read_b128 v[46:49], v3 offset:3376
	ds_read_b128 v[200:203], v3 offset:3392
	ds_read_b128 v[204:207], v3 offset:3408
	ds_read_b128 v[208:211], v3 offset:3424
	ds_read_b128 v[212:215], v3 offset:3440
	v_pk_fma_f32 v[50:51], v[16:17], v[216:217], v[32:33] op_sel_hi:[0,1,0]
	v_pk_fma_f32 v[50:51], v[16:17], v[218:219], v[50:51] op_sel:[1,0,0] op_sel_hi:[1,1,1]
	v_pk_fma_f32 v[50:51], v[18:19], v[220:221], v[50:51] op_sel_hi:[0,1,1]
	v_pk_fma_f32 v[50:51], v[18:19], v[222:223], v[50:51] op_sel:[1,0,0] op_sel_hi:[1,1,1]
	v_pk_fma_f32 v[50:51], v[20:21], v[224:225], v[50:51] op_sel_hi:[0,1,1]
	v_pk_fma_f32 v[50:51], v[20:21], v[226:227], v[50:51] op_sel:[1,0,0] op_sel_hi:[1,1,1]
	v_pk_fma_f32 v[50:51], v[22:23], v[232:233], v[50:51] op_sel_hi:[0,1,1]
	v_pk_fma_f32 v[50:51], v[22:23], v[234:235], v[50:51] op_sel:[1,0,0] op_sel_hi:[1,1,1]
	v_pk_fma_f32 v[50:51], v[24:25], v[236:237], v[50:51] op_sel_hi:[0,1,1]
	v_pk_fma_f32 v[50:51], v[24:25], v[238:239], v[50:51] op_sel:[1,0,0] op_sel_hi:[1,1,1]
	v_pk_fma_f32 v[50:51], v[26:27], v[240:241], v[50:51] op_sel_hi:[0,1,1]
	v_pk_fma_f32 v[50:51], v[26:27], v[242:243], v[50:51] op_sel:[1,0,0] op_sel_hi:[1,1,1]
	v_pk_fma_f32 v[50:51], v[28:29], v[244:245], v[50:51] op_sel_hi:[0,1,1]
	v_pk_fma_f32 v[50:51], v[28:29], v[246:247], v[50:51] op_sel:[1,0,0] op_sel_hi:[1,1,1]
	v_pk_fma_f32 v[50:51], v[30:31], v[248:249], v[50:51] op_sel_hi:[0,1,1]
	v_pk_fma_f32 v[50:51], v[30:31], v[250:251], v[50:51] op_sel:[1,0,0] op_sel_hi:[1,1,1]
	v_mul_f32_e64 v52, |v50|, s7
	v_mul_f32_e64 v53, |v51|, s7
	v_exp_f32_e32 v52, v52
	v_exp_f32_e32 v53, v53
	v_min_f32_e32 v50, 0, v50
	v_min_f32_e32 v51, 0, v51
	v_pk_add_f32 v[52:53], v[52:53], 1.0 op_sel_hi:[1,0]
	v_log_f32_e32 v52, v52
	v_log_f32_e32 v53, v53
	s_nop 0
	v_pk_mul_f32 v[54:55], v[52:53], s[8:9] op_sel:[0,1] op_sel_hi:[1,1]
	v_pk_fma_f32 v[56:57], v[52:53], s[8:9], v[54:55] op_sel:[0,1,0] op_sel_hi:[1,1,1] neg_lo:[0,0,1] neg_hi:[0,0,1]
	v_pk_fma_f32 v[56:57], v[52:53], s[86:87], v[56:57] op_sel:[0,1,0] op_sel_hi:[1,1,1]
	v_pk_add_f32 v[54:55], v[54:55], v[56:57]
	v_pk_add_f32 v[50:51], v[50:51], v[54:55] neg_lo:[0,1] neg_hi:[0,1]
	v_fmamk_f32 v114, v50, 0x3d800000, v113
	v_fmamk_f32 v115, v51, 0x3d800000, v114
	s_waitcnt lgkmcnt(0)
	ds_read_b128 v[216:219], v3 offset:3456
	ds_read_b128 v[220:223], v3 offset:3472
	ds_read_b128 v[224:227], v3 offset:3488
	ds_read_b128 v[232:235], v3 offset:3504
	ds_read_b128 v[236:239], v3 offset:3520
	ds_read_b128 v[240:243], v3 offset:3536
	ds_read_b128 v[244:247], v3 offset:3552
	ds_read_b128 v[248:251], v3 offset:3568
	v_pk_fma_f32 v[50:51], v[16:17], v[34:35], v[32:33] op_sel_hi:[0,1,0]
	v_pk_fma_f32 v[50:51], v[16:17], v[36:37], v[50:51] op_sel:[1,0,0] op_sel_hi:[1,1,1]
	v_pk_fma_f32 v[50:51], v[18:19], v[38:39], v[50:51] op_sel_hi:[0,1,1]
	v_pk_fma_f32 v[50:51], v[18:19], v[40:41], v[50:51] op_sel:[1,0,0] op_sel_hi:[1,1,1]
	v_pk_fma_f32 v[50:51], v[20:21], v[42:43], v[50:51] op_sel_hi:[0,1,1]
	v_pk_fma_f32 v[50:51], v[20:21], v[44:45], v[50:51] op_sel:[1,0,0] op_sel_hi:[1,1,1]
	v_pk_fma_f32 v[50:51], v[22:23], v[46:47], v[50:51] op_sel_hi:[0,1,1]
	v_pk_fma_f32 v[50:51], v[22:23], v[48:49], v[50:51] op_sel:[1,0,0] op_sel_hi:[1,1,1]
	v_pk_fma_f32 v[50:51], v[24:25], v[200:201], v[50:51] op_sel_hi:[0,1,1]
	v_pk_fma_f32 v[50:51], v[24:25], v[202:203], v[50:51] op_sel:[1,0,0] op_sel_hi:[1,1,1]
	v_pk_fma_f32 v[50:51], v[26:27], v[204:205], v[50:51] op_sel_hi:[0,1,1]
	v_pk_fma_f32 v[50:51], v[26:27], v[206:207], v[50:51] op_sel:[1,0,0] op_sel_hi:[1,1,1]
	v_pk_fma_f32 v[50:51], v[28:29], v[208:209], v[50:51] op_sel_hi:[0,1,1]
	v_pk_fma_f32 v[50:51], v[28:29], v[210:211], v[50:51] op_sel:[1,0,0] op_sel_hi:[1,1,1]
	v_pk_fma_f32 v[50:51], v[30:31], v[212:213], v[50:51] op_sel_hi:[0,1,1]
	v_pk_fma_f32 v[50:51], v[30:31], v[214:215], v[50:51] op_sel:[1,0,0] op_sel_hi:[1,1,1]
	v_mul_f32_e64 v52, |v50|, s7
	v_mul_f32_e64 v53, |v51|, s7
	v_exp_f32_e32 v52, v52
	v_exp_f32_e32 v53, v53
	v_min_f32_e32 v50, 0, v50
	v_min_f32_e32 v51, 0, v51
	v_pk_add_f32 v[52:53], v[52:53], 1.0 op_sel_hi:[1,0]
	v_log_f32_e32 v52, v52
	v_log_f32_e32 v53, v53
	s_nop 0
	v_pk_mul_f32 v[54:55], v[52:53], s[8:9] op_sel:[0,1] op_sel_hi:[1,1]
	v_pk_fma_f32 v[56:57], v[52:53], s[8:9], v[54:55] op_sel:[0,1,0] op_sel_hi:[1,1,1] neg_lo:[0,0,1] neg_hi:[0,0,1]
	v_pk_fma_f32 v[56:57], v[52:53], s[86:87], v[56:57] op_sel:[0,1,0] op_sel_hi:[1,1,1]
	v_pk_add_f32 v[54:55], v[54:55], v[56:57]
	v_pk_add_f32 v[50:51], v[50:51], v[54:55] neg_lo:[0,1] neg_hi:[0,1]
	v_fmamk_f32 v116, v50, 0x3d800000, v115
	v_fmamk_f32 v117, v51, 0x3d800000, v116
	s_waitcnt lgkmcnt(0)
	ds_read_b128 v[34:37], v3 offset:3584
	ds_read_b128 v[38:41], v3 offset:3600
	ds_read_b128 v[42:45], v3 offset:3616
	ds_read_b128 v[46:49], v3 offset:3632
	ds_read_b128 v[200:203], v3 offset:3648
	ds_read_b128 v[204:207], v3 offset:3664
	ds_read_b128 v[208:211], v3 offset:3680
	ds_read_b128 v[212:215], v3 offset:3696
	v_pk_fma_f32 v[50:51], v[16:17], v[216:217], v[32:33] op_sel_hi:[0,1,0]
	v_pk_fma_f32 v[50:51], v[16:17], v[218:219], v[50:51] op_sel:[1,0,0] op_sel_hi:[1,1,1]
	v_pk_fma_f32 v[50:51], v[18:19], v[220:221], v[50:51] op_sel_hi:[0,1,1]
	v_pk_fma_f32 v[50:51], v[18:19], v[222:223], v[50:51] op_sel:[1,0,0] op_sel_hi:[1,1,1]
	v_pk_fma_f32 v[50:51], v[20:21], v[224:225], v[50:51] op_sel_hi:[0,1,1]
	v_pk_fma_f32 v[50:51], v[20:21], v[226:227], v[50:51] op_sel:[1,0,0] op_sel_hi:[1,1,1]
	v_pk_fma_f32 v[50:51], v[22:23], v[232:233], v[50:51] op_sel_hi:[0,1,1]
	v_pk_fma_f32 v[50:51], v[22:23], v[234:235], v[50:51] op_sel:[1,0,0] op_sel_hi:[1,1,1]
	v_pk_fma_f32 v[50:51], v[24:25], v[236:237], v[50:51] op_sel_hi:[0,1,1]
	v_pk_fma_f32 v[50:51], v[24:25], v[238:239], v[50:51] op_sel:[1,0,0] op_sel_hi:[1,1,1]
	v_pk_fma_f32 v[50:51], v[26:27], v[240:241], v[50:51] op_sel_hi:[0,1,1]
	v_pk_fma_f32 v[50:51], v[26:27], v[242:243], v[50:51] op_sel:[1,0,0] op_sel_hi:[1,1,1]
	v_pk_fma_f32 v[50:51], v[28:29], v[244:245], v[50:51] op_sel_hi:[0,1,1]
	v_pk_fma_f32 v[50:51], v[28:29], v[246:247], v[50:51] op_sel:[1,0,0] op_sel_hi:[1,1,1]
	v_pk_fma_f32 v[50:51], v[30:31], v[248:249], v[50:51] op_sel_hi:[0,1,1]
	v_pk_fma_f32 v[50:51], v[30:31], v[250:251], v[50:51] op_sel:[1,0,0] op_sel_hi:[1,1,1]
	v_mul_f32_e64 v52, |v50|, s7
	v_mul_f32_e64 v53, |v51|, s7
	v_exp_f32_e32 v52, v52
	v_exp_f32_e32 v53, v53
	v_min_f32_e32 v50, 0, v50
	v_min_f32_e32 v51, 0, v51
	v_pk_add_f32 v[52:53], v[52:53], 1.0 op_sel_hi:[1,0]
	v_log_f32_e32 v52, v52
	v_log_f32_e32 v53, v53
	s_nop 0
	v_pk_mul_f32 v[54:55], v[52:53], s[8:9] op_sel:[0,1] op_sel_hi:[1,1]
	v_pk_fma_f32 v[56:57], v[52:53], s[8:9], v[54:55] op_sel:[0,1,0] op_sel_hi:[1,1,1] neg_lo:[0,0,1] neg_hi:[0,0,1]
	v_pk_fma_f32 v[56:57], v[52:53], s[86:87], v[56:57] op_sel:[0,1,0] op_sel_hi:[1,1,1]
	v_pk_add_f32 v[54:55], v[54:55], v[56:57]
	v_pk_add_f32 v[50:51], v[50:51], v[54:55] neg_lo:[0,1] neg_hi:[0,1]
	v_fmamk_f32 v118, v50, 0x3d800000, v117
	v_fmamk_f32 v119, v51, 0x3d800000, v118
	s_waitcnt lgkmcnt(0)
	ds_read_b128 v[216:219], v3 offset:3712
	ds_read_b128 v[220:223], v3 offset:3728
	ds_read_b128 v[224:227], v3 offset:3744
	ds_read_b128 v[232:235], v3 offset:3760
	ds_read_b128 v[236:239], v3 offset:3776
	ds_read_b128 v[240:243], v3 offset:3792
	ds_read_b128 v[244:247], v3 offset:3808
	ds_read_b128 v[248:251], v3 offset:3824
	v_pk_fma_f32 v[50:51], v[16:17], v[34:35], v[32:33] op_sel_hi:[0,1,0]
	v_pk_fma_f32 v[50:51], v[16:17], v[36:37], v[50:51] op_sel:[1,0,0] op_sel_hi:[1,1,1]
	v_pk_fma_f32 v[50:51], v[18:19], v[38:39], v[50:51] op_sel_hi:[0,1,1]
	v_pk_fma_f32 v[50:51], v[18:19], v[40:41], v[50:51] op_sel:[1,0,0] op_sel_hi:[1,1,1]
	v_pk_fma_f32 v[50:51], v[20:21], v[42:43], v[50:51] op_sel_hi:[0,1,1]
	v_pk_fma_f32 v[50:51], v[20:21], v[44:45], v[50:51] op_sel:[1,0,0] op_sel_hi:[1,1,1]
	v_pk_fma_f32 v[50:51], v[22:23], v[46:47], v[50:51] op_sel_hi:[0,1,1]
	v_pk_fma_f32 v[50:51], v[22:23], v[48:49], v[50:51] op_sel:[1,0,0] op_sel_hi:[1,1,1]
	v_pk_fma_f32 v[50:51], v[24:25], v[200:201], v[50:51] op_sel_hi:[0,1,1]
	v_pk_fma_f32 v[50:51], v[24:25], v[202:203], v[50:51] op_sel:[1,0,0] op_sel_hi:[1,1,1]
	v_pk_fma_f32 v[50:51], v[26:27], v[204:205], v[50:51] op_sel_hi:[0,1,1]
	v_pk_fma_f32 v[50:51], v[26:27], v[206:207], v[50:51] op_sel:[1,0,0] op_sel_hi:[1,1,1]
	v_pk_fma_f32 v[50:51], v[28:29], v[208:209], v[50:51] op_sel_hi:[0,1,1]
	v_pk_fma_f32 v[50:51], v[28:29], v[210:211], v[50:51] op_sel:[1,0,0] op_sel_hi:[1,1,1]
	v_pk_fma_f32 v[50:51], v[30:31], v[212:213], v[50:51] op_sel_hi:[0,1,1]
	v_pk_fma_f32 v[50:51], v[30:31], v[214:215], v[50:51] op_sel:[1,0,0] op_sel_hi:[1,1,1]
	v_mul_f32_e64 v52, |v50|, s7
	v_mul_f32_e64 v53, |v51|, s7
	v_exp_f32_e32 v52, v52
	v_exp_f32_e32 v53, v53
	v_min_f32_e32 v50, 0, v50
	v_min_f32_e32 v51, 0, v51
	v_pk_add_f32 v[52:53], v[52:53], 1.0 op_sel_hi:[1,0]
	v_log_f32_e32 v52, v52
	v_log_f32_e32 v53, v53
	s_nop 0
	v_pk_mul_f32 v[54:55], v[52:53], s[8:9] op_sel:[0,1] op_sel_hi:[1,1]
	v_pk_fma_f32 v[56:57], v[52:53], s[8:9], v[54:55] op_sel:[0,1,0] op_sel_hi:[1,1,1] neg_lo:[0,0,1] neg_hi:[0,0,1]
	v_pk_fma_f32 v[56:57], v[52:53], s[86:87], v[56:57] op_sel:[0,1,0] op_sel_hi:[1,1,1]
	v_pk_add_f32 v[54:55], v[54:55], v[56:57]
	v_pk_add_f32 v[50:51], v[50:51], v[54:55] neg_lo:[0,1] neg_hi:[0,1]
	v_fmamk_f32 v120, v50, 0x3d800000, v119
	v_fmamk_f32 v121, v51, 0x3d800000, v120
	s_waitcnt lgkmcnt(0)
	ds_read_b128 v[34:37], v3 offset:3840
	ds_read_b128 v[38:41], v3 offset:3856
	ds_read_b128 v[42:45], v3 offset:3872
	ds_read_b128 v[46:49], v3 offset:3888
	ds_read_b128 v[200:203], v3 offset:3904
	ds_read_b128 v[204:207], v3 offset:3920
	ds_read_b128 v[208:211], v3 offset:3936
	ds_read_b128 v[212:215], v3 offset:3952
	v_pk_fma_f32 v[50:51], v[16:17], v[216:217], v[32:33] op_sel_hi:[0,1,0]
	v_pk_fma_f32 v[50:51], v[16:17], v[218:219], v[50:51] op_sel:[1,0,0] op_sel_hi:[1,1,1]
	v_pk_fma_f32 v[50:51], v[18:19], v[220:221], v[50:51] op_sel_hi:[0,1,1]
	v_pk_fma_f32 v[50:51], v[18:19], v[222:223], v[50:51] op_sel:[1,0,0] op_sel_hi:[1,1,1]
	v_pk_fma_f32 v[50:51], v[20:21], v[224:225], v[50:51] op_sel_hi:[0,1,1]
	v_pk_fma_f32 v[50:51], v[20:21], v[226:227], v[50:51] op_sel:[1,0,0] op_sel_hi:[1,1,1]
	v_pk_fma_f32 v[50:51], v[22:23], v[232:233], v[50:51] op_sel_hi:[0,1,1]
	v_pk_fma_f32 v[50:51], v[22:23], v[234:235], v[50:51] op_sel:[1,0,0] op_sel_hi:[1,1,1]
	v_pk_fma_f32 v[50:51], v[24:25], v[236:237], v[50:51] op_sel_hi:[0,1,1]
	v_pk_fma_f32 v[50:51], v[24:25], v[238:239], v[50:51] op_sel:[1,0,0] op_sel_hi:[1,1,1]
	v_pk_fma_f32 v[50:51], v[26:27], v[240:241], v[50:51] op_sel_hi:[0,1,1]
	v_pk_fma_f32 v[50:51], v[26:27], v[242:243], v[50:51] op_sel:[1,0,0] op_sel_hi:[1,1,1]
	v_pk_fma_f32 v[50:51], v[28:29], v[244:245], v[50:51] op_sel_hi:[0,1,1]
	v_pk_fma_f32 v[50:51], v[28:29], v[246:247], v[50:51] op_sel:[1,0,0] op_sel_hi:[1,1,1]
	v_pk_fma_f32 v[50:51], v[30:31], v[248:249], v[50:51] op_sel_hi:[0,1,1]
	v_pk_fma_f32 v[50:51], v[30:31], v[250:251], v[50:51] op_sel:[1,0,0] op_sel_hi:[1,1,1]
	v_mul_f32_e64 v52, |v50|, s7
	v_mul_f32_e64 v53, |v51|, s7
	v_exp_f32_e32 v52, v52
	v_exp_f32_e32 v53, v53
	v_min_f32_e32 v50, 0, v50
	v_min_f32_e32 v51, 0, v51
	v_pk_add_f32 v[52:53], v[52:53], 1.0 op_sel_hi:[1,0]
	v_log_f32_e32 v52, v52
	v_log_f32_e32 v53, v53
	s_nop 0
	v_pk_mul_f32 v[54:55], v[52:53], s[8:9] op_sel:[0,1] op_sel_hi:[1,1]
	v_pk_fma_f32 v[56:57], v[52:53], s[8:9], v[54:55] op_sel:[0,1,0] op_sel_hi:[1,1,1] neg_lo:[0,0,1] neg_hi:[0,0,1]
	v_pk_fma_f32 v[56:57], v[52:53], s[86:87], v[56:57] op_sel:[0,1,0] op_sel_hi:[1,1,1]
	v_pk_add_f32 v[54:55], v[54:55], v[56:57]
	v_pk_add_f32 v[50:51], v[50:51], v[54:55] neg_lo:[0,1] neg_hi:[0,1]
	v_fmamk_f32 v122, v50, 0x3d800000, v121
	v_fmamk_f32 v123, v51, 0x3d800000, v122
	s_waitcnt lgkmcnt(0)
	ds_read_b128 v[216:219], v3 offset:3968
	ds_read_b128 v[220:223], v3 offset:3984
	ds_read_b128 v[224:227], v3 offset:4000
	ds_read_b128 v[232:235], v3 offset:4016
	ds_read_b128 v[236:239], v3 offset:4032
	ds_read_b128 v[240:243], v3 offset:4048
	ds_read_b128 v[244:247], v3 offset:4064
	ds_read_b128 v[248:251], v3 offset:4080
	v_pk_fma_f32 v[50:51], v[16:17], v[34:35], v[32:33] op_sel_hi:[0,1,0]
	v_pk_fma_f32 v[50:51], v[16:17], v[36:37], v[50:51] op_sel:[1,0,0] op_sel_hi:[1,1,1]
	v_pk_fma_f32 v[50:51], v[18:19], v[38:39], v[50:51] op_sel_hi:[0,1,1]
	v_pk_fma_f32 v[50:51], v[18:19], v[40:41], v[50:51] op_sel:[1,0,0] op_sel_hi:[1,1,1]
	v_pk_fma_f32 v[50:51], v[20:21], v[42:43], v[50:51] op_sel_hi:[0,1,1]
	v_pk_fma_f32 v[50:51], v[20:21], v[44:45], v[50:51] op_sel:[1,0,0] op_sel_hi:[1,1,1]
	v_pk_fma_f32 v[50:51], v[22:23], v[46:47], v[50:51] op_sel_hi:[0,1,1]
	v_pk_fma_f32 v[50:51], v[22:23], v[48:49], v[50:51] op_sel:[1,0,0] op_sel_hi:[1,1,1]
	v_pk_fma_f32 v[50:51], v[24:25], v[200:201], v[50:51] op_sel_hi:[0,1,1]
	v_pk_fma_f32 v[50:51], v[24:25], v[202:203], v[50:51] op_sel:[1,0,0] op_sel_hi:[1,1,1]
	v_pk_fma_f32 v[50:51], v[26:27], v[204:205], v[50:51] op_sel_hi:[0,1,1]
	v_pk_fma_f32 v[50:51], v[26:27], v[206:207], v[50:51] op_sel:[1,0,0] op_sel_hi:[1,1,1]
	v_pk_fma_f32 v[50:51], v[28:29], v[208:209], v[50:51] op_sel_hi:[0,1,1]
	v_pk_fma_f32 v[50:51], v[28:29], v[210:211], v[50:51] op_sel:[1,0,0] op_sel_hi:[1,1,1]
	v_pk_fma_f32 v[50:51], v[30:31], v[212:213], v[50:51] op_sel_hi:[0,1,1]
	v_pk_fma_f32 v[50:51], v[30:31], v[214:215], v[50:51] op_sel:[1,0,0] op_sel_hi:[1,1,1]
	v_mul_f32_e64 v52, |v50|, s7
	v_mul_f32_e64 v53, |v51|, s7
	v_exp_f32_e32 v52, v52
	v_exp_f32_e32 v53, v53
	v_min_f32_e32 v50, 0, v50
	v_min_f32_e32 v51, 0, v51
	v_pk_add_f32 v[52:53], v[52:53], 1.0 op_sel_hi:[1,0]
	v_log_f32_e32 v52, v52
	v_log_f32_e32 v53, v53
	s_nop 0
	v_pk_mul_f32 v[54:55], v[52:53], s[8:9] op_sel:[0,1] op_sel_hi:[1,1]
	v_pk_fma_f32 v[56:57], v[52:53], s[8:9], v[54:55] op_sel:[0,1,0] op_sel_hi:[1,1,1] neg_lo:[0,0,1] neg_hi:[0,0,1]
	v_pk_fma_f32 v[56:57], v[52:53], s[86:87], v[56:57] op_sel:[0,1,0] op_sel_hi:[1,1,1]
	v_pk_add_f32 v[54:55], v[54:55], v[56:57]
	v_pk_add_f32 v[50:51], v[50:51], v[54:55] neg_lo:[0,1] neg_hi:[0,1]
	v_fmamk_f32 v124, v50, 0x3d800000, v123
	v_fmamk_f32 v125, v51, 0x3d800000, v124
	s_waitcnt lgkmcnt(0)
	v_pk_fma_f32 v[50:51], v[16:17], v[216:217], v[32:33] op_sel_hi:[0,1,0]
	v_pk_fma_f32 v[50:51], v[16:17], v[218:219], v[50:51] op_sel:[1,0,0] op_sel_hi:[1,1,1]
	v_pk_fma_f32 v[50:51], v[18:19], v[220:221], v[50:51] op_sel_hi:[0,1,1]
	v_pk_fma_f32 v[50:51], v[18:19], v[222:223], v[50:51] op_sel:[1,0,0] op_sel_hi:[1,1,1]
	v_pk_fma_f32 v[50:51], v[20:21], v[224:225], v[50:51] op_sel_hi:[0,1,1]
	v_pk_fma_f32 v[50:51], v[20:21], v[226:227], v[50:51] op_sel:[1,0,0] op_sel_hi:[1,1,1]
	v_pk_fma_f32 v[50:51], v[22:23], v[232:233], v[50:51] op_sel_hi:[0,1,1]
	v_pk_fma_f32 v[50:51], v[22:23], v[234:235], v[50:51] op_sel:[1,0,0] op_sel_hi:[1,1,1]
	v_pk_fma_f32 v[50:51], v[24:25], v[236:237], v[50:51] op_sel_hi:[0,1,1]
	v_pk_fma_f32 v[50:51], v[24:25], v[238:239], v[50:51] op_sel:[1,0,0] op_sel_hi:[1,1,1]
	v_pk_fma_f32 v[50:51], v[26:27], v[240:241], v[50:51] op_sel_hi:[0,1,1]
	v_pk_fma_f32 v[50:51], v[26:27], v[242:243], v[50:51] op_sel:[1,0,0] op_sel_hi:[1,1,1]
	v_pk_fma_f32 v[50:51], v[28:29], v[244:245], v[50:51] op_sel_hi:[0,1,1]
	v_pk_fma_f32 v[50:51], v[28:29], v[246:247], v[50:51] op_sel:[1,0,0] op_sel_hi:[1,1,1]
	v_pk_fma_f32 v[50:51], v[30:31], v[248:249], v[50:51] op_sel_hi:[0,1,1]
	v_pk_fma_f32 v[50:51], v[30:31], v[250:251], v[50:51] op_sel:[1,0,0] op_sel_hi:[1,1,1]
	v_mul_f32_e64 v52, |v50|, s7
	v_mul_f32_e64 v53, |v51|, s7
	v_exp_f32_e32 v52, v52
	v_exp_f32_e32 v53, v53
	v_min_f32_e32 v50, 0, v50
	v_min_f32_e32 v51, 0, v51
	v_pk_add_f32 v[52:53], v[52:53], 1.0 op_sel_hi:[1,0]
	v_log_f32_e32 v52, v52
	v_log_f32_e32 v53, v53
	s_nop 0
	v_pk_mul_f32 v[54:55], v[52:53], s[8:9] op_sel:[0,1] op_sel_hi:[1,1]
	v_pk_fma_f32 v[56:57], v[52:53], s[8:9], v[54:55] op_sel:[0,1,0] op_sel_hi:[1,1,1] neg_lo:[0,0,1] neg_hi:[0,0,1]
	v_pk_fma_f32 v[56:57], v[52:53], s[86:87], v[56:57] op_sel:[0,1,0] op_sel_hi:[1,1,1]
	v_pk_add_f32 v[54:55], v[54:55], v[56:57]
	v_pk_add_f32 v[50:51], v[50:51], v[54:55] neg_lo:[0,1] neg_hi:[0,1]
	v_fmamk_f32 v126, v50, 0x3d800000, v125
	v_fmamk_f32 v127, v51, 0x3d800000, v126
	s_waitcnt vmcnt(0)
	v_sub_f32_e32 v52, v96, v96
	v_lshlrev_b32_e32 v50, 16, v136
	v_mul_f32_e32 v52, 0x3fb8aa3b, v52
	v_lshlrev_b32_e32 v51, 16, v137
	v_exp_f32_e32 v53, v52
	v_exp_f32_e64 v54, -v52
	v_mul_f32_e32 v50, 0x3db504f3, v50
	s_nop 0
	v_mul_f32_e32 v50, v53, v50
	v_mul_f32_e32 v8, v54, v51
	v_cvt_pk_bf16_f32 v50, v50, v8
	global_store_short v1, v50, s[22:23]
	global_store_short_d16_hi v1, v50, s[22:23] offset:1024
	s_add_u32 s22, s22, 0x1a00
	s_addc_u32 s23, s23, 0
	v_sub_f32_e32 v52, v97, v96
	v_lshlrev_b32_e32 v50, 16, v138
	v_mul_f32_e32 v52, 0x3fb8aa3b, v52
	v_lshlrev_b32_e32 v51, 16, v139
	v_exp_f32_e32 v53, v52
	v_exp_f32_e64 v54, -v52
	v_mul_f32_e32 v50, 0x3db504f3, v50
	s_nop 0
	v_mul_f32_e32 v50, v53, v50
	v_mul_f32_e32 v9, v54, v51
	v_cvt_pk_bf16_f32 v50, v50, v9
	global_store_short v1, v50, s[22:23]
	global_store_short_d16_hi v1, v50, s[22:23] offset:1024
	s_add_u32 s22, s22, 0x1a00
	s_addc_u32 s23, s23, 0
	v_sub_f32_e32 v52, v98, v96
	v_lshlrev_b32_e32 v50, 16, v140
	v_mul_f32_e32 v52, 0x3fb8aa3b, v52
	v_lshlrev_b32_e32 v51, 16, v141
	v_exp_f32_e32 v53, v52
	v_exp_f32_e64 v54, -v52
	v_mul_f32_e32 v50, 0x3db504f3, v50
	s_nop 0
	v_mul_f32_e32 v50, v53, v50
	v_mul_f32_e32 v10, v54, v51
	v_cvt_pk_bf16_f32 v50, v50, v10
	global_store_short v1, v50, s[22:23]
	global_store_short_d16_hi v1, v50, s[22:23] offset:1024
	s_add_u32 s22, s22, 0x1a00
	s_addc_u32 s23, s23, 0
	v_sub_f32_e32 v52, v99, v96
	v_lshlrev_b32_e32 v50, 16, v142
	v_mul_f32_e32 v52, 0x3fb8aa3b, v52
	v_lshlrev_b32_e32 v51, 16, v143
	v_exp_f32_e32 v53, v52
	v_exp_f32_e64 v54, -v52
	v_mul_f32_e32 v50, 0x3db504f3, v50
	s_nop 0
	v_mul_f32_e32 v50, v53, v50
	v_mul_f32_e32 v11, v54, v51
	v_cvt_pk_bf16_f32 v50, v50, v11
	global_store_short v1, v50, s[22:23]
	global_store_short_d16_hi v1, v50, s[22:23] offset:1024
	s_add_u32 s22, s22, 0x1a00
	s_addc_u32 s23, s23, 0
	v_sub_f32_e32 v52, v100, v96
	v_lshlrev_b32_e32 v50, 16, v144
	v_mul_f32_e32 v52, 0x3fb8aa3b, v52
	v_lshlrev_b32_e32 v51, 16, v145
	v_exp_f32_e32 v53, v52
	v_exp_f32_e64 v54, -v52
	v_mul_f32_e32 v50, 0x3db504f3, v50
	s_nop 0
	v_mul_f32_e32 v50, v53, v50
	v_mul_f32_e32 v12, v54, v51
	v_cvt_pk_bf16_f32 v50, v50, v12
	global_store_short v1, v50, s[22:23]
	global_store_short_d16_hi v1, v50, s[22:23] offset:1024
	s_add_u32 s22, s22, 0x1a00
	s_addc_u32 s23, s23, 0
	v_sub_f32_e32 v52, v101, v96
	v_lshlrev_b32_e32 v50, 16, v146
	v_mul_f32_e32 v52, 0x3fb8aa3b, v52
	v_lshlrev_b32_e32 v51, 16, v147
	v_exp_f32_e32 v53, v52
	v_exp_f32_e64 v54, -v52
	v_mul_f32_e32 v50, 0x3db504f3, v50
	s_nop 0
	v_mul_f32_e32 v50, v53, v50
	v_mul_f32_e32 v13, v54, v51
	v_cvt_pk_bf16_f32 v50, v50, v13
	global_store_short v1, v50, s[22:23]
	global_store_short_d16_hi v1, v50, s[22:23] offset:1024
	s_add_u32 s22, s22, 0x1a00
	s_addc_u32 s23, s23, 0
	v_sub_f32_e32 v52, v102, v96
	v_lshlrev_b32_e32 v50, 16, v148
	v_mul_f32_e32 v52, 0x3fb8aa3b, v52
	v_lshlrev_b32_e32 v51, 16, v149
	v_exp_f32_e32 v53, v52
	v_exp_f32_e64 v54, -v52
	v_mul_f32_e32 v50, 0x3db504f3, v50
	s_nop 0
	v_mul_f32_e32 v50, v53, v50
	v_mul_f32_e32 v14, v54, v51
	v_cvt_pk_bf16_f32 v50, v50, v14
	global_store_short v1, v50, s[22:23]
	global_store_short_d16_hi v1, v50, s[22:23] offset:1024
	s_add_u32 s22, s22, 0x1a00
	s_addc_u32 s23, s23, 0
	v_sub_f32_e32 v52, v103, v96
	v_lshlrev_b32_e32 v50, 16, v150
	v_mul_f32_e32 v52, 0x3fb8aa3b, v52
	v_lshlrev_b32_e32 v51, 16, v151
	v_exp_f32_e32 v53, v52
	v_exp_f32_e64 v54, -v52
	v_mul_f32_e32 v50, 0x3db504f3, v50
	s_nop 0
	v_mul_f32_e32 v50, v53, v50
	v_mul_f32_e32 v15, v54, v51
	v_cvt_pk_bf16_f32 v50, v50, v15
	global_store_short v1, v50, s[22:23]
	global_store_short_d16_hi v1, v50, s[22:23] offset:1024
	s_add_u32 s22, s22, 0x1a00
	s_addc_u32 s23, s23, 0
	v_cvt_pk_bf16_f32 v4, v8, v9
	v_cvt_pk_bf16_f32 v5, v10, v11
	v_cvt_pk_bf16_f32 v6, v12, v13
	v_cvt_pk_bf16_f32 v7, v14, v15
	global_store_dwordx4 v2, v[4:7], s[26:27] offset:64
	v_sub_f32_e32 v52, v104, v96
	v_lshlrev_b32_e32 v50, 16, v152
	v_mul_f32_e32 v52, 0x3fb8aa3b, v52
	v_lshlrev_b32_e32 v51, 16, v153
	v_exp_f32_e32 v53, v52
	v_exp_f32_e64 v54, -v52
	v_mul_f32_e32 v50, 0x3db504f3, v50
	s_nop 0
	v_mul_f32_e32 v50, v53, v50
	v_mul_f32_e32 v8, v54, v51
	v_cvt_pk_bf16_f32 v50, v50, v8
	global_store_short v1, v50, s[22:23]
	global_store_short_d16_hi v1, v50, s[22:23] offset:1024
	s_add_u32 s22, s22, 0x1a00
	s_addc_u32 s23, s23, 0
	v_sub_f32_e32 v52, v105, v96
	v_lshlrev_b32_e32 v50, 16, v154
	v_mul_f32_e32 v52, 0x3fb8aa3b, v52
	v_lshlrev_b32_e32 v51, 16, v155
	v_exp_f32_e32 v53, v52
	v_exp_f32_e64 v54, -v52
	v_mul_f32_e32 v50, 0x3db504f3, v50
	s_nop 0
	v_mul_f32_e32 v50, v53, v50
	v_mul_f32_e32 v9, v54, v51
	v_cvt_pk_bf16_f32 v50, v50, v9
	global_store_short v1, v50, s[22:23]
	global_store_short_d16_hi v1, v50, s[22:23] offset:1024
	s_add_u32 s22, s22, 0x1a00
	s_addc_u32 s23, s23, 0
	v_sub_f32_e32 v52, v106, v96
	v_lshlrev_b32_e32 v50, 16, v156
	v_mul_f32_e32 v52, 0x3fb8aa3b, v52
	v_lshlrev_b32_e32 v51, 16, v157
	v_exp_f32_e32 v53, v52
	v_exp_f32_e64 v54, -v52
	v_mul_f32_e32 v50, 0x3db504f3, v50
	s_nop 0
	v_mul_f32_e32 v50, v53, v50
	v_mul_f32_e32 v10, v54, v51
	v_cvt_pk_bf16_f32 v50, v50, v10
	global_store_short v1, v50, s[22:23]
	global_store_short_d16_hi v1, v50, s[22:23] offset:1024
	s_add_u32 s22, s22, 0x1a00
	s_addc_u32 s23, s23, 0
	v_sub_f32_e32 v52, v107, v96
	v_lshlrev_b32_e32 v50, 16, v158
	v_mul_f32_e32 v52, 0x3fb8aa3b, v52
	v_lshlrev_b32_e32 v51, 16, v159
	v_exp_f32_e32 v53, v52
	v_exp_f32_e64 v54, -v52
	v_mul_f32_e32 v50, 0x3db504f3, v50
	s_nop 0
	v_mul_f32_e32 v50, v53, v50
	v_mul_f32_e32 v11, v54, v51
	v_cvt_pk_bf16_f32 v50, v50, v11
	global_store_short v1, v50, s[22:23]
	global_store_short_d16_hi v1, v50, s[22:23] offset:1024
	s_add_u32 s22, s22, 0x1a00
	s_addc_u32 s23, s23, 0
	v_sub_f32_e32 v52, v108, v96
	v_lshlrev_b32_e32 v50, 16, v160
	v_mul_f32_e32 v52, 0x3fb8aa3b, v52
	v_lshlrev_b32_e32 v51, 16, v161
	v_exp_f32_e32 v53, v52
	v_exp_f32_e64 v54, -v52
	v_mul_f32_e32 v50, 0x3db504f3, v50
	s_nop 0
	v_mul_f32_e32 v50, v53, v50
	v_mul_f32_e32 v12, v54, v51
	v_cvt_pk_bf16_f32 v50, v50, v12
	global_store_short v1, v50, s[22:23]
	global_store_short_d16_hi v1, v50, s[22:23] offset:1024
	s_add_u32 s22, s22, 0x1a00
	s_addc_u32 s23, s23, 0
	v_sub_f32_e32 v52, v109, v96
	v_lshlrev_b32_e32 v50, 16, v162
	v_mul_f32_e32 v52, 0x3fb8aa3b, v52
	v_lshlrev_b32_e32 v51, 16, v163
	v_exp_f32_e32 v53, v52
	v_exp_f32_e64 v54, -v52
	v_mul_f32_e32 v50, 0x3db504f3, v50
	s_nop 0
	v_mul_f32_e32 v50, v53, v50
	v_mul_f32_e32 v13, v54, v51
	v_cvt_pk_bf16_f32 v50, v50, v13
	global_store_short v1, v50, s[22:23]
	global_store_short_d16_hi v1, v50, s[22:23] offset:1024
	s_add_u32 s22, s22, 0x1a00
	s_addc_u32 s23, s23, 0
	v_sub_f32_e32 v52, v110, v96
	v_lshlrev_b32_e32 v50, 16, v164
	v_mul_f32_e32 v52, 0x3fb8aa3b, v52
	v_lshlrev_b32_e32 v51, 16, v165
	v_exp_f32_e32 v53, v52
	v_exp_f32_e64 v54, -v52
	v_mul_f32_e32 v50, 0x3db504f3, v50
	s_nop 0
	v_mul_f32_e32 v50, v53, v50
	v_mul_f32_e32 v14, v54, v51
	v_cvt_pk_bf16_f32 v50, v50, v14
	global_store_short v1, v50, s[22:23]
	global_store_short_d16_hi v1, v50, s[22:23] offset:1024
	s_add_u32 s22, s22, 0x1a00
	s_addc_u32 s23, s23, 0
	v_sub_f32_e32 v52, v111, v96
	v_lshlrev_b32_e32 v50, 16, v166
	v_mul_f32_e32 v52, 0x3fb8aa3b, v52
	v_lshlrev_b32_e32 v51, 16, v167
	v_exp_f32_e32 v53, v52
	v_exp_f32_e64 v54, -v52
	v_mul_f32_e32 v50, 0x3db504f3, v50
	s_nop 0
	v_mul_f32_e32 v50, v53, v50
	v_mul_f32_e32 v15, v54, v51
	v_cvt_pk_bf16_f32 v50, v50, v15
	global_store_short v1, v50, s[22:23]
	global_store_short_d16_hi v1, v50, s[22:23] offset:1024
	s_add_u32 s22, s22, 0x1a00
	s_addc_u32 s23, s23, 0
	v_cvt_pk_bf16_f32 v4, v8, v9
	v_cvt_pk_bf16_f32 v5, v10, v11
	v_cvt_pk_bf16_f32 v6, v12, v13
	v_cvt_pk_bf16_f32 v7, v14, v15
	global_store_dwordx4 v2, v[4:7], s[26:27] offset:80
	v_sub_f32_e32 v52, v112, v96
	v_lshlrev_b32_e32 v50, 16, v168
	v_mul_f32_e32 v52, 0x3fb8aa3b, v52
	v_lshlrev_b32_e32 v51, 16, v169
	v_exp_f32_e32 v53, v52
	v_exp_f32_e64 v54, -v52
	v_mul_f32_e32 v50, 0x3db504f3, v50
	s_nop 0
	v_mul_f32_e32 v50, v53, v50
	v_mul_f32_e32 v8, v54, v51
	v_cvt_pk_bf16_f32 v50, v50, v8
	global_store_short v1, v50, s[22:23]
	global_store_short_d16_hi v1, v50, s[22:23] offset:1024
	s_add_u32 s22, s22, 0x1a00
	s_addc_u32 s23, s23, 0
	v_sub_f32_e32 v52, v113, v96
	v_lshlrev_b32_e32 v50, 16, v170
	v_mul_f32_e32 v52, 0x3fb8aa3b, v52
	v_lshlrev_b32_e32 v51, 16, v171
	v_exp_f32_e32 v53, v52
	v_exp_f32_e64 v54, -v52
	v_mul_f32_e32 v50, 0x3db504f3, v50
	s_nop 0
	v_mul_f32_e32 v50, v53, v50
	v_mul_f32_e32 v9, v54, v51
	v_cvt_pk_bf16_f32 v50, v50, v9
	global_store_short v1, v50, s[22:23]
	global_store_short_d16_hi v1, v50, s[22:23] offset:1024
	s_add_u32 s22, s22, 0x1a00
	s_addc_u32 s23, s23, 0
	v_sub_f32_e32 v52, v114, v96
	v_lshlrev_b32_e32 v50, 16, v172
	v_mul_f32_e32 v52, 0x3fb8aa3b, v52
	v_lshlrev_b32_e32 v51, 16, v173
	v_exp_f32_e32 v53, v52
	v_exp_f32_e64 v54, -v52
	v_mul_f32_e32 v50, 0x3db504f3, v50
	s_nop 0
	v_mul_f32_e32 v50, v53, v50
	v_mul_f32_e32 v10, v54, v51
	v_cvt_pk_bf16_f32 v50, v50, v10
	global_store_short v1, v50, s[22:23]
	global_store_short_d16_hi v1, v50, s[22:23] offset:1024
	s_add_u32 s22, s22, 0x1a00
	s_addc_u32 s23, s23, 0
	v_sub_f32_e32 v52, v115, v96
	v_lshlrev_b32_e32 v50, 16, v174
	v_mul_f32_e32 v52, 0x3fb8aa3b, v52
	v_lshlrev_b32_e32 v51, 16, v175
	v_exp_f32_e32 v53, v52
	v_exp_f32_e64 v54, -v52
	v_mul_f32_e32 v50, 0x3db504f3, v50
	s_nop 0
	v_mul_f32_e32 v50, v53, v50
	v_mul_f32_e32 v11, v54, v51
	v_cvt_pk_bf16_f32 v50, v50, v11
	global_store_short v1, v50, s[22:23]
	global_store_short_d16_hi v1, v50, s[22:23] offset:1024
	s_add_u32 s22, s22, 0x1a00
	s_addc_u32 s23, s23, 0
	v_sub_f32_e32 v52, v116, v96
	v_lshlrev_b32_e32 v50, 16, v176
	v_mul_f32_e32 v52, 0x3fb8aa3b, v52
	v_lshlrev_b32_e32 v51, 16, v177
	v_exp_f32_e32 v53, v52
	v_exp_f32_e64 v54, -v52
	v_mul_f32_e32 v50, 0x3db504f3, v50
	s_nop 0
	v_mul_f32_e32 v50, v53, v50
	v_mul_f32_e32 v12, v54, v51
	v_cvt_pk_bf16_f32 v50, v50, v12
	global_store_short v1, v50, s[22:23]
	global_store_short_d16_hi v1, v50, s[22:23] offset:1024
	s_add_u32 s22, s22, 0x1a00
	s_addc_u32 s23, s23, 0
	v_sub_f32_e32 v52, v117, v96
	v_lshlrev_b32_e32 v50, 16, v178
	v_mul_f32_e32 v52, 0x3fb8aa3b, v52
	v_lshlrev_b32_e32 v51, 16, v179
	v_exp_f32_e32 v53, v52
	v_exp_f32_e64 v54, -v52
	v_mul_f32_e32 v50, 0x3db504f3, v50
	s_nop 0
	v_mul_f32_e32 v50, v53, v50
	v_mul_f32_e32 v13, v54, v51
	v_cvt_pk_bf16_f32 v50, v50, v13
	global_store_short v1, v50, s[22:23]
	global_store_short_d16_hi v1, v50, s[22:23] offset:1024
	s_add_u32 s22, s22, 0x1a00
	s_addc_u32 s23, s23, 0
	v_sub_f32_e32 v52, v118, v96
	v_lshlrev_b32_e32 v50, 16, v180
	v_mul_f32_e32 v52, 0x3fb8aa3b, v52
	v_lshlrev_b32_e32 v51, 16, v181
	v_exp_f32_e32 v53, v52
	v_exp_f32_e64 v54, -v52
	v_mul_f32_e32 v50, 0x3db504f3, v50
	s_nop 0
	v_mul_f32_e32 v50, v53, v50
	v_mul_f32_e32 v14, v54, v51
	v_cvt_pk_bf16_f32 v50, v50, v14
	global_store_short v1, v50, s[22:23]
	global_store_short_d16_hi v1, v50, s[22:23] offset:1024
	s_add_u32 s22, s22, 0x1a00
	s_addc_u32 s23, s23, 0
	v_sub_f32_e32 v52, v119, v96
	v_lshlrev_b32_e32 v50, 16, v182
	v_mul_f32_e32 v52, 0x3fb8aa3b, v52
	v_lshlrev_b32_e32 v51, 16, v183
	v_exp_f32_e32 v53, v52
	v_exp_f32_e64 v54, -v52
	v_mul_f32_e32 v50, 0x3db504f3, v50
	s_nop 0
	v_mul_f32_e32 v50, v53, v50
	v_mul_f32_e32 v15, v54, v51
	v_cvt_pk_bf16_f32 v50, v50, v15
	global_store_short v1, v50, s[22:23]
	global_store_short_d16_hi v1, v50, s[22:23] offset:1024
	s_add_u32 s22, s22, 0x1a00
	s_addc_u32 s23, s23, 0
	v_cvt_pk_bf16_f32 v4, v8, v9
	v_cvt_pk_bf16_f32 v5, v10, v11
	v_cvt_pk_bf16_f32 v6, v12, v13
	v_cvt_pk_bf16_f32 v7, v14, v15
	global_store_dwordx4 v2, v[4:7], s[26:27] offset:96
	s_waitcnt vmcnt(52)
	v_sub_f32_e32 v52, v120, v96
	v_lshlrev_b32_e32 v50, 16, v184
	v_mul_f32_e32 v52, 0x3fb8aa3b, v52
	v_lshlrev_b32_e32 v51, 16, v185
	v_exp_f32_e32 v53, v52
	v_exp_f32_e64 v54, -v52
	v_mul_f32_e32 v50, 0x3db504f3, v50
	s_nop 0
	v_mul_f32_e32 v50, v53, v50
	v_mul_f32_e32 v8, v54, v51
	v_cvt_pk_bf16_f32 v50, v50, v8
	global_store_short v1, v50, s[22:23]
	global_store_short_d16_hi v1, v50, s[22:23] offset:1024
	s_add_u32 s22, s22, 0x1a00
	s_addc_u32 s23, s23, 0
	s_waitcnt vmcnt(52)
	v_sub_f32_e32 v52, v121, v96
	v_lshlrev_b32_e32 v50, 16, v186
	v_mul_f32_e32 v52, 0x3fb8aa3b, v52
	v_lshlrev_b32_e32 v51, 16, v187
	v_exp_f32_e32 v53, v52
	v_exp_f32_e64 v54, -v52
	v_mul_f32_e32 v50, 0x3db504f3, v50
	s_nop 0
	v_mul_f32_e32 v50, v53, v50
	v_mul_f32_e32 v9, v54, v51
	v_cvt_pk_bf16_f32 v50, v50, v9
	global_store_short v1, v50, s[22:23]
	global_store_short_d16_hi v1, v50, s[22:23] offset:1024
	s_add_u32 s22, s22, 0x1a00
	s_addc_u32 s23, s23, 0
	s_waitcnt vmcnt(52)
	v_sub_f32_e32 v52, v122, v96
	v_lshlrev_b32_e32 v50, 16, v188
	v_mul_f32_e32 v52, 0x3fb8aa3b, v52
	v_lshlrev_b32_e32 v51, 16, v189
	v_exp_f32_e32 v53, v52
	v_exp_f32_e64 v54, -v52
	v_mul_f32_e32 v50, 0x3db504f3, v50
	s_nop 0
	v_mul_f32_e32 v50, v53, v50
	v_mul_f32_e32 v10, v54, v51
	v_cvt_pk_bf16_f32 v50, v50, v10
	global_store_short v1, v50, s[22:23]
	global_store_short_d16_hi v1, v50, s[22:23] offset:1024
	s_add_u32 s22, s22, 0x1a00
	s_addc_u32 s23, s23, 0
	s_waitcnt vmcnt(52)
	v_sub_f32_e32 v52, v123, v96
	v_lshlrev_b32_e32 v50, 16, v190
	v_mul_f32_e32 v52, 0x3fb8aa3b, v52
	v_lshlrev_b32_e32 v51, 16, v191
	v_exp_f32_e32 v53, v52
	v_exp_f32_e64 v54, -v52
	v_mul_f32_e32 v50, 0x3db504f3, v50
	s_nop 0
	v_mul_f32_e32 v50, v53, v50
	v_mul_f32_e32 v11, v54, v51
	v_cvt_pk_bf16_f32 v50, v50, v11
	global_store_short v1, v50, s[22:23]
	global_store_short_d16_hi v1, v50, s[22:23] offset:1024
	s_add_u32 s22, s22, 0x1a00
	s_addc_u32 s23, s23, 0
	s_waitcnt vmcnt(52)
	v_sub_f32_e32 v52, v124, v96
	v_lshlrev_b32_e32 v50, 16, v192
	v_mul_f32_e32 v52, 0x3fb8aa3b, v52
	v_lshlrev_b32_e32 v51, 16, v193
	v_exp_f32_e32 v53, v52
	v_exp_f32_e64 v54, -v52
	v_mul_f32_e32 v50, 0x3db504f3, v50
	s_nop 0
	v_mul_f32_e32 v50, v53, v50
	v_mul_f32_e32 v12, v54, v51
	v_cvt_pk_bf16_f32 v50, v50, v12
	global_store_short v1, v50, s[22:23]
	global_store_short_d16_hi v1, v50, s[22:23] offset:1024
	s_add_u32 s22, s22, 0x1a00
	s_addc_u32 s23, s23, 0
	s_waitcnt vmcnt(52)
	v_sub_f32_e32 v52, v125, v96
	v_lshlrev_b32_e32 v50, 16, v194
	v_mul_f32_e32 v52, 0x3fb8aa3b, v52
	v_lshlrev_b32_e32 v51, 16, v195
	v_exp_f32_e32 v53, v52
	v_exp_f32_e64 v54, -v52
	v_mul_f32_e32 v50, 0x3db504f3, v50
	s_nop 0
	v_mul_f32_e32 v50, v53, v50
	v_mul_f32_e32 v13, v54, v51
	v_cvt_pk_bf16_f32 v50, v50, v13
	global_store_short v1, v50, s[22:23]
	global_store_short_d16_hi v1, v50, s[22:23] offset:1024
	s_add_u32 s22, s22, 0x1a00
	s_addc_u32 s23, s23, 0
	s_waitcnt vmcnt(52)
	v_sub_f32_e32 v52, v126, v96
	v_lshlrev_b32_e32 v50, 16, v196
	v_mul_f32_e32 v52, 0x3fb8aa3b, v52
	v_lshlrev_b32_e32 v51, 16, v197
	v_exp_f32_e32 v53, v52
	v_exp_f32_e64 v54, -v52
	v_mul_f32_e32 v50, 0x3db504f3, v50
	s_nop 0
	v_mul_f32_e32 v50, v53, v50
	v_mul_f32_e32 v14, v54, v51
	v_cvt_pk_bf16_f32 v50, v50, v14
	global_store_short v1, v50, s[22:23]
	global_store_short_d16_hi v1, v50, s[22:23] offset:1024
	s_add_u32 s22, s22, 0x1a00
	s_addc_u32 s23, s23, 0
	s_waitcnt vmcnt(52)
	v_sub_f32_e32 v52, v127, v96
	v_lshlrev_b32_e32 v50, 16, v198
	v_mul_f32_e32 v52, 0x3fb8aa3b, v52
	v_lshlrev_b32_e32 v51, 16, v199
	v_exp_f32_e32 v53, v52
	v_exp_f32_e64 v54, -v52
	v_mul_f32_e32 v50, 0x3db504f3, v50
	s_nop 0
	v_mul_f32_e32 v50, v53, v50
	v_mul_f32_e32 v15, v54, v51
	v_cvt_pk_bf16_f32 v50, v50, v15
	global_store_short v1, v50, s[22:23]
	global_store_short_d16_hi v1, v50, s[22:23] offset:1024
	s_add_u32 s22, s22, 0x1a00
	s_addc_u32 s23, s23, 0
	v_cvt_pk_bf16_f32 v4, v8, v9
	v_cvt_pk_bf16_f32 v5, v10, v11
	v_cvt_pk_bf16_f32 v6, v12, v13
	v_cvt_pk_bf16_f32 v7, v14, v15
	global_store_dwordx4 v2, v[4:7], s[26:27] offset:112
	v_mul_f32_e32 v50, 0x3fb8aa3b, v96
	v_sub_f32_e32 v51, v127, v96
	v_mul_f32_e32 v52, 0x3fb8aa3b, v127
	v_mul_f32_e32 v51, 0x3fb8aa3b, v51
	v_exp_f32_e32 v50, v50
	v_exp_f32_e32 v51, v51
	v_exp_f32_e32 v52, v52
	s_nop 0
	global_store_dword v0, v50, s[28:29]
	global_store_dword v0, v51, s[28:29] offset:2048
	s_add_u32 s28, s28, 0x1000
	s_addc_u32 s29, s29, 0
	global_store_dword v0, v52, s[28:29]
	s_add_i32 s82, s82, s3
	s_cmpk_lt_i32 s82, 0x100
	s_cbranch_scc1 .Lprep_item
